# rwkv scan inner loop fully unrolled with immediate LDS offsets, loads one step ahead, no mov/address VALU (on top of dilated prefetch)
# speedup vs baseline: 1.0086x; 1.0086x over previous
.LBB0_985:
	s_and_saveexec_b64 s[24:25], s[16:17]
	s_cbranch_execz .LBB0_988
	ds_read_b128 v[30:33], v161 offset:8192
	ds_read_b128 v[34:37], v161 offset:16384
	ds_read_b128 v[46:49], v161 offset:24576
	ds_read_b64 v[80:81], v82 offset:40960
	ds_read_b128 v[38:41], v161
	ds_read_b128 v[42:45], v161 offset:32768
	s_waitcnt lgkmcnt(0)
	v_pk_mul_f32 v[106:107], v[72:73], v[30:31]
	v_pk_mul_f32 v[108:109], v[76:77], v[30:31]
	v_pk_fma_f32 v[106:107], v[74:75], v[32:33], v[106:107]
	v_pk_fma_f32 v[108:109], v[78:79], v[32:33], v[108:109]
	v_add_f32_e32 v110, v106, v107
	v_add_f32_e32 v112, v108, v109
	ds_read_b128 v[84:87], v161 offset:8448
	v_add_f32_dpp v110, v110, v110 quad_perm:[1,0,3,2] row_mask:0xf bank_mask:0xf bound_ctrl:1
	v_add_f32_dpp v112, v112, v112 quad_perm:[1,0,3,2] row_mask:0xf bank_mask:0xf bound_ctrl:1
	ds_read_b128 v[88:91], v161 offset:16640
	v_add_f32_dpp v110, v110, v110 quad_perm:[2,3,0,1] row_mask:0xf bank_mask:0xf bound_ctrl:1
	v_add_f32_dpp v112, v112, v112 quad_perm:[2,3,0,1] row_mask:0xf bank_mask:0xf bound_ctrl:1
	ds_read_b128 v[100:103], v161 offset:24832
	v_add_f32_dpp v110, v110, v110 row_half_mirror row_mask:0xf bank_mask:0xf bound_ctrl:1
	v_add_f32_dpp v112, v112, v112 row_half_mirror row_mask:0xf bank_mask:0xf bound_ctrl:1
	ds_read_b64 v[104:105], v82 offset:41216
	v_add_f32_dpp v110, v110, v110 row_ror:8 row_mask:0xf bank_mask:0xf bound_ctrl:1
	v_add_f32_dpp v112, v112, v112 row_ror:8 row_mask:0xf bank_mask:0xf bound_ctrl:1
	ds_read_b128 v[92:95], v161 offset:256
	ds_read_b128 v[96:99], v161 offset:33024
	v_pk_mul_f32 v[114:115], v[34:35], v[110:111] op_sel_hi:[1,0]
	v_pk_mul_f32 v[116:117], v[34:35], v[112:113] op_sel_hi:[1,0]
	v_pk_mul_f32 v[118:119], v[36:37], v[110:111] op_sel_hi:[1,0]
	v_pk_mul_f32 v[120:121], v[36:37], v[112:113] op_sel_hi:[1,0]
	v_pk_fma_f32 v[114:115], v[46:47], v[80:81], v[114:115] op_sel_hi:[1,0,1]
	v_pk_fma_f32 v[116:117], v[46:47], v[80:81], v[116:117] op_sel:[0,1,0]
	v_pk_fma_f32 v[118:119], v[48:49], v[80:81], v[118:119] op_sel_hi:[1,0,1]
	v_pk_fma_f32 v[120:121], v[48:49], v[80:81], v[120:121] op_sel:[0,1,0]
	v_pk_fma_f32 v[72:73], v[72:73], v[38:39], v[114:115]
	v_pk_fma_f32 v[76:77], v[76:77], v[38:39], v[116:117]
	v_pk_fma_f32 v[74:75], v[74:75], v[40:41], v[118:119]
	v_pk_fma_f32 v[78:79], v[78:79], v[40:41], v[120:121]
	v_pk_mul_f32 v[122:123], v[72:73], v[42:43]
	v_pk_mul_f32 v[124:125], v[76:77], v[42:43]
	v_pk_fma_f32 v[122:123], v[74:75], v[44:45], v[122:123]
	v_pk_fma_f32 v[124:125], v[78:79], v[44:45], v[124:125]
	v_add_f32_e32 v126, v122, v123
	v_add_f32_e32 v127, v124, v125
	ds_write_b64 v187, v[126:127]
	s_waitcnt lgkmcnt(1)
	v_pk_mul_f32 v[106:107], v[72:73], v[84:85]
	v_pk_mul_f32 v[108:109], v[76:77], v[84:85]
	v_pk_fma_f32 v[106:107], v[74:75], v[86:87], v[106:107]
	v_pk_fma_f32 v[108:109], v[78:79], v[86:87], v[108:109]
	v_add_f32_e32 v110, v106, v107
	v_add_f32_e32 v112, v108, v109
	ds_read_b128 v[30:33], v161 offset:8704
	v_add_f32_dpp v110, v110, v110 quad_perm:[1,0,3,2] row_mask:0xf bank_mask:0xf bound_ctrl:1
	v_add_f32_dpp v112, v112, v112 quad_perm:[1,0,3,2] row_mask:0xf bank_mask:0xf bound_ctrl:1
	ds_read_b128 v[34:37], v161 offset:16896
	v_add_f32_dpp v110, v110, v110 quad_perm:[2,3,0,1] row_mask:0xf bank_mask:0xf bound_ctrl:1
	v_add_f32_dpp v112, v112, v112 quad_perm:[2,3,0,1] row_mask:0xf bank_mask:0xf bound_ctrl:1
	ds_read_b128 v[46:49], v161 offset:25088
	v_add_f32_dpp v110, v110, v110 row_half_mirror row_mask:0xf bank_mask:0xf bound_ctrl:1
	v_add_f32_dpp v112, v112, v112 row_half_mirror row_mask:0xf bank_mask:0xf bound_ctrl:1
	ds_read_b64 v[80:81], v82 offset:41472
	v_add_f32_dpp v110, v110, v110 row_ror:8 row_mask:0xf bank_mask:0xf bound_ctrl:1
	v_add_f32_dpp v112, v112, v112 row_ror:8 row_mask:0xf bank_mask:0xf bound_ctrl:1
	ds_read_b128 v[38:41], v161 offset:512
	ds_read_b128 v[42:45], v161 offset:33280
	v_pk_mul_f32 v[114:115], v[88:89], v[110:111] op_sel_hi:[1,0]
	v_pk_mul_f32 v[116:117], v[88:89], v[112:113] op_sel_hi:[1,0]
	v_pk_mul_f32 v[118:119], v[90:91], v[110:111] op_sel_hi:[1,0]
	v_pk_mul_f32 v[120:121], v[90:91], v[112:113] op_sel_hi:[1,0]
	v_pk_fma_f32 v[114:115], v[100:101], v[104:105], v[114:115] op_sel_hi:[1,0,1]
	v_pk_fma_f32 v[116:117], v[100:101], v[104:105], v[116:117] op_sel:[0,1,0]
	v_pk_fma_f32 v[118:119], v[102:103], v[104:105], v[118:119] op_sel_hi:[1,0,1]
	v_pk_fma_f32 v[120:121], v[102:103], v[104:105], v[120:121] op_sel:[0,1,0]
	v_pk_fma_f32 v[72:73], v[72:73], v[92:93], v[114:115]
	v_pk_fma_f32 v[76:77], v[76:77], v[92:93], v[116:117]
	v_pk_fma_f32 v[74:75], v[74:75], v[94:95], v[118:119]
	v_pk_fma_f32 v[78:79], v[78:79], v[94:95], v[120:121]
	v_pk_mul_f32 v[122:123], v[72:73], v[96:97]
	v_pk_mul_f32 v[124:125], v[76:77], v[96:97]
	v_pk_fma_f32 v[122:123], v[74:75], v[98:99], v[122:123]
	v_pk_fma_f32 v[124:125], v[78:79], v[98:99], v[124:125]
	v_add_f32_e32 v126, v122, v123
	v_add_f32_e32 v127, v124, v125
	ds_write_b64 v187, v[126:127] offset:2048
	s_waitcnt lgkmcnt(1)
	v_pk_mul_f32 v[106:107], v[72:73], v[30:31]
	v_pk_mul_f32 v[108:109], v[76:77], v[30:31]
	v_pk_fma_f32 v[106:107], v[74:75], v[32:33], v[106:107]
	v_pk_fma_f32 v[108:109], v[78:79], v[32:33], v[108:109]
	v_add_f32_e32 v110, v106, v107
	v_add_f32_e32 v112, v108, v109
	ds_read_b128 v[84:87], v161 offset:8960
	v_add_f32_dpp v110, v110, v110 quad_perm:[1,0,3,2] row_mask:0xf bank_mask:0xf bound_ctrl:1
	v_add_f32_dpp v112, v112, v112 quad_perm:[1,0,3,2] row_mask:0xf bank_mask:0xf bound_ctrl:1
	ds_read_b128 v[88:91], v161 offset:17152
	v_add_f32_dpp v110, v110, v110 quad_perm:[2,3,0,1] row_mask:0xf bank_mask:0xf bound_ctrl:1
	v_add_f32_dpp v112, v112, v112 quad_perm:[2,3,0,1] row_mask:0xf bank_mask:0xf bound_ctrl:1
	ds_read_b128 v[100:103], v161 offset:25344
	v_add_f32_dpp v110, v110, v110 row_half_mirror row_mask:0xf bank_mask:0xf bound_ctrl:1
	v_add_f32_dpp v112, v112, v112 row_half_mirror row_mask:0xf bank_mask:0xf bound_ctrl:1
	ds_read_b64 v[104:105], v82 offset:41728
	v_add_f32_dpp v110, v110, v110 row_ror:8 row_mask:0xf bank_mask:0xf bound_ctrl:1
	v_add_f32_dpp v112, v112, v112 row_ror:8 row_mask:0xf bank_mask:0xf bound_ctrl:1
	ds_read_b128 v[92:95], v161 offset:768
	ds_read_b128 v[96:99], v161 offset:33536
	v_pk_mul_f32 v[114:115], v[34:35], v[110:111] op_sel_hi:[1,0]
	v_pk_mul_f32 v[116:117], v[34:35], v[112:113] op_sel_hi:[1,0]
	v_pk_mul_f32 v[118:119], v[36:37], v[110:111] op_sel_hi:[1,0]
	v_pk_mul_f32 v[120:121], v[36:37], v[112:113] op_sel_hi:[1,0]
	v_pk_fma_f32 v[114:115], v[46:47], v[80:81], v[114:115] op_sel_hi:[1,0,1]
	v_pk_fma_f32 v[116:117], v[46:47], v[80:81], v[116:117] op_sel:[0,1,0]
	v_pk_fma_f32 v[118:119], v[48:49], v[80:81], v[118:119] op_sel_hi:[1,0,1]
	v_pk_fma_f32 v[120:121], v[48:49], v[80:81], v[120:121] op_sel:[0,1,0]
	v_pk_fma_f32 v[72:73], v[72:73], v[38:39], v[114:115]
	v_pk_fma_f32 v[76:77], v[76:77], v[38:39], v[116:117]
	v_pk_fma_f32 v[74:75], v[74:75], v[40:41], v[118:119]
	v_pk_fma_f32 v[78:79], v[78:79], v[40:41], v[120:121]
	v_pk_mul_f32 v[122:123], v[72:73], v[42:43]
	v_pk_mul_f32 v[124:125], v[76:77], v[42:43]
	v_pk_fma_f32 v[122:123], v[74:75], v[44:45], v[122:123]
	v_pk_fma_f32 v[124:125], v[78:79], v[44:45], v[124:125]
	v_add_f32_e32 v126, v122, v123
	v_add_f32_e32 v127, v124, v125
	ds_write_b64 v187, v[126:127] offset:4096
	s_waitcnt lgkmcnt(1)
	v_pk_mul_f32 v[106:107], v[72:73], v[84:85]
	v_pk_mul_f32 v[108:109], v[76:77], v[84:85]
	v_pk_fma_f32 v[106:107], v[74:75], v[86:87], v[106:107]
	v_pk_fma_f32 v[108:109], v[78:79], v[86:87], v[108:109]
	v_add_f32_e32 v110, v106, v107
	v_add_f32_e32 v112, v108, v109
	ds_read_b128 v[30:33], v161 offset:9216
	v_add_f32_dpp v110, v110, v110 quad_perm:[1,0,3,2] row_mask:0xf bank_mask:0xf bound_ctrl:1
	v_add_f32_dpp v112, v112, v112 quad_perm:[1,0,3,2] row_mask:0xf bank_mask:0xf bound_ctrl:1
	ds_read_b128 v[34:37], v161 offset:17408
	v_add_f32_dpp v110, v110, v110 quad_perm:[2,3,0,1] row_mask:0xf bank_mask:0xf bound_ctrl:1
	v_add_f32_dpp v112, v112, v112 quad_perm:[2,3,0,1] row_mask:0xf bank_mask:0xf bound_ctrl:1
	ds_read_b128 v[46:49], v161 offset:25600
	v_add_f32_dpp v110, v110, v110 row_half_mirror row_mask:0xf bank_mask:0xf bound_ctrl:1
	v_add_f32_dpp v112, v112, v112 row_half_mirror row_mask:0xf bank_mask:0xf bound_ctrl:1
	ds_read_b64 v[80:81], v82 offset:41984
	v_add_f32_dpp v110, v110, v110 row_ror:8 row_mask:0xf bank_mask:0xf bound_ctrl:1
	v_add_f32_dpp v112, v112, v112 row_ror:8 row_mask:0xf bank_mask:0xf bound_ctrl:1
	ds_read_b128 v[38:41], v161 offset:1024
	ds_read_b128 v[42:45], v161 offset:33792
	v_pk_mul_f32 v[114:115], v[88:89], v[110:111] op_sel_hi:[1,0]
	v_pk_mul_f32 v[116:117], v[88:89], v[112:113] op_sel_hi:[1,0]
	v_pk_mul_f32 v[118:119], v[90:91], v[110:111] op_sel_hi:[1,0]
	v_pk_mul_f32 v[120:121], v[90:91], v[112:113] op_sel_hi:[1,0]
	v_pk_fma_f32 v[114:115], v[100:101], v[104:105], v[114:115] op_sel_hi:[1,0,1]
	v_pk_fma_f32 v[116:117], v[100:101], v[104:105], v[116:117] op_sel:[0,1,0]
	v_pk_fma_f32 v[118:119], v[102:103], v[104:105], v[118:119] op_sel_hi:[1,0,1]
	v_pk_fma_f32 v[120:121], v[102:103], v[104:105], v[120:121] op_sel:[0,1,0]
	v_pk_fma_f32 v[72:73], v[72:73], v[92:93], v[114:115]
	v_pk_fma_f32 v[76:77], v[76:77], v[92:93], v[116:117]
	v_pk_fma_f32 v[74:75], v[74:75], v[94:95], v[118:119]
	v_pk_fma_f32 v[78:79], v[78:79], v[94:95], v[120:121]
	v_pk_mul_f32 v[122:123], v[72:73], v[96:97]
	v_pk_mul_f32 v[124:125], v[76:77], v[96:97]
	v_pk_fma_f32 v[122:123], v[74:75], v[98:99], v[122:123]
	v_pk_fma_f32 v[124:125], v[78:79], v[98:99], v[124:125]
	v_add_f32_e32 v126, v122, v123
	v_add_f32_e32 v127, v124, v125
	ds_write_b64 v187, v[126:127] offset:6144
	s_waitcnt lgkmcnt(1)
	v_pk_mul_f32 v[106:107], v[72:73], v[30:31]
	v_pk_mul_f32 v[108:109], v[76:77], v[30:31]
	v_pk_fma_f32 v[106:107], v[74:75], v[32:33], v[106:107]
	v_pk_fma_f32 v[108:109], v[78:79], v[32:33], v[108:109]
	v_add_f32_e32 v110, v106, v107
	v_add_f32_e32 v112, v108, v109
	ds_read_b128 v[84:87], v161 offset:9472
	v_add_f32_dpp v110, v110, v110 quad_perm:[1,0,3,2] row_mask:0xf bank_mask:0xf bound_ctrl:1
	v_add_f32_dpp v112, v112, v112 quad_perm:[1,0,3,2] row_mask:0xf bank_mask:0xf bound_ctrl:1
	ds_read_b128 v[88:91], v161 offset:17664
	v_add_f32_dpp v110, v110, v110 quad_perm:[2,3,0,1] row_mask:0xf bank_mask:0xf bound_ctrl:1
	v_add_f32_dpp v112, v112, v112 quad_perm:[2,3,0,1] row_mask:0xf bank_mask:0xf bound_ctrl:1
	ds_read_b128 v[100:103], v161 offset:25856
	v_add_f32_dpp v110, v110, v110 row_half_mirror row_mask:0xf bank_mask:0xf bound_ctrl:1
	v_add_f32_dpp v112, v112, v112 row_half_mirror row_mask:0xf bank_mask:0xf bound_ctrl:1
	ds_read_b64 v[104:105], v82 offset:42240
	v_add_f32_dpp v110, v110, v110 row_ror:8 row_mask:0xf bank_mask:0xf bound_ctrl:1
	v_add_f32_dpp v112, v112, v112 row_ror:8 row_mask:0xf bank_mask:0xf bound_ctrl:1
	ds_read_b128 v[92:95], v161 offset:1280
	ds_read_b128 v[96:99], v161 offset:34048
	v_pk_mul_f32 v[114:115], v[34:35], v[110:111] op_sel_hi:[1,0]
	v_pk_mul_f32 v[116:117], v[34:35], v[112:113] op_sel_hi:[1,0]
	v_pk_mul_f32 v[118:119], v[36:37], v[110:111] op_sel_hi:[1,0]
	v_pk_mul_f32 v[120:121], v[36:37], v[112:113] op_sel_hi:[1,0]
	v_pk_fma_f32 v[114:115], v[46:47], v[80:81], v[114:115] op_sel_hi:[1,0,1]
	v_pk_fma_f32 v[116:117], v[46:47], v[80:81], v[116:117] op_sel:[0,1,0]
	v_pk_fma_f32 v[118:119], v[48:49], v[80:81], v[118:119] op_sel_hi:[1,0,1]
	v_pk_fma_f32 v[120:121], v[48:49], v[80:81], v[120:121] op_sel:[0,1,0]
	v_pk_fma_f32 v[72:73], v[72:73], v[38:39], v[114:115]
	v_pk_fma_f32 v[76:77], v[76:77], v[38:39], v[116:117]
	v_pk_fma_f32 v[74:75], v[74:75], v[40:41], v[118:119]
	v_pk_fma_f32 v[78:79], v[78:79], v[40:41], v[120:121]
	v_pk_mul_f32 v[122:123], v[72:73], v[42:43]
	v_pk_mul_f32 v[124:125], v[76:77], v[42:43]
	v_pk_fma_f32 v[122:123], v[74:75], v[44:45], v[122:123]
	v_pk_fma_f32 v[124:125], v[78:79], v[44:45], v[124:125]
	v_add_f32_e32 v126, v122, v123
	v_add_f32_e32 v127, v124, v125
	ds_write_b64 v187, v[126:127] offset:8192
	s_waitcnt lgkmcnt(1)
	v_pk_mul_f32 v[106:107], v[72:73], v[84:85]
	v_pk_mul_f32 v[108:109], v[76:77], v[84:85]
	v_pk_fma_f32 v[106:107], v[74:75], v[86:87], v[106:107]
	v_pk_fma_f32 v[108:109], v[78:79], v[86:87], v[108:109]
	v_add_f32_e32 v110, v106, v107
	v_add_f32_e32 v112, v108, v109
	ds_read_b128 v[30:33], v161 offset:9728
	v_add_f32_dpp v110, v110, v110 quad_perm:[1,0,3,2] row_mask:0xf bank_mask:0xf bound_ctrl:1
	v_add_f32_dpp v112, v112, v112 quad_perm:[1,0,3,2] row_mask:0xf bank_mask:0xf bound_ctrl:1
	ds_read_b128 v[34:37], v161 offset:17920
	v_add_f32_dpp v110, v110, v110 quad_perm:[2,3,0,1] row_mask:0xf bank_mask:0xf bound_ctrl:1
	v_add_f32_dpp v112, v112, v112 quad_perm:[2,3,0,1] row_mask:0xf bank_mask:0xf bound_ctrl:1
	ds_read_b128 v[46:49], v161 offset:26112
	v_add_f32_dpp v110, v110, v110 row_half_mirror row_mask:0xf bank_mask:0xf bound_ctrl:1
	v_add_f32_dpp v112, v112, v112 row_half_mirror row_mask:0xf bank_mask:0xf bound_ctrl:1
	ds_read_b64 v[80:81], v82 offset:42496
	v_add_f32_dpp v110, v110, v110 row_ror:8 row_mask:0xf bank_mask:0xf bound_ctrl:1
	v_add_f32_dpp v112, v112, v112 row_ror:8 row_mask:0xf bank_mask:0xf bound_ctrl:1
	ds_read_b128 v[38:41], v161 offset:1536
	ds_read_b128 v[42:45], v161 offset:34304
	v_pk_mul_f32 v[114:115], v[88:89], v[110:111] op_sel_hi:[1,0]
	v_pk_mul_f32 v[116:117], v[88:89], v[112:113] op_sel_hi:[1,0]
	v_pk_mul_f32 v[118:119], v[90:91], v[110:111] op_sel_hi:[1,0]
	v_pk_mul_f32 v[120:121], v[90:91], v[112:113] op_sel_hi:[1,0]
	v_pk_fma_f32 v[114:115], v[100:101], v[104:105], v[114:115] op_sel_hi:[1,0,1]
	v_pk_fma_f32 v[116:117], v[100:101], v[104:105], v[116:117] op_sel:[0,1,0]
	v_pk_fma_f32 v[118:119], v[102:103], v[104:105], v[118:119] op_sel_hi:[1,0,1]
	v_pk_fma_f32 v[120:121], v[102:103], v[104:105], v[120:121] op_sel:[0,1,0]
	v_pk_fma_f32 v[72:73], v[72:73], v[92:93], v[114:115]
	v_pk_fma_f32 v[76:77], v[76:77], v[92:93], v[116:117]
	v_pk_fma_f32 v[74:75], v[74:75], v[94:95], v[118:119]
	v_pk_fma_f32 v[78:79], v[78:79], v[94:95], v[120:121]
	v_pk_mul_f32 v[122:123], v[72:73], v[96:97]
	v_pk_mul_f32 v[124:125], v[76:77], v[96:97]
	v_pk_fma_f32 v[122:123], v[74:75], v[98:99], v[122:123]
	v_pk_fma_f32 v[124:125], v[78:79], v[98:99], v[124:125]
	v_add_f32_e32 v126, v122, v123
	v_add_f32_e32 v127, v124, v125
	ds_write_b64 v187, v[126:127] offset:10240
	s_waitcnt lgkmcnt(1)
	v_pk_mul_f32 v[106:107], v[72:73], v[30:31]
	v_pk_mul_f32 v[108:109], v[76:77], v[30:31]
	v_pk_fma_f32 v[106:107], v[74:75], v[32:33], v[106:107]
	v_pk_fma_f32 v[108:109], v[78:79], v[32:33], v[108:109]
	v_add_f32_e32 v110, v106, v107
	v_add_f32_e32 v112, v108, v109
	ds_read_b128 v[84:87], v161 offset:9984
	v_add_f32_dpp v110, v110, v110 quad_perm:[1,0,3,2] row_mask:0xf bank_mask:0xf bound_ctrl:1
	v_add_f32_dpp v112, v112, v112 quad_perm:[1,0,3,2] row_mask:0xf bank_mask:0xf bound_ctrl:1
	ds_read_b128 v[88:91], v161 offset:18176
	v_add_f32_dpp v110, v110, v110 quad_perm:[2,3,0,1] row_mask:0xf bank_mask:0xf bound_ctrl:1
	v_add_f32_dpp v112, v112, v112 quad_perm:[2,3,0,1] row_mask:0xf bank_mask:0xf bound_ctrl:1
	ds_read_b128 v[100:103], v161 offset:26368
	v_add_f32_dpp v110, v110, v110 row_half_mirror row_mask:0xf bank_mask:0xf bound_ctrl:1
	v_add_f32_dpp v112, v112, v112 row_half_mirror row_mask:0xf bank_mask:0xf bound_ctrl:1
	ds_read_b64 v[104:105], v82 offset:42752
	v_add_f32_dpp v110, v110, v110 row_ror:8 row_mask:0xf bank_mask:0xf bound_ctrl:1
	v_add_f32_dpp v112, v112, v112 row_ror:8 row_mask:0xf bank_mask:0xf bound_ctrl:1
	ds_read_b128 v[92:95], v161 offset:1792
	ds_read_b128 v[96:99], v161 offset:34560
	v_pk_mul_f32 v[114:115], v[34:35], v[110:111] op_sel_hi:[1,0]
	v_pk_mul_f32 v[116:117], v[34:35], v[112:113] op_sel_hi:[1,0]
	v_pk_mul_f32 v[118:119], v[36:37], v[110:111] op_sel_hi:[1,0]
	v_pk_mul_f32 v[120:121], v[36:37], v[112:113] op_sel_hi:[1,0]
	v_pk_fma_f32 v[114:115], v[46:47], v[80:81], v[114:115] op_sel_hi:[1,0,1]
	v_pk_fma_f32 v[116:117], v[46:47], v[80:81], v[116:117] op_sel:[0,1,0]
	v_pk_fma_f32 v[118:119], v[48:49], v[80:81], v[118:119] op_sel_hi:[1,0,1]
	v_pk_fma_f32 v[120:121], v[48:49], v[80:81], v[120:121] op_sel:[0,1,0]
	v_pk_fma_f32 v[72:73], v[72:73], v[38:39], v[114:115]
	v_pk_fma_f32 v[76:77], v[76:77], v[38:39], v[116:117]
	v_pk_fma_f32 v[74:75], v[74:75], v[40:41], v[118:119]
	v_pk_fma_f32 v[78:79], v[78:79], v[40:41], v[120:121]
	v_pk_mul_f32 v[122:123], v[72:73], v[42:43]
	v_pk_mul_f32 v[124:125], v[76:77], v[42:43]
	v_pk_fma_f32 v[122:123], v[74:75], v[44:45], v[122:123]
	v_pk_fma_f32 v[124:125], v[78:79], v[44:45], v[124:125]
	v_add_f32_e32 v126, v122, v123
	v_add_f32_e32 v127, v124, v125
	ds_write_b64 v187, v[126:127] offset:12288
	s_waitcnt lgkmcnt(1)
	v_pk_mul_f32 v[106:107], v[72:73], v[84:85]
	v_pk_mul_f32 v[108:109], v[76:77], v[84:85]
	v_pk_fma_f32 v[106:107], v[74:75], v[86:87], v[106:107]
	v_pk_fma_f32 v[108:109], v[78:79], v[86:87], v[108:109]
	v_add_f32_e32 v110, v106, v107
	v_add_f32_e32 v112, v108, v109
	ds_read_b128 v[30:33], v161 offset:10240
	v_add_f32_dpp v110, v110, v110 quad_perm:[1,0,3,2] row_mask:0xf bank_mask:0xf bound_ctrl:1
	v_add_f32_dpp v112, v112, v112 quad_perm:[1,0,3,2] row_mask:0xf bank_mask:0xf bound_ctrl:1
	ds_read_b128 v[34:37], v161 offset:18432
	v_add_f32_dpp v110, v110, v110 quad_perm:[2,3,0,1] row_mask:0xf bank_mask:0xf bound_ctrl:1
	v_add_f32_dpp v112, v112, v112 quad_perm:[2,3,0,1] row_mask:0xf bank_mask:0xf bound_ctrl:1
	ds_read_b128 v[46:49], v161 offset:26624
	v_add_f32_dpp v110, v110, v110 row_half_mirror row_mask:0xf bank_mask:0xf bound_ctrl:1
	v_add_f32_dpp v112, v112, v112 row_half_mirror row_mask:0xf bank_mask:0xf bound_ctrl:1
	ds_read_b64 v[80:81], v82 offset:43008
	v_add_f32_dpp v110, v110, v110 row_ror:8 row_mask:0xf bank_mask:0xf bound_ctrl:1
	v_add_f32_dpp v112, v112, v112 row_ror:8 row_mask:0xf bank_mask:0xf bound_ctrl:1
	ds_read_b128 v[38:41], v161 offset:2048
	ds_read_b128 v[42:45], v161 offset:34816
	v_pk_mul_f32 v[114:115], v[88:89], v[110:111] op_sel_hi:[1,0]
	v_pk_mul_f32 v[116:117], v[88:89], v[112:113] op_sel_hi:[1,0]
	v_pk_mul_f32 v[118:119], v[90:91], v[110:111] op_sel_hi:[1,0]
	v_pk_mul_f32 v[120:121], v[90:91], v[112:113] op_sel_hi:[1,0]
	v_pk_fma_f32 v[114:115], v[100:101], v[104:105], v[114:115] op_sel_hi:[1,0,1]
	v_pk_fma_f32 v[116:117], v[100:101], v[104:105], v[116:117] op_sel:[0,1,0]
	v_pk_fma_f32 v[118:119], v[102:103], v[104:105], v[118:119] op_sel_hi:[1,0,1]
	v_pk_fma_f32 v[120:121], v[102:103], v[104:105], v[120:121] op_sel:[0,1,0]
	v_pk_fma_f32 v[72:73], v[72:73], v[92:93], v[114:115]
	v_pk_fma_f32 v[76:77], v[76:77], v[92:93], v[116:117]
	v_pk_fma_f32 v[74:75], v[74:75], v[94:95], v[118:119]
	v_pk_fma_f32 v[78:79], v[78:79], v[94:95], v[120:121]
	v_pk_mul_f32 v[122:123], v[72:73], v[96:97]
	v_pk_mul_f32 v[124:125], v[76:77], v[96:97]
	v_pk_fma_f32 v[122:123], v[74:75], v[98:99], v[122:123]
	v_pk_fma_f32 v[124:125], v[78:79], v[98:99], v[124:125]
	v_add_f32_e32 v126, v122, v123
	v_add_f32_e32 v127, v124, v125
	ds_write_b64 v187, v[126:127] offset:14336
	s_waitcnt lgkmcnt(1)
	v_pk_mul_f32 v[106:107], v[72:73], v[30:31]
	v_pk_mul_f32 v[108:109], v[76:77], v[30:31]
	v_pk_fma_f32 v[106:107], v[74:75], v[32:33], v[106:107]
	v_pk_fma_f32 v[108:109], v[78:79], v[32:33], v[108:109]
	v_add_f32_e32 v110, v106, v107
	v_add_f32_e32 v112, v108, v109
	ds_read_b128 v[84:87], v161 offset:10496
	v_add_f32_dpp v110, v110, v110 quad_perm:[1,0,3,2] row_mask:0xf bank_mask:0xf bound_ctrl:1
	v_add_f32_dpp v112, v112, v112 quad_perm:[1,0,3,2] row_mask:0xf bank_mask:0xf bound_ctrl:1
	ds_read_b128 v[88:91], v161 offset:18688
	v_add_f32_dpp v110, v110, v110 quad_perm:[2,3,0,1] row_mask:0xf bank_mask:0xf bound_ctrl:1
	v_add_f32_dpp v112, v112, v112 quad_perm:[2,3,0,1] row_mask:0xf bank_mask:0xf bound_ctrl:1
	ds_read_b128 v[100:103], v161 offset:26880
	v_add_f32_dpp v110, v110, v110 row_half_mirror row_mask:0xf bank_mask:0xf bound_ctrl:1
	v_add_f32_dpp v112, v112, v112 row_half_mirror row_mask:0xf bank_mask:0xf bound_ctrl:1
	ds_read_b64 v[104:105], v82 offset:43264
	v_add_f32_dpp v110, v110, v110 row_ror:8 row_mask:0xf bank_mask:0xf bound_ctrl:1
	v_add_f32_dpp v112, v112, v112 row_ror:8 row_mask:0xf bank_mask:0xf bound_ctrl:1
	ds_read_b128 v[92:95], v161 offset:2304
	ds_read_b128 v[96:99], v161 offset:35072
	v_pk_mul_f32 v[114:115], v[34:35], v[110:111] op_sel_hi:[1,0]
	v_pk_mul_f32 v[116:117], v[34:35], v[112:113] op_sel_hi:[1,0]
	v_pk_mul_f32 v[118:119], v[36:37], v[110:111] op_sel_hi:[1,0]
	v_pk_mul_f32 v[120:121], v[36:37], v[112:113] op_sel_hi:[1,0]
	v_pk_fma_f32 v[114:115], v[46:47], v[80:81], v[114:115] op_sel_hi:[1,0,1]
	v_pk_fma_f32 v[116:117], v[46:47], v[80:81], v[116:117] op_sel:[0,1,0]
	v_pk_fma_f32 v[118:119], v[48:49], v[80:81], v[118:119] op_sel_hi:[1,0,1]
	v_pk_fma_f32 v[120:121], v[48:49], v[80:81], v[120:121] op_sel:[0,1,0]
	v_pk_fma_f32 v[72:73], v[72:73], v[38:39], v[114:115]
	v_pk_fma_f32 v[76:77], v[76:77], v[38:39], v[116:117]
	v_pk_fma_f32 v[74:75], v[74:75], v[40:41], v[118:119]
	v_pk_fma_f32 v[78:79], v[78:79], v[40:41], v[120:121]
	v_pk_mul_f32 v[122:123], v[72:73], v[42:43]
	v_pk_mul_f32 v[124:125], v[76:77], v[42:43]
	v_pk_fma_f32 v[122:123], v[74:75], v[44:45], v[122:123]
	v_pk_fma_f32 v[124:125], v[78:79], v[44:45], v[124:125]
	v_add_f32_e32 v126, v122, v123
	v_add_f32_e32 v127, v124, v125
	ds_write_b64 v187, v[126:127] offset:16384
	s_waitcnt lgkmcnt(1)
	v_pk_mul_f32 v[106:107], v[72:73], v[84:85]
	v_pk_mul_f32 v[108:109], v[76:77], v[84:85]
	v_pk_fma_f32 v[106:107], v[74:75], v[86:87], v[106:107]
	v_pk_fma_f32 v[108:109], v[78:79], v[86:87], v[108:109]
	v_add_f32_e32 v110, v106, v107
	v_add_f32_e32 v112, v108, v109
	ds_read_b128 v[30:33], v161 offset:10752
	v_add_f32_dpp v110, v110, v110 quad_perm:[1,0,3,2] row_mask:0xf bank_mask:0xf bound_ctrl:1
	v_add_f32_dpp v112, v112, v112 quad_perm:[1,0,3,2] row_mask:0xf bank_mask:0xf bound_ctrl:1
	ds_read_b128 v[34:37], v161 offset:18944
	v_add_f32_dpp v110, v110, v110 quad_perm:[2,3,0,1] row_mask:0xf bank_mask:0xf bound_ctrl:1
	v_add_f32_dpp v112, v112, v112 quad_perm:[2,3,0,1] row_mask:0xf bank_mask:0xf bound_ctrl:1
	ds_read_b128 v[46:49], v161 offset:27136
	v_add_f32_dpp v110, v110, v110 row_half_mirror row_mask:0xf bank_mask:0xf bound_ctrl:1
	v_add_f32_dpp v112, v112, v112 row_half_mirror row_mask:0xf bank_mask:0xf bound_ctrl:1
	ds_read_b64 v[80:81], v82 offset:43520
	v_add_f32_dpp v110, v110, v110 row_ror:8 row_mask:0xf bank_mask:0xf bound_ctrl:1
	v_add_f32_dpp v112, v112, v112 row_ror:8 row_mask:0xf bank_mask:0xf bound_ctrl:1
	ds_read_b128 v[38:41], v161 offset:2560
	ds_read_b128 v[42:45], v161 offset:35328
	v_pk_mul_f32 v[114:115], v[88:89], v[110:111] op_sel_hi:[1,0]
	v_pk_mul_f32 v[116:117], v[88:89], v[112:113] op_sel_hi:[1,0]
	v_pk_mul_f32 v[118:119], v[90:91], v[110:111] op_sel_hi:[1,0]
	v_pk_mul_f32 v[120:121], v[90:91], v[112:113] op_sel_hi:[1,0]
	v_pk_fma_f32 v[114:115], v[100:101], v[104:105], v[114:115] op_sel_hi:[1,0,1]
	v_pk_fma_f32 v[116:117], v[100:101], v[104:105], v[116:117] op_sel:[0,1,0]
	v_pk_fma_f32 v[118:119], v[102:103], v[104:105], v[118:119] op_sel_hi:[1,0,1]
	v_pk_fma_f32 v[120:121], v[102:103], v[104:105], v[120:121] op_sel:[0,1,0]
	v_pk_fma_f32 v[72:73], v[72:73], v[92:93], v[114:115]
	v_pk_fma_f32 v[76:77], v[76:77], v[92:93], v[116:117]
	v_pk_fma_f32 v[74:75], v[74:75], v[94:95], v[118:119]
	v_pk_fma_f32 v[78:79], v[78:79], v[94:95], v[120:121]
	v_pk_mul_f32 v[122:123], v[72:73], v[96:97]
	v_pk_mul_f32 v[124:125], v[76:77], v[96:97]
	v_pk_fma_f32 v[122:123], v[74:75], v[98:99], v[122:123]
	v_pk_fma_f32 v[124:125], v[78:79], v[98:99], v[124:125]
	v_add_f32_e32 v126, v122, v123
	v_add_f32_e32 v127, v124, v125
	ds_write_b64 v187, v[126:127] offset:18432
	s_waitcnt lgkmcnt(1)
	v_pk_mul_f32 v[106:107], v[72:73], v[30:31]
	v_pk_mul_f32 v[108:109], v[76:77], v[30:31]
	v_pk_fma_f32 v[106:107], v[74:75], v[32:33], v[106:107]
	v_pk_fma_f32 v[108:109], v[78:79], v[32:33], v[108:109]
	v_add_f32_e32 v110, v106, v107
	v_add_f32_e32 v112, v108, v109
	ds_read_b128 v[84:87], v161 offset:11008
	v_add_f32_dpp v110, v110, v110 quad_perm:[1,0,3,2] row_mask:0xf bank_mask:0xf bound_ctrl:1
	v_add_f32_dpp v112, v112, v112 quad_perm:[1,0,3,2] row_mask:0xf bank_mask:0xf bound_ctrl:1
	ds_read_b128 v[88:91], v161 offset:19200
	v_add_f32_dpp v110, v110, v110 quad_perm:[2,3,0,1] row_mask:0xf bank_mask:0xf bound_ctrl:1
	v_add_f32_dpp v112, v112, v112 quad_perm:[2,3,0,1] row_mask:0xf bank_mask:0xf bound_ctrl:1
	ds_read_b128 v[100:103], v161 offset:27392
	v_add_f32_dpp v110, v110, v110 row_half_mirror row_mask:0xf bank_mask:0xf bound_ctrl:1
	v_add_f32_dpp v112, v112, v112 row_half_mirror row_mask:0xf bank_mask:0xf bound_ctrl:1
	ds_read_b64 v[104:105], v82 offset:43776
	v_add_f32_dpp v110, v110, v110 row_ror:8 row_mask:0xf bank_mask:0xf bound_ctrl:1
	v_add_f32_dpp v112, v112, v112 row_ror:8 row_mask:0xf bank_mask:0xf bound_ctrl:1
	ds_read_b128 v[92:95], v161 offset:2816
	ds_read_b128 v[96:99], v161 offset:35584
	v_pk_mul_f32 v[114:115], v[34:35], v[110:111] op_sel_hi:[1,0]
	v_pk_mul_f32 v[116:117], v[34:35], v[112:113] op_sel_hi:[1,0]
	v_pk_mul_f32 v[118:119], v[36:37], v[110:111] op_sel_hi:[1,0]
	v_pk_mul_f32 v[120:121], v[36:37], v[112:113] op_sel_hi:[1,0]
	v_pk_fma_f32 v[114:115], v[46:47], v[80:81], v[114:115] op_sel_hi:[1,0,1]
	v_pk_fma_f32 v[116:117], v[46:47], v[80:81], v[116:117] op_sel:[0,1,0]
	v_pk_fma_f32 v[118:119], v[48:49], v[80:81], v[118:119] op_sel_hi:[1,0,1]
	v_pk_fma_f32 v[120:121], v[48:49], v[80:81], v[120:121] op_sel:[0,1,0]
	v_pk_fma_f32 v[72:73], v[72:73], v[38:39], v[114:115]
	v_pk_fma_f32 v[76:77], v[76:77], v[38:39], v[116:117]
	v_pk_fma_f32 v[74:75], v[74:75], v[40:41], v[118:119]
	v_pk_fma_f32 v[78:79], v[78:79], v[40:41], v[120:121]
	v_pk_mul_f32 v[122:123], v[72:73], v[42:43]
	v_pk_mul_f32 v[124:125], v[76:77], v[42:43]
	v_pk_fma_f32 v[122:123], v[74:75], v[44:45], v[122:123]
	v_pk_fma_f32 v[124:125], v[78:79], v[44:45], v[124:125]
	v_add_f32_e32 v126, v122, v123
	v_add_f32_e32 v127, v124, v125
	ds_write_b64 v187, v[126:127] offset:20480
	s_waitcnt lgkmcnt(1)
	v_pk_mul_f32 v[106:107], v[72:73], v[84:85]
	v_pk_mul_f32 v[108:109], v[76:77], v[84:85]
	v_pk_fma_f32 v[106:107], v[74:75], v[86:87], v[106:107]
	v_pk_fma_f32 v[108:109], v[78:79], v[86:87], v[108:109]
	v_add_f32_e32 v110, v106, v107
	v_add_f32_e32 v112, v108, v109
	ds_read_b128 v[30:33], v161 offset:11264
	v_add_f32_dpp v110, v110, v110 quad_perm:[1,0,3,2] row_mask:0xf bank_mask:0xf bound_ctrl:1
	v_add_f32_dpp v112, v112, v112 quad_perm:[1,0,3,2] row_mask:0xf bank_mask:0xf bound_ctrl:1
	ds_read_b128 v[34:37], v161 offset:19456
	v_add_f32_dpp v110, v110, v110 quad_perm:[2,3,0,1] row_mask:0xf bank_mask:0xf bound_ctrl:1
	v_add_f32_dpp v112, v112, v112 quad_perm:[2,3,0,1] row_mask:0xf bank_mask:0xf bound_ctrl:1
	ds_read_b128 v[46:49], v161 offset:27648
	v_add_f32_dpp v110, v110, v110 row_half_mirror row_mask:0xf bank_mask:0xf bound_ctrl:1
	v_add_f32_dpp v112, v112, v112 row_half_mirror row_mask:0xf bank_mask:0xf bound_ctrl:1
	ds_read_b64 v[80:81], v82 offset:44032
	v_add_f32_dpp v110, v110, v110 row_ror:8 row_mask:0xf bank_mask:0xf bound_ctrl:1
	v_add_f32_dpp v112, v112, v112 row_ror:8 row_mask:0xf bank_mask:0xf bound_ctrl:1
	ds_read_b128 v[38:41], v161 offset:3072
	ds_read_b128 v[42:45], v161 offset:35840
	v_pk_mul_f32 v[114:115], v[88:89], v[110:111] op_sel_hi:[1,0]
	v_pk_mul_f32 v[116:117], v[88:89], v[112:113] op_sel_hi:[1,0]
	v_pk_mul_f32 v[118:119], v[90:91], v[110:111] op_sel_hi:[1,0]
	v_pk_mul_f32 v[120:121], v[90:91], v[112:113] op_sel_hi:[1,0]
	v_pk_fma_f32 v[114:115], v[100:101], v[104:105], v[114:115] op_sel_hi:[1,0,1]
	v_pk_fma_f32 v[116:117], v[100:101], v[104:105], v[116:117] op_sel:[0,1,0]
	v_pk_fma_f32 v[118:119], v[102:103], v[104:105], v[118:119] op_sel_hi:[1,0,1]
	v_pk_fma_f32 v[120:121], v[102:103], v[104:105], v[120:121] op_sel:[0,1,0]
	v_pk_fma_f32 v[72:73], v[72:73], v[92:93], v[114:115]
	v_pk_fma_f32 v[76:77], v[76:77], v[92:93], v[116:117]
	v_pk_fma_f32 v[74:75], v[74:75], v[94:95], v[118:119]
	v_pk_fma_f32 v[78:79], v[78:79], v[94:95], v[120:121]
	v_pk_mul_f32 v[122:123], v[72:73], v[96:97]
	v_pk_mul_f32 v[124:125], v[76:77], v[96:97]
	v_pk_fma_f32 v[122:123], v[74:75], v[98:99], v[122:123]
	v_pk_fma_f32 v[124:125], v[78:79], v[98:99], v[124:125]
	v_add_f32_e32 v126, v122, v123
	v_add_f32_e32 v127, v124, v125
	ds_write_b64 v187, v[126:127] offset:22528
	s_waitcnt lgkmcnt(1)
	v_pk_mul_f32 v[106:107], v[72:73], v[30:31]
	v_pk_mul_f32 v[108:109], v[76:77], v[30:31]
	v_pk_fma_f32 v[106:107], v[74:75], v[32:33], v[106:107]
	v_pk_fma_f32 v[108:109], v[78:79], v[32:33], v[108:109]
	v_add_f32_e32 v110, v106, v107
	v_add_f32_e32 v112, v108, v109
	ds_read_b128 v[84:87], v161 offset:11520
	v_add_f32_dpp v110, v110, v110 quad_perm:[1,0,3,2] row_mask:0xf bank_mask:0xf bound_ctrl:1
	v_add_f32_dpp v112, v112, v112 quad_perm:[1,0,3,2] row_mask:0xf bank_mask:0xf bound_ctrl:1
	ds_read_b128 v[88:91], v161 offset:19712
	v_add_f32_dpp v110, v110, v110 quad_perm:[2,3,0,1] row_mask:0xf bank_mask:0xf bound_ctrl:1
	v_add_f32_dpp v112, v112, v112 quad_perm:[2,3,0,1] row_mask:0xf bank_mask:0xf bound_ctrl:1
	ds_read_b128 v[100:103], v161 offset:27904
	v_add_f32_dpp v110, v110, v110 row_half_mirror row_mask:0xf bank_mask:0xf bound_ctrl:1
	v_add_f32_dpp v112, v112, v112 row_half_mirror row_mask:0xf bank_mask:0xf bound_ctrl:1
	ds_read_b64 v[104:105], v82 offset:44288
	v_add_f32_dpp v110, v110, v110 row_ror:8 row_mask:0xf bank_mask:0xf bound_ctrl:1
	v_add_f32_dpp v112, v112, v112 row_ror:8 row_mask:0xf bank_mask:0xf bound_ctrl:1
	ds_read_b128 v[92:95], v161 offset:3328
	ds_read_b128 v[96:99], v161 offset:36096
	v_pk_mul_f32 v[114:115], v[34:35], v[110:111] op_sel_hi:[1,0]
	v_pk_mul_f32 v[116:117], v[34:35], v[112:113] op_sel_hi:[1,0]
	v_pk_mul_f32 v[118:119], v[36:37], v[110:111] op_sel_hi:[1,0]
	v_pk_mul_f32 v[120:121], v[36:37], v[112:113] op_sel_hi:[1,0]
	v_pk_fma_f32 v[114:115], v[46:47], v[80:81], v[114:115] op_sel_hi:[1,0,1]
	v_pk_fma_f32 v[116:117], v[46:47], v[80:81], v[116:117] op_sel:[0,1,0]
	v_pk_fma_f32 v[118:119], v[48:49], v[80:81], v[118:119] op_sel_hi:[1,0,1]
	v_pk_fma_f32 v[120:121], v[48:49], v[80:81], v[120:121] op_sel:[0,1,0]
	v_pk_fma_f32 v[72:73], v[72:73], v[38:39], v[114:115]
	v_pk_fma_f32 v[76:77], v[76:77], v[38:39], v[116:117]
	v_pk_fma_f32 v[74:75], v[74:75], v[40:41], v[118:119]
	v_pk_fma_f32 v[78:79], v[78:79], v[40:41], v[120:121]
	v_pk_mul_f32 v[122:123], v[72:73], v[42:43]
	v_pk_mul_f32 v[124:125], v[76:77], v[42:43]
	v_pk_fma_f32 v[122:123], v[74:75], v[44:45], v[122:123]
	v_pk_fma_f32 v[124:125], v[78:79], v[44:45], v[124:125]
	v_add_f32_e32 v126, v122, v123
	v_add_f32_e32 v127, v124, v125
	ds_write_b64 v187, v[126:127] offset:24576
	s_waitcnt lgkmcnt(1)
	v_pk_mul_f32 v[106:107], v[72:73], v[84:85]
	v_pk_mul_f32 v[108:109], v[76:77], v[84:85]
	v_pk_fma_f32 v[106:107], v[74:75], v[86:87], v[106:107]
	v_pk_fma_f32 v[108:109], v[78:79], v[86:87], v[108:109]
	v_add_f32_e32 v110, v106, v107
	v_add_f32_e32 v112, v108, v109
	ds_read_b128 v[30:33], v161 offset:11776
	v_add_f32_dpp v110, v110, v110 quad_perm:[1,0,3,2] row_mask:0xf bank_mask:0xf bound_ctrl:1
	v_add_f32_dpp v112, v112, v112 quad_perm:[1,0,3,2] row_mask:0xf bank_mask:0xf bound_ctrl:1
	ds_read_b128 v[34:37], v161 offset:19968
	v_add_f32_dpp v110, v110, v110 quad_perm:[2,3,0,1] row_mask:0xf bank_mask:0xf bound_ctrl:1
	v_add_f32_dpp v112, v112, v112 quad_perm:[2,3,0,1] row_mask:0xf bank_mask:0xf bound_ctrl:1
	ds_read_b128 v[46:49], v161 offset:28160
	v_add_f32_dpp v110, v110, v110 row_half_mirror row_mask:0xf bank_mask:0xf bound_ctrl:1
	v_add_f32_dpp v112, v112, v112 row_half_mirror row_mask:0xf bank_mask:0xf bound_ctrl:1
	ds_read_b64 v[80:81], v82 offset:44544
	v_add_f32_dpp v110, v110, v110 row_ror:8 row_mask:0xf bank_mask:0xf bound_ctrl:1
	v_add_f32_dpp v112, v112, v112 row_ror:8 row_mask:0xf bank_mask:0xf bound_ctrl:1
	ds_read_b128 v[38:41], v161 offset:3584
	ds_read_b128 v[42:45], v161 offset:36352
	v_pk_mul_f32 v[114:115], v[88:89], v[110:111] op_sel_hi:[1,0]
	v_pk_mul_f32 v[116:117], v[88:89], v[112:113] op_sel_hi:[1,0]
	v_pk_mul_f32 v[118:119], v[90:91], v[110:111] op_sel_hi:[1,0]
	v_pk_mul_f32 v[120:121], v[90:91], v[112:113] op_sel_hi:[1,0]
	v_pk_fma_f32 v[114:115], v[100:101], v[104:105], v[114:115] op_sel_hi:[1,0,1]
	v_pk_fma_f32 v[116:117], v[100:101], v[104:105], v[116:117] op_sel:[0,1,0]
	v_pk_fma_f32 v[118:119], v[102:103], v[104:105], v[118:119] op_sel_hi:[1,0,1]
	v_pk_fma_f32 v[120:121], v[102:103], v[104:105], v[120:121] op_sel:[0,1,0]
	v_pk_fma_f32 v[72:73], v[72:73], v[92:93], v[114:115]
	v_pk_fma_f32 v[76:77], v[76:77], v[92:93], v[116:117]
	v_pk_fma_f32 v[74:75], v[74:75], v[94:95], v[118:119]
	v_pk_fma_f32 v[78:79], v[78:79], v[94:95], v[120:121]
	v_pk_mul_f32 v[122:123], v[72:73], v[96:97]
	v_pk_mul_f32 v[124:125], v[76:77], v[96:97]
	v_pk_fma_f32 v[122:123], v[74:75], v[98:99], v[122:123]
	v_pk_fma_f32 v[124:125], v[78:79], v[98:99], v[124:125]
	v_add_f32_e32 v126, v122, v123
	v_add_f32_e32 v127, v124, v125
	ds_write_b64 v187, v[126:127] offset:26624
	s_waitcnt lgkmcnt(1)
	v_pk_mul_f32 v[106:107], v[72:73], v[30:31]
	v_pk_mul_f32 v[108:109], v[76:77], v[30:31]
	v_pk_fma_f32 v[106:107], v[74:75], v[32:33], v[106:107]
	v_pk_fma_f32 v[108:109], v[78:79], v[32:33], v[108:109]
	v_add_f32_e32 v110, v106, v107
	v_add_f32_e32 v112, v108, v109
	ds_read_b128 v[84:87], v161 offset:12032
	v_add_f32_dpp v110, v110, v110 quad_perm:[1,0,3,2] row_mask:0xf bank_mask:0xf bound_ctrl:1
	v_add_f32_dpp v112, v112, v112 quad_perm:[1,0,3,2] row_mask:0xf bank_mask:0xf bound_ctrl:1
	ds_read_b128 v[88:91], v161 offset:20224
	v_add_f32_dpp v110, v110, v110 quad_perm:[2,3,0,1] row_mask:0xf bank_mask:0xf bound_ctrl:1
	v_add_f32_dpp v112, v112, v112 quad_perm:[2,3,0,1] row_mask:0xf bank_mask:0xf bound_ctrl:1
	ds_read_b128 v[100:103], v161 offset:28416
	v_add_f32_dpp v110, v110, v110 row_half_mirror row_mask:0xf bank_mask:0xf bound_ctrl:1
	v_add_f32_dpp v112, v112, v112 row_half_mirror row_mask:0xf bank_mask:0xf bound_ctrl:1
	ds_read_b64 v[104:105], v82 offset:44800
	v_add_f32_dpp v110, v110, v110 row_ror:8 row_mask:0xf bank_mask:0xf bound_ctrl:1
	v_add_f32_dpp v112, v112, v112 row_ror:8 row_mask:0xf bank_mask:0xf bound_ctrl:1
	ds_read_b128 v[92:95], v161 offset:3840
	ds_read_b128 v[96:99], v161 offset:36608
	v_pk_mul_f32 v[114:115], v[34:35], v[110:111] op_sel_hi:[1,0]
	v_pk_mul_f32 v[116:117], v[34:35], v[112:113] op_sel_hi:[1,0]
	v_pk_mul_f32 v[118:119], v[36:37], v[110:111] op_sel_hi:[1,0]
	v_pk_mul_f32 v[120:121], v[36:37], v[112:113] op_sel_hi:[1,0]
	v_pk_fma_f32 v[114:115], v[46:47], v[80:81], v[114:115] op_sel_hi:[1,0,1]
	v_pk_fma_f32 v[116:117], v[46:47], v[80:81], v[116:117] op_sel:[0,1,0]
	v_pk_fma_f32 v[118:119], v[48:49], v[80:81], v[118:119] op_sel_hi:[1,0,1]
	v_pk_fma_f32 v[120:121], v[48:49], v[80:81], v[120:121] op_sel:[0,1,0]
	v_pk_fma_f32 v[72:73], v[72:73], v[38:39], v[114:115]
	v_pk_fma_f32 v[76:77], v[76:77], v[38:39], v[116:117]
	v_pk_fma_f32 v[74:75], v[74:75], v[40:41], v[118:119]
	v_pk_fma_f32 v[78:79], v[78:79], v[40:41], v[120:121]
	v_pk_mul_f32 v[122:123], v[72:73], v[42:43]
	v_pk_mul_f32 v[124:125], v[76:77], v[42:43]
	v_pk_fma_f32 v[122:123], v[74:75], v[44:45], v[122:123]
	v_pk_fma_f32 v[124:125], v[78:79], v[44:45], v[124:125]
	v_add_f32_e32 v126, v122, v123
	v_add_f32_e32 v127, v124, v125
	ds_write_b64 v187, v[126:127] offset:28672
	s_waitcnt lgkmcnt(1)
	v_pk_mul_f32 v[106:107], v[72:73], v[84:85]
	v_pk_mul_f32 v[108:109], v[76:77], v[84:85]
	v_pk_fma_f32 v[106:107], v[74:75], v[86:87], v[106:107]
	v_pk_fma_f32 v[108:109], v[78:79], v[86:87], v[108:109]
	v_add_f32_e32 v110, v106, v107
	v_add_f32_e32 v112, v108, v109
	ds_read_b128 v[30:33], v161 offset:12288
	v_add_f32_dpp v110, v110, v110 quad_perm:[1,0,3,2] row_mask:0xf bank_mask:0xf bound_ctrl:1
	v_add_f32_dpp v112, v112, v112 quad_perm:[1,0,3,2] row_mask:0xf bank_mask:0xf bound_ctrl:1
	ds_read_b128 v[34:37], v161 offset:20480
	v_add_f32_dpp v110, v110, v110 quad_perm:[2,3,0,1] row_mask:0xf bank_mask:0xf bound_ctrl:1
	v_add_f32_dpp v112, v112, v112 quad_perm:[2,3,0,1] row_mask:0xf bank_mask:0xf bound_ctrl:1
	ds_read_b128 v[46:49], v161 offset:28672
	v_add_f32_dpp v110, v110, v110 row_half_mirror row_mask:0xf bank_mask:0xf bound_ctrl:1
	v_add_f32_dpp v112, v112, v112 row_half_mirror row_mask:0xf bank_mask:0xf bound_ctrl:1
	ds_read_b64 v[80:81], v82 offset:45056
	v_add_f32_dpp v110, v110, v110 row_ror:8 row_mask:0xf bank_mask:0xf bound_ctrl:1
	v_add_f32_dpp v112, v112, v112 row_ror:8 row_mask:0xf bank_mask:0xf bound_ctrl:1
	ds_read_b128 v[38:41], v161 offset:4096
	ds_read_b128 v[42:45], v161 offset:36864
	v_pk_mul_f32 v[114:115], v[88:89], v[110:111] op_sel_hi:[1,0]
	v_pk_mul_f32 v[116:117], v[88:89], v[112:113] op_sel_hi:[1,0]
	v_pk_mul_f32 v[118:119], v[90:91], v[110:111] op_sel_hi:[1,0]
	v_pk_mul_f32 v[120:121], v[90:91], v[112:113] op_sel_hi:[1,0]
	v_pk_fma_f32 v[114:115], v[100:101], v[104:105], v[114:115] op_sel_hi:[1,0,1]
	v_pk_fma_f32 v[116:117], v[100:101], v[104:105], v[116:117] op_sel:[0,1,0]
	v_pk_fma_f32 v[118:119], v[102:103], v[104:105], v[118:119] op_sel_hi:[1,0,1]
	v_pk_fma_f32 v[120:121], v[102:103], v[104:105], v[120:121] op_sel:[0,1,0]
	v_pk_fma_f32 v[72:73], v[72:73], v[92:93], v[114:115]
	v_pk_fma_f32 v[76:77], v[76:77], v[92:93], v[116:117]
	v_pk_fma_f32 v[74:75], v[74:75], v[94:95], v[118:119]
	v_pk_fma_f32 v[78:79], v[78:79], v[94:95], v[120:121]
	v_pk_mul_f32 v[122:123], v[72:73], v[96:97]
	v_pk_mul_f32 v[124:125], v[76:77], v[96:97]
	v_pk_fma_f32 v[122:123], v[74:75], v[98:99], v[122:123]
	v_pk_fma_f32 v[124:125], v[78:79], v[98:99], v[124:125]
	v_add_f32_e32 v126, v122, v123
	v_add_f32_e32 v127, v124, v125
	ds_write_b64 v187, v[126:127] offset:30720
	s_waitcnt lgkmcnt(1)
	v_pk_mul_f32 v[106:107], v[72:73], v[30:31]
	v_pk_mul_f32 v[108:109], v[76:77], v[30:31]
	v_pk_fma_f32 v[106:107], v[74:75], v[32:33], v[106:107]
	v_pk_fma_f32 v[108:109], v[78:79], v[32:33], v[108:109]
	v_add_f32_e32 v110, v106, v107
	v_add_f32_e32 v112, v108, v109
	ds_read_b128 v[84:87], v161 offset:12544
	v_add_f32_dpp v110, v110, v110 quad_perm:[1,0,3,2] row_mask:0xf bank_mask:0xf bound_ctrl:1
	v_add_f32_dpp v112, v112, v112 quad_perm:[1,0,3,2] row_mask:0xf bank_mask:0xf bound_ctrl:1
	ds_read_b128 v[88:91], v161 offset:20736
	v_add_f32_dpp v110, v110, v110 quad_perm:[2,3,0,1] row_mask:0xf bank_mask:0xf bound_ctrl:1
	v_add_f32_dpp v112, v112, v112 quad_perm:[2,3,0,1] row_mask:0xf bank_mask:0xf bound_ctrl:1
	ds_read_b128 v[100:103], v161 offset:28928
	v_add_f32_dpp v110, v110, v110 row_half_mirror row_mask:0xf bank_mask:0xf bound_ctrl:1
	v_add_f32_dpp v112, v112, v112 row_half_mirror row_mask:0xf bank_mask:0xf bound_ctrl:1
	ds_read_b64 v[104:105], v82 offset:45312
	v_add_f32_dpp v110, v110, v110 row_ror:8 row_mask:0xf bank_mask:0xf bound_ctrl:1
	v_add_f32_dpp v112, v112, v112 row_ror:8 row_mask:0xf bank_mask:0xf bound_ctrl:1
	ds_read_b128 v[92:95], v161 offset:4352
	ds_read_b128 v[96:99], v161 offset:37120
	v_pk_mul_f32 v[114:115], v[34:35], v[110:111] op_sel_hi:[1,0]
	v_pk_mul_f32 v[116:117], v[34:35], v[112:113] op_sel_hi:[1,0]
	v_pk_mul_f32 v[118:119], v[36:37], v[110:111] op_sel_hi:[1,0]
	v_pk_mul_f32 v[120:121], v[36:37], v[112:113] op_sel_hi:[1,0]
	v_pk_fma_f32 v[114:115], v[46:47], v[80:81], v[114:115] op_sel_hi:[1,0,1]
	v_pk_fma_f32 v[116:117], v[46:47], v[80:81], v[116:117] op_sel:[0,1,0]
	v_pk_fma_f32 v[118:119], v[48:49], v[80:81], v[118:119] op_sel_hi:[1,0,1]
	v_pk_fma_f32 v[120:121], v[48:49], v[80:81], v[120:121] op_sel:[0,1,0]
	v_pk_fma_f32 v[72:73], v[72:73], v[38:39], v[114:115]
	v_pk_fma_f32 v[76:77], v[76:77], v[38:39], v[116:117]
	v_pk_fma_f32 v[74:75], v[74:75], v[40:41], v[118:119]
	v_pk_fma_f32 v[78:79], v[78:79], v[40:41], v[120:121]
	v_pk_mul_f32 v[122:123], v[72:73], v[42:43]
	v_pk_mul_f32 v[124:125], v[76:77], v[42:43]
	v_pk_fma_f32 v[122:123], v[74:75], v[44:45], v[122:123]
	v_pk_fma_f32 v[124:125], v[78:79], v[44:45], v[124:125]
	v_add_f32_e32 v126, v122, v123
	v_add_f32_e32 v127, v124, v125
	ds_write_b64 v187, v[126:127] offset:32768
	s_waitcnt lgkmcnt(1)
	v_pk_mul_f32 v[106:107], v[72:73], v[84:85]
	v_pk_mul_f32 v[108:109], v[76:77], v[84:85]
	v_pk_fma_f32 v[106:107], v[74:75], v[86:87], v[106:107]
	v_pk_fma_f32 v[108:109], v[78:79], v[86:87], v[108:109]
	v_add_f32_e32 v110, v106, v107
	v_add_f32_e32 v112, v108, v109
	ds_read_b128 v[30:33], v161 offset:12800
	v_add_f32_dpp v110, v110, v110 quad_perm:[1,0,3,2] row_mask:0xf bank_mask:0xf bound_ctrl:1
	v_add_f32_dpp v112, v112, v112 quad_perm:[1,0,3,2] row_mask:0xf bank_mask:0xf bound_ctrl:1
	ds_read_b128 v[34:37], v161 offset:20992
	v_add_f32_dpp v110, v110, v110 quad_perm:[2,3,0,1] row_mask:0xf bank_mask:0xf bound_ctrl:1
	v_add_f32_dpp v112, v112, v112 quad_perm:[2,3,0,1] row_mask:0xf bank_mask:0xf bound_ctrl:1
	ds_read_b128 v[46:49], v161 offset:29184
	v_add_f32_dpp v110, v110, v110 row_half_mirror row_mask:0xf bank_mask:0xf bound_ctrl:1
	v_add_f32_dpp v112, v112, v112 row_half_mirror row_mask:0xf bank_mask:0xf bound_ctrl:1
	ds_read_b64 v[80:81], v82 offset:45568
	v_add_f32_dpp v110, v110, v110 row_ror:8 row_mask:0xf bank_mask:0xf bound_ctrl:1
	v_add_f32_dpp v112, v112, v112 row_ror:8 row_mask:0xf bank_mask:0xf bound_ctrl:1
	ds_read_b128 v[38:41], v161 offset:4608
	ds_read_b128 v[42:45], v161 offset:37376
	v_pk_mul_f32 v[114:115], v[88:89], v[110:111] op_sel_hi:[1,0]
	v_pk_mul_f32 v[116:117], v[88:89], v[112:113] op_sel_hi:[1,0]
	v_pk_mul_f32 v[118:119], v[90:91], v[110:111] op_sel_hi:[1,0]
	v_pk_mul_f32 v[120:121], v[90:91], v[112:113] op_sel_hi:[1,0]
	v_pk_fma_f32 v[114:115], v[100:101], v[104:105], v[114:115] op_sel_hi:[1,0,1]
	v_pk_fma_f32 v[116:117], v[100:101], v[104:105], v[116:117] op_sel:[0,1,0]
	v_pk_fma_f32 v[118:119], v[102:103], v[104:105], v[118:119] op_sel_hi:[1,0,1]
	v_pk_fma_f32 v[120:121], v[102:103], v[104:105], v[120:121] op_sel:[0,1,0]
	v_pk_fma_f32 v[72:73], v[72:73], v[92:93], v[114:115]
	v_pk_fma_f32 v[76:77], v[76:77], v[92:93], v[116:117]
	v_pk_fma_f32 v[74:75], v[74:75], v[94:95], v[118:119]
	v_pk_fma_f32 v[78:79], v[78:79], v[94:95], v[120:121]
	v_pk_mul_f32 v[122:123], v[72:73], v[96:97]
	v_pk_mul_f32 v[124:125], v[76:77], v[96:97]
	v_pk_fma_f32 v[122:123], v[74:75], v[98:99], v[122:123]
	v_pk_fma_f32 v[124:125], v[78:79], v[98:99], v[124:125]
	v_add_f32_e32 v126, v122, v123
	v_add_f32_e32 v127, v124, v125
	ds_write_b64 v187, v[126:127] offset:34816
	s_waitcnt lgkmcnt(1)
	v_pk_mul_f32 v[106:107], v[72:73], v[30:31]
	v_pk_mul_f32 v[108:109], v[76:77], v[30:31]
	v_pk_fma_f32 v[106:107], v[74:75], v[32:33], v[106:107]
	v_pk_fma_f32 v[108:109], v[78:79], v[32:33], v[108:109]
	v_add_f32_e32 v110, v106, v107
	v_add_f32_e32 v112, v108, v109
	ds_read_b128 v[84:87], v161 offset:13056
	v_add_f32_dpp v110, v110, v110 quad_perm:[1,0,3,2] row_mask:0xf bank_mask:0xf bound_ctrl:1
	v_add_f32_dpp v112, v112, v112 quad_perm:[1,0,3,2] row_mask:0xf bank_mask:0xf bound_ctrl:1
	ds_read_b128 v[88:91], v161 offset:21248
	v_add_f32_dpp v110, v110, v110 quad_perm:[2,3,0,1] row_mask:0xf bank_mask:0xf bound_ctrl:1
	v_add_f32_dpp v112, v112, v112 quad_perm:[2,3,0,1] row_mask:0xf bank_mask:0xf bound_ctrl:1
	ds_read_b128 v[100:103], v161 offset:29440
	v_add_f32_dpp v110, v110, v110 row_half_mirror row_mask:0xf bank_mask:0xf bound_ctrl:1
	v_add_f32_dpp v112, v112, v112 row_half_mirror row_mask:0xf bank_mask:0xf bound_ctrl:1
	ds_read_b64 v[104:105], v82 offset:45824
	v_add_f32_dpp v110, v110, v110 row_ror:8 row_mask:0xf bank_mask:0xf bound_ctrl:1
	v_add_f32_dpp v112, v112, v112 row_ror:8 row_mask:0xf bank_mask:0xf bound_ctrl:1
	ds_read_b128 v[92:95], v161 offset:4864
	ds_read_b128 v[96:99], v161 offset:37632
	v_pk_mul_f32 v[114:115], v[34:35], v[110:111] op_sel_hi:[1,0]
	v_pk_mul_f32 v[116:117], v[34:35], v[112:113] op_sel_hi:[1,0]
	v_pk_mul_f32 v[118:119], v[36:37], v[110:111] op_sel_hi:[1,0]
	v_pk_mul_f32 v[120:121], v[36:37], v[112:113] op_sel_hi:[1,0]
	v_pk_fma_f32 v[114:115], v[46:47], v[80:81], v[114:115] op_sel_hi:[1,0,1]
	v_pk_fma_f32 v[116:117], v[46:47], v[80:81], v[116:117] op_sel:[0,1,0]
	v_pk_fma_f32 v[118:119], v[48:49], v[80:81], v[118:119] op_sel_hi:[1,0,1]
	v_pk_fma_f32 v[120:121], v[48:49], v[80:81], v[120:121] op_sel:[0,1,0]
	v_pk_fma_f32 v[72:73], v[72:73], v[38:39], v[114:115]
	v_pk_fma_f32 v[76:77], v[76:77], v[38:39], v[116:117]
	v_pk_fma_f32 v[74:75], v[74:75], v[40:41], v[118:119]
	v_pk_fma_f32 v[78:79], v[78:79], v[40:41], v[120:121]
	v_pk_mul_f32 v[122:123], v[72:73], v[42:43]
	v_pk_mul_f32 v[124:125], v[76:77], v[42:43]
	v_pk_fma_f32 v[122:123], v[74:75], v[44:45], v[122:123]
	v_pk_fma_f32 v[124:125], v[78:79], v[44:45], v[124:125]
	v_add_f32_e32 v126, v122, v123
	v_add_f32_e32 v127, v124, v125
	ds_write_b64 v187, v[126:127] offset:36864
	s_waitcnt lgkmcnt(1)
	v_pk_mul_f32 v[106:107], v[72:73], v[84:85]
	v_pk_mul_f32 v[108:109], v[76:77], v[84:85]
	v_pk_fma_f32 v[106:107], v[74:75], v[86:87], v[106:107]
	v_pk_fma_f32 v[108:109], v[78:79], v[86:87], v[108:109]
	v_add_f32_e32 v110, v106, v107
	v_add_f32_e32 v112, v108, v109
	ds_read_b128 v[30:33], v161 offset:13312
	v_add_f32_dpp v110, v110, v110 quad_perm:[1,0,3,2] row_mask:0xf bank_mask:0xf bound_ctrl:1
	v_add_f32_dpp v112, v112, v112 quad_perm:[1,0,3,2] row_mask:0xf bank_mask:0xf bound_ctrl:1
	ds_read_b128 v[34:37], v161 offset:21504
	v_add_f32_dpp v110, v110, v110 quad_perm:[2,3,0,1] row_mask:0xf bank_mask:0xf bound_ctrl:1
	v_add_f32_dpp v112, v112, v112 quad_perm:[2,3,0,1] row_mask:0xf bank_mask:0xf bound_ctrl:1
	ds_read_b128 v[46:49], v161 offset:29696
	v_add_f32_dpp v110, v110, v110 row_half_mirror row_mask:0xf bank_mask:0xf bound_ctrl:1
	v_add_f32_dpp v112, v112, v112 row_half_mirror row_mask:0xf bank_mask:0xf bound_ctrl:1
	ds_read_b64 v[80:81], v82 offset:46080
	v_add_f32_dpp v110, v110, v110 row_ror:8 row_mask:0xf bank_mask:0xf bound_ctrl:1
	v_add_f32_dpp v112, v112, v112 row_ror:8 row_mask:0xf bank_mask:0xf bound_ctrl:1
	ds_read_b128 v[38:41], v161 offset:5120
	ds_read_b128 v[42:45], v161 offset:37888
	v_pk_mul_f32 v[114:115], v[88:89], v[110:111] op_sel_hi:[1,0]
	v_pk_mul_f32 v[116:117], v[88:89], v[112:113] op_sel_hi:[1,0]
	v_pk_mul_f32 v[118:119], v[90:91], v[110:111] op_sel_hi:[1,0]
	v_pk_mul_f32 v[120:121], v[90:91], v[112:113] op_sel_hi:[1,0]
	v_pk_fma_f32 v[114:115], v[100:101], v[104:105], v[114:115] op_sel_hi:[1,0,1]
	v_pk_fma_f32 v[116:117], v[100:101], v[104:105], v[116:117] op_sel:[0,1,0]
	v_pk_fma_f32 v[118:119], v[102:103], v[104:105], v[118:119] op_sel_hi:[1,0,1]
	v_pk_fma_f32 v[120:121], v[102:103], v[104:105], v[120:121] op_sel:[0,1,0]
	v_pk_fma_f32 v[72:73], v[72:73], v[92:93], v[114:115]
	v_pk_fma_f32 v[76:77], v[76:77], v[92:93], v[116:117]
	v_pk_fma_f32 v[74:75], v[74:75], v[94:95], v[118:119]
	v_pk_fma_f32 v[78:79], v[78:79], v[94:95], v[120:121]
	v_pk_mul_f32 v[122:123], v[72:73], v[96:97]
	v_pk_mul_f32 v[124:125], v[76:77], v[96:97]
	v_pk_fma_f32 v[122:123], v[74:75], v[98:99], v[122:123]
	v_pk_fma_f32 v[124:125], v[78:79], v[98:99], v[124:125]
	v_add_f32_e32 v126, v122, v123
	v_add_f32_e32 v127, v124, v125
	ds_write_b64 v187, v[126:127] offset:38912
	s_waitcnt lgkmcnt(1)
	v_pk_mul_f32 v[106:107], v[72:73], v[30:31]
	v_pk_mul_f32 v[108:109], v[76:77], v[30:31]
	v_pk_fma_f32 v[106:107], v[74:75], v[32:33], v[106:107]
	v_pk_fma_f32 v[108:109], v[78:79], v[32:33], v[108:109]
	v_add_f32_e32 v110, v106, v107
	v_add_f32_e32 v112, v108, v109
	ds_read_b128 v[84:87], v161 offset:13568
	v_add_f32_dpp v110, v110, v110 quad_perm:[1,0,3,2] row_mask:0xf bank_mask:0xf bound_ctrl:1
	v_add_f32_dpp v112, v112, v112 quad_perm:[1,0,3,2] row_mask:0xf bank_mask:0xf bound_ctrl:1
	ds_read_b128 v[88:91], v161 offset:21760
	v_add_f32_dpp v110, v110, v110 quad_perm:[2,3,0,1] row_mask:0xf bank_mask:0xf bound_ctrl:1
	v_add_f32_dpp v112, v112, v112 quad_perm:[2,3,0,1] row_mask:0xf bank_mask:0xf bound_ctrl:1
	ds_read_b128 v[100:103], v161 offset:29952
	v_add_f32_dpp v110, v110, v110 row_half_mirror row_mask:0xf bank_mask:0xf bound_ctrl:1
	v_add_f32_dpp v112, v112, v112 row_half_mirror row_mask:0xf bank_mask:0xf bound_ctrl:1
	ds_read_b64 v[104:105], v82 offset:46336
	v_add_f32_dpp v110, v110, v110 row_ror:8 row_mask:0xf bank_mask:0xf bound_ctrl:1
	v_add_f32_dpp v112, v112, v112 row_ror:8 row_mask:0xf bank_mask:0xf bound_ctrl:1
	ds_read_b128 v[92:95], v161 offset:5376
	ds_read_b128 v[96:99], v161 offset:38144
	v_pk_mul_f32 v[114:115], v[34:35], v[110:111] op_sel_hi:[1,0]
	v_pk_mul_f32 v[116:117], v[34:35], v[112:113] op_sel_hi:[1,0]
	v_pk_mul_f32 v[118:119], v[36:37], v[110:111] op_sel_hi:[1,0]
	v_pk_mul_f32 v[120:121], v[36:37], v[112:113] op_sel_hi:[1,0]
	v_pk_fma_f32 v[114:115], v[46:47], v[80:81], v[114:115] op_sel_hi:[1,0,1]
	v_pk_fma_f32 v[116:117], v[46:47], v[80:81], v[116:117] op_sel:[0,1,0]
	v_pk_fma_f32 v[118:119], v[48:49], v[80:81], v[118:119] op_sel_hi:[1,0,1]
	v_pk_fma_f32 v[120:121], v[48:49], v[80:81], v[120:121] op_sel:[0,1,0]
	v_pk_fma_f32 v[72:73], v[72:73], v[38:39], v[114:115]
	v_pk_fma_f32 v[76:77], v[76:77], v[38:39], v[116:117]
	v_pk_fma_f32 v[74:75], v[74:75], v[40:41], v[118:119]
	v_pk_fma_f32 v[78:79], v[78:79], v[40:41], v[120:121]
	v_pk_mul_f32 v[122:123], v[72:73], v[42:43]
	v_pk_mul_f32 v[124:125], v[76:77], v[42:43]
	v_pk_fma_f32 v[122:123], v[74:75], v[44:45], v[122:123]
	v_pk_fma_f32 v[124:125], v[78:79], v[44:45], v[124:125]
	v_add_f32_e32 v126, v122, v123
	v_add_f32_e32 v127, v124, v125
	ds_write_b64 v187, v[126:127] offset:40960
	s_waitcnt lgkmcnt(1)
	v_pk_mul_f32 v[106:107], v[72:73], v[84:85]
	v_pk_mul_f32 v[108:109], v[76:77], v[84:85]
	v_pk_fma_f32 v[106:107], v[74:75], v[86:87], v[106:107]
	v_pk_fma_f32 v[108:109], v[78:79], v[86:87], v[108:109]
	v_add_f32_e32 v110, v106, v107
	v_add_f32_e32 v112, v108, v109
	ds_read_b128 v[30:33], v161 offset:13824
	v_add_f32_dpp v110, v110, v110 quad_perm:[1,0,3,2] row_mask:0xf bank_mask:0xf bound_ctrl:1
	v_add_f32_dpp v112, v112, v112 quad_perm:[1,0,3,2] row_mask:0xf bank_mask:0xf bound_ctrl:1
	ds_read_b128 v[34:37], v161 offset:22016
	v_add_f32_dpp v110, v110, v110 quad_perm:[2,3,0,1] row_mask:0xf bank_mask:0xf bound_ctrl:1
	v_add_f32_dpp v112, v112, v112 quad_perm:[2,3,0,1] row_mask:0xf bank_mask:0xf bound_ctrl:1
	ds_read_b128 v[46:49], v161 offset:30208
	v_add_f32_dpp v110, v110, v110 row_half_mirror row_mask:0xf bank_mask:0xf bound_ctrl:1
	v_add_f32_dpp v112, v112, v112 row_half_mirror row_mask:0xf bank_mask:0xf bound_ctrl:1
	ds_read_b64 v[80:81], v82 offset:46592
	v_add_f32_dpp v110, v110, v110 row_ror:8 row_mask:0xf bank_mask:0xf bound_ctrl:1
	v_add_f32_dpp v112, v112, v112 row_ror:8 row_mask:0xf bank_mask:0xf bound_ctrl:1
	ds_read_b128 v[38:41], v161 offset:5632
	ds_read_b128 v[42:45], v161 offset:38400
	v_pk_mul_f32 v[114:115], v[88:89], v[110:111] op_sel_hi:[1,0]
	v_pk_mul_f32 v[116:117], v[88:89], v[112:113] op_sel_hi:[1,0]
	v_pk_mul_f32 v[118:119], v[90:91], v[110:111] op_sel_hi:[1,0]
	v_pk_mul_f32 v[120:121], v[90:91], v[112:113] op_sel_hi:[1,0]
	v_pk_fma_f32 v[114:115], v[100:101], v[104:105], v[114:115] op_sel_hi:[1,0,1]
	v_pk_fma_f32 v[116:117], v[100:101], v[104:105], v[116:117] op_sel:[0,1,0]
	v_pk_fma_f32 v[118:119], v[102:103], v[104:105], v[118:119] op_sel_hi:[1,0,1]
	v_pk_fma_f32 v[120:121], v[102:103], v[104:105], v[120:121] op_sel:[0,1,0]
	v_pk_fma_f32 v[72:73], v[72:73], v[92:93], v[114:115]
	v_pk_fma_f32 v[76:77], v[76:77], v[92:93], v[116:117]
	v_pk_fma_f32 v[74:75], v[74:75], v[94:95], v[118:119]
	v_pk_fma_f32 v[78:79], v[78:79], v[94:95], v[120:121]
	v_pk_mul_f32 v[122:123], v[72:73], v[96:97]
	v_pk_mul_f32 v[124:125], v[76:77], v[96:97]
	v_pk_fma_f32 v[122:123], v[74:75], v[98:99], v[122:123]
	v_pk_fma_f32 v[124:125], v[78:79], v[98:99], v[124:125]
	v_add_f32_e32 v126, v122, v123
	v_add_f32_e32 v127, v124, v125
	ds_write_b64 v187, v[126:127] offset:43008
	s_waitcnt lgkmcnt(1)
	v_pk_mul_f32 v[106:107], v[72:73], v[30:31]
	v_pk_mul_f32 v[108:109], v[76:77], v[30:31]
	v_pk_fma_f32 v[106:107], v[74:75], v[32:33], v[106:107]
	v_pk_fma_f32 v[108:109], v[78:79], v[32:33], v[108:109]
	v_add_f32_e32 v110, v106, v107
	v_add_f32_e32 v112, v108, v109
	ds_read_b128 v[84:87], v161 offset:14080
	v_add_f32_dpp v110, v110, v110 quad_perm:[1,0,3,2] row_mask:0xf bank_mask:0xf bound_ctrl:1
	v_add_f32_dpp v112, v112, v112 quad_perm:[1,0,3,2] row_mask:0xf bank_mask:0xf bound_ctrl:1
	ds_read_b128 v[88:91], v161 offset:22272
	v_add_f32_dpp v110, v110, v110 quad_perm:[2,3,0,1] row_mask:0xf bank_mask:0xf bound_ctrl:1
	v_add_f32_dpp v112, v112, v112 quad_perm:[2,3,0,1] row_mask:0xf bank_mask:0xf bound_ctrl:1
	ds_read_b128 v[100:103], v161 offset:30464
	v_add_f32_dpp v110, v110, v110 row_half_mirror row_mask:0xf bank_mask:0xf bound_ctrl:1
	v_add_f32_dpp v112, v112, v112 row_half_mirror row_mask:0xf bank_mask:0xf bound_ctrl:1
	ds_read_b64 v[104:105], v82 offset:46848
	v_add_f32_dpp v110, v110, v110 row_ror:8 row_mask:0xf bank_mask:0xf bound_ctrl:1
	v_add_f32_dpp v112, v112, v112 row_ror:8 row_mask:0xf bank_mask:0xf bound_ctrl:1
	ds_read_b128 v[92:95], v161 offset:5888
	ds_read_b128 v[96:99], v161 offset:38656
	v_pk_mul_f32 v[114:115], v[34:35], v[110:111] op_sel_hi:[1,0]
	v_pk_mul_f32 v[116:117], v[34:35], v[112:113] op_sel_hi:[1,0]
	v_pk_mul_f32 v[118:119], v[36:37], v[110:111] op_sel_hi:[1,0]
	v_pk_mul_f32 v[120:121], v[36:37], v[112:113] op_sel_hi:[1,0]
	v_pk_fma_f32 v[114:115], v[46:47], v[80:81], v[114:115] op_sel_hi:[1,0,1]
	v_pk_fma_f32 v[116:117], v[46:47], v[80:81], v[116:117] op_sel:[0,1,0]
	v_pk_fma_f32 v[118:119], v[48:49], v[80:81], v[118:119] op_sel_hi:[1,0,1]
	v_pk_fma_f32 v[120:121], v[48:49], v[80:81], v[120:121] op_sel:[0,1,0]
	v_pk_fma_f32 v[72:73], v[72:73], v[38:39], v[114:115]
	v_pk_fma_f32 v[76:77], v[76:77], v[38:39], v[116:117]
	v_pk_fma_f32 v[74:75], v[74:75], v[40:41], v[118:119]
	v_pk_fma_f32 v[78:79], v[78:79], v[40:41], v[120:121]
	v_pk_mul_f32 v[122:123], v[72:73], v[42:43]
	v_pk_mul_f32 v[124:125], v[76:77], v[42:43]
	v_pk_fma_f32 v[122:123], v[74:75], v[44:45], v[122:123]
	v_pk_fma_f32 v[124:125], v[78:79], v[44:45], v[124:125]
	v_add_f32_e32 v126, v122, v123
	v_add_f32_e32 v127, v124, v125
	ds_write_b64 v187, v[126:127] offset:45056
	s_waitcnt lgkmcnt(1)
	v_pk_mul_f32 v[106:107], v[72:73], v[84:85]
	v_pk_mul_f32 v[108:109], v[76:77], v[84:85]
	v_pk_fma_f32 v[106:107], v[74:75], v[86:87], v[106:107]
	v_pk_fma_f32 v[108:109], v[78:79], v[86:87], v[108:109]
	v_add_f32_e32 v110, v106, v107
	v_add_f32_e32 v112, v108, v109
	ds_read_b128 v[30:33], v161 offset:14336
	v_add_f32_dpp v110, v110, v110 quad_perm:[1,0,3,2] row_mask:0xf bank_mask:0xf bound_ctrl:1
	v_add_f32_dpp v112, v112, v112 quad_perm:[1,0,3,2] row_mask:0xf bank_mask:0xf bound_ctrl:1
	ds_read_b128 v[34:37], v161 offset:22528
	v_add_f32_dpp v110, v110, v110 quad_perm:[2,3,0,1] row_mask:0xf bank_mask:0xf bound_ctrl:1
	v_add_f32_dpp v112, v112, v112 quad_perm:[2,3,0,1] row_mask:0xf bank_mask:0xf bound_ctrl:1
	ds_read_b128 v[46:49], v161 offset:30720
	v_add_f32_dpp v110, v110, v110 row_half_mirror row_mask:0xf bank_mask:0xf bound_ctrl:1
	v_add_f32_dpp v112, v112, v112 row_half_mirror row_mask:0xf bank_mask:0xf bound_ctrl:1
	ds_read_b64 v[80:81], v82 offset:47104
	v_add_f32_dpp v110, v110, v110 row_ror:8 row_mask:0xf bank_mask:0xf bound_ctrl:1
	v_add_f32_dpp v112, v112, v112 row_ror:8 row_mask:0xf bank_mask:0xf bound_ctrl:1
	ds_read_b128 v[38:41], v161 offset:6144
	ds_read_b128 v[42:45], v161 offset:38912
	v_pk_mul_f32 v[114:115], v[88:89], v[110:111] op_sel_hi:[1,0]
	v_pk_mul_f32 v[116:117], v[88:89], v[112:113] op_sel_hi:[1,0]
	v_pk_mul_f32 v[118:119], v[90:91], v[110:111] op_sel_hi:[1,0]
	v_pk_mul_f32 v[120:121], v[90:91], v[112:113] op_sel_hi:[1,0]
	v_pk_fma_f32 v[114:115], v[100:101], v[104:105], v[114:115] op_sel_hi:[1,0,1]
	v_pk_fma_f32 v[116:117], v[100:101], v[104:105], v[116:117] op_sel:[0,1,0]
	v_pk_fma_f32 v[118:119], v[102:103], v[104:105], v[118:119] op_sel_hi:[1,0,1]
	v_pk_fma_f32 v[120:121], v[102:103], v[104:105], v[120:121] op_sel:[0,1,0]
	v_pk_fma_f32 v[72:73], v[72:73], v[92:93], v[114:115]
	v_pk_fma_f32 v[76:77], v[76:77], v[92:93], v[116:117]
	v_pk_fma_f32 v[74:75], v[74:75], v[94:95], v[118:119]
	v_pk_fma_f32 v[78:79], v[78:79], v[94:95], v[120:121]
	v_pk_mul_f32 v[122:123], v[72:73], v[96:97]
	v_pk_mul_f32 v[124:125], v[76:77], v[96:97]
	v_pk_fma_f32 v[122:123], v[74:75], v[98:99], v[122:123]
	v_pk_fma_f32 v[124:125], v[78:79], v[98:99], v[124:125]
	v_add_f32_e32 v126, v122, v123
	v_add_f32_e32 v127, v124, v125
	ds_write_b64 v187, v[126:127] offset:47104
	s_waitcnt lgkmcnt(1)
	v_pk_mul_f32 v[106:107], v[72:73], v[30:31]
	v_pk_mul_f32 v[108:109], v[76:77], v[30:31]
	v_pk_fma_f32 v[106:107], v[74:75], v[32:33], v[106:107]
	v_pk_fma_f32 v[108:109], v[78:79], v[32:33], v[108:109]
	v_add_f32_e32 v110, v106, v107
	v_add_f32_e32 v112, v108, v109
	ds_read_b128 v[84:87], v161 offset:14592
	v_add_f32_dpp v110, v110, v110 quad_perm:[1,0,3,2] row_mask:0xf bank_mask:0xf bound_ctrl:1
	v_add_f32_dpp v112, v112, v112 quad_perm:[1,0,3,2] row_mask:0xf bank_mask:0xf bound_ctrl:1
	ds_read_b128 v[88:91], v161 offset:22784
	v_add_f32_dpp v110, v110, v110 quad_perm:[2,3,0,1] row_mask:0xf bank_mask:0xf bound_ctrl:1
	v_add_f32_dpp v112, v112, v112 quad_perm:[2,3,0,1] row_mask:0xf bank_mask:0xf bound_ctrl:1
	ds_read_b128 v[100:103], v161 offset:30976
	v_add_f32_dpp v110, v110, v110 row_half_mirror row_mask:0xf bank_mask:0xf bound_ctrl:1
	v_add_f32_dpp v112, v112, v112 row_half_mirror row_mask:0xf bank_mask:0xf bound_ctrl:1
	ds_read_b64 v[104:105], v82 offset:47360
	v_add_f32_dpp v110, v110, v110 row_ror:8 row_mask:0xf bank_mask:0xf bound_ctrl:1
	v_add_f32_dpp v112, v112, v112 row_ror:8 row_mask:0xf bank_mask:0xf bound_ctrl:1
	ds_read_b128 v[92:95], v161 offset:6400
	ds_read_b128 v[96:99], v161 offset:39168
	v_pk_mul_f32 v[114:115], v[34:35], v[110:111] op_sel_hi:[1,0]
	v_pk_mul_f32 v[116:117], v[34:35], v[112:113] op_sel_hi:[1,0]
	v_pk_mul_f32 v[118:119], v[36:37], v[110:111] op_sel_hi:[1,0]
	v_pk_mul_f32 v[120:121], v[36:37], v[112:113] op_sel_hi:[1,0]
	v_pk_fma_f32 v[114:115], v[46:47], v[80:81], v[114:115] op_sel_hi:[1,0,1]
	v_pk_fma_f32 v[116:117], v[46:47], v[80:81], v[116:117] op_sel:[0,1,0]
	v_pk_fma_f32 v[118:119], v[48:49], v[80:81], v[118:119] op_sel_hi:[1,0,1]
	v_pk_fma_f32 v[120:121], v[48:49], v[80:81], v[120:121] op_sel:[0,1,0]
	v_pk_fma_f32 v[72:73], v[72:73], v[38:39], v[114:115]
	v_pk_fma_f32 v[76:77], v[76:77], v[38:39], v[116:117]
	v_pk_fma_f32 v[74:75], v[74:75], v[40:41], v[118:119]
	v_pk_fma_f32 v[78:79], v[78:79], v[40:41], v[120:121]
	v_pk_mul_f32 v[122:123], v[72:73], v[42:43]
	v_pk_mul_f32 v[124:125], v[76:77], v[42:43]
	v_pk_fma_f32 v[122:123], v[74:75], v[44:45], v[122:123]
	v_pk_fma_f32 v[124:125], v[78:79], v[44:45], v[124:125]
	v_add_f32_e32 v126, v122, v123
	v_add_f32_e32 v127, v124, v125
	ds_write_b64 v187, v[126:127] offset:49152
	s_waitcnt lgkmcnt(1)
	v_pk_mul_f32 v[106:107], v[72:73], v[84:85]
	v_pk_mul_f32 v[108:109], v[76:77], v[84:85]
	v_pk_fma_f32 v[106:107], v[74:75], v[86:87], v[106:107]
	v_pk_fma_f32 v[108:109], v[78:79], v[86:87], v[108:109]
	v_add_f32_e32 v110, v106, v107
	v_add_f32_e32 v112, v108, v109
	ds_read_b128 v[30:33], v161 offset:14848
	v_add_f32_dpp v110, v110, v110 quad_perm:[1,0,3,2] row_mask:0xf bank_mask:0xf bound_ctrl:1
	v_add_f32_dpp v112, v112, v112 quad_perm:[1,0,3,2] row_mask:0xf bank_mask:0xf bound_ctrl:1
	ds_read_b128 v[34:37], v161 offset:23040
	v_add_f32_dpp v110, v110, v110 quad_perm:[2,3,0,1] row_mask:0xf bank_mask:0xf bound_ctrl:1
	v_add_f32_dpp v112, v112, v112 quad_perm:[2,3,0,1] row_mask:0xf bank_mask:0xf bound_ctrl:1
	ds_read_b128 v[46:49], v161 offset:31232
	v_add_f32_dpp v110, v110, v110 row_half_mirror row_mask:0xf bank_mask:0xf bound_ctrl:1
	v_add_f32_dpp v112, v112, v112 row_half_mirror row_mask:0xf bank_mask:0xf bound_ctrl:1
	ds_read_b64 v[80:81], v82 offset:47616
	v_add_f32_dpp v110, v110, v110 row_ror:8 row_mask:0xf bank_mask:0xf bound_ctrl:1
	v_add_f32_dpp v112, v112, v112 row_ror:8 row_mask:0xf bank_mask:0xf bound_ctrl:1
	ds_read_b128 v[38:41], v161 offset:6656
	ds_read_b128 v[42:45], v161 offset:39424
	v_pk_mul_f32 v[114:115], v[88:89], v[110:111] op_sel_hi:[1,0]
	v_pk_mul_f32 v[116:117], v[88:89], v[112:113] op_sel_hi:[1,0]
	v_pk_mul_f32 v[118:119], v[90:91], v[110:111] op_sel_hi:[1,0]
	v_pk_mul_f32 v[120:121], v[90:91], v[112:113] op_sel_hi:[1,0]
	v_pk_fma_f32 v[114:115], v[100:101], v[104:105], v[114:115] op_sel_hi:[1,0,1]
	v_pk_fma_f32 v[116:117], v[100:101], v[104:105], v[116:117] op_sel:[0,1,0]
	v_pk_fma_f32 v[118:119], v[102:103], v[104:105], v[118:119] op_sel_hi:[1,0,1]
	v_pk_fma_f32 v[120:121], v[102:103], v[104:105], v[120:121] op_sel:[0,1,0]
	v_pk_fma_f32 v[72:73], v[72:73], v[92:93], v[114:115]
	v_pk_fma_f32 v[76:77], v[76:77], v[92:93], v[116:117]
	v_pk_fma_f32 v[74:75], v[74:75], v[94:95], v[118:119]
	v_pk_fma_f32 v[78:79], v[78:79], v[94:95], v[120:121]
	v_pk_mul_f32 v[122:123], v[72:73], v[96:97]
	v_pk_mul_f32 v[124:125], v[76:77], v[96:97]
	v_pk_fma_f32 v[122:123], v[74:75], v[98:99], v[122:123]
	v_pk_fma_f32 v[124:125], v[78:79], v[98:99], v[124:125]
	v_add_f32_e32 v126, v122, v123
	v_add_f32_e32 v127, v124, v125
	ds_write_b64 v187, v[126:127] offset:51200
	s_waitcnt lgkmcnt(1)
	v_pk_mul_f32 v[106:107], v[72:73], v[30:31]
	v_pk_mul_f32 v[108:109], v[76:77], v[30:31]
	v_pk_fma_f32 v[106:107], v[74:75], v[32:33], v[106:107]
	v_pk_fma_f32 v[108:109], v[78:79], v[32:33], v[108:109]
	v_add_f32_e32 v110, v106, v107
	v_add_f32_e32 v112, v108, v109
	ds_read_b128 v[84:87], v161 offset:15104
	v_add_f32_dpp v110, v110, v110 quad_perm:[1,0,3,2] row_mask:0xf bank_mask:0xf bound_ctrl:1
	v_add_f32_dpp v112, v112, v112 quad_perm:[1,0,3,2] row_mask:0xf bank_mask:0xf bound_ctrl:1
	ds_read_b128 v[88:91], v161 offset:23296
	v_add_f32_dpp v110, v110, v110 quad_perm:[2,3,0,1] row_mask:0xf bank_mask:0xf bound_ctrl:1
	v_add_f32_dpp v112, v112, v112 quad_perm:[2,3,0,1] row_mask:0xf bank_mask:0xf bound_ctrl:1
	ds_read_b128 v[100:103], v161 offset:31488
	v_add_f32_dpp v110, v110, v110 row_half_mirror row_mask:0xf bank_mask:0xf bound_ctrl:1
	v_add_f32_dpp v112, v112, v112 row_half_mirror row_mask:0xf bank_mask:0xf bound_ctrl:1
	ds_read_b64 v[104:105], v82 offset:47872
	v_add_f32_dpp v110, v110, v110 row_ror:8 row_mask:0xf bank_mask:0xf bound_ctrl:1
	v_add_f32_dpp v112, v112, v112 row_ror:8 row_mask:0xf bank_mask:0xf bound_ctrl:1
	ds_read_b128 v[92:95], v161 offset:6912
	ds_read_b128 v[96:99], v161 offset:39680
	v_pk_mul_f32 v[114:115], v[34:35], v[110:111] op_sel_hi:[1,0]
	v_pk_mul_f32 v[116:117], v[34:35], v[112:113] op_sel_hi:[1,0]
	v_pk_mul_f32 v[118:119], v[36:37], v[110:111] op_sel_hi:[1,0]
	v_pk_mul_f32 v[120:121], v[36:37], v[112:113] op_sel_hi:[1,0]
	v_pk_fma_f32 v[114:115], v[46:47], v[80:81], v[114:115] op_sel_hi:[1,0,1]
	v_pk_fma_f32 v[116:117], v[46:47], v[80:81], v[116:117] op_sel:[0,1,0]
	v_pk_fma_f32 v[118:119], v[48:49], v[80:81], v[118:119] op_sel_hi:[1,0,1]
	v_pk_fma_f32 v[120:121], v[48:49], v[80:81], v[120:121] op_sel:[0,1,0]
	v_pk_fma_f32 v[72:73], v[72:73], v[38:39], v[114:115]
	v_pk_fma_f32 v[76:77], v[76:77], v[38:39], v[116:117]
	v_pk_fma_f32 v[74:75], v[74:75], v[40:41], v[118:119]
	v_pk_fma_f32 v[78:79], v[78:79], v[40:41], v[120:121]
	v_pk_mul_f32 v[122:123], v[72:73], v[42:43]
	v_pk_mul_f32 v[124:125], v[76:77], v[42:43]
	v_pk_fma_f32 v[122:123], v[74:75], v[44:45], v[122:123]
	v_pk_fma_f32 v[124:125], v[78:79], v[44:45], v[124:125]
	v_add_f32_e32 v126, v122, v123
	v_add_f32_e32 v127, v124, v125
	ds_write_b64 v187, v[126:127] offset:53248
	s_waitcnt lgkmcnt(1)
	v_pk_mul_f32 v[106:107], v[72:73], v[84:85]
	v_pk_mul_f32 v[108:109], v[76:77], v[84:85]
	v_pk_fma_f32 v[106:107], v[74:75], v[86:87], v[106:107]
	v_pk_fma_f32 v[108:109], v[78:79], v[86:87], v[108:109]
	v_add_f32_e32 v110, v106, v107
	v_add_f32_e32 v112, v108, v109
	ds_read_b128 v[30:33], v161 offset:15360
	v_add_f32_dpp v110, v110, v110 quad_perm:[1,0,3,2] row_mask:0xf bank_mask:0xf bound_ctrl:1
	v_add_f32_dpp v112, v112, v112 quad_perm:[1,0,3,2] row_mask:0xf bank_mask:0xf bound_ctrl:1
	ds_read_b128 v[34:37], v161 offset:23552
	v_add_f32_dpp v110, v110, v110 quad_perm:[2,3,0,1] row_mask:0xf bank_mask:0xf bound_ctrl:1
	v_add_f32_dpp v112, v112, v112 quad_perm:[2,3,0,1] row_mask:0xf bank_mask:0xf bound_ctrl:1
	ds_read_b128 v[46:49], v161 offset:31744
	v_add_f32_dpp v110, v110, v110 row_half_mirror row_mask:0xf bank_mask:0xf bound_ctrl:1
	v_add_f32_dpp v112, v112, v112 row_half_mirror row_mask:0xf bank_mask:0xf bound_ctrl:1
	ds_read_b64 v[80:81], v82 offset:48128
	v_add_f32_dpp v110, v110, v110 row_ror:8 row_mask:0xf bank_mask:0xf bound_ctrl:1
	v_add_f32_dpp v112, v112, v112 row_ror:8 row_mask:0xf bank_mask:0xf bound_ctrl:1
	ds_read_b128 v[38:41], v161 offset:7168
	ds_read_b128 v[42:45], v161 offset:39936
	v_pk_mul_f32 v[114:115], v[88:89], v[110:111] op_sel_hi:[1,0]
	v_pk_mul_f32 v[116:117], v[88:89], v[112:113] op_sel_hi:[1,0]
	v_pk_mul_f32 v[118:119], v[90:91], v[110:111] op_sel_hi:[1,0]
	v_pk_mul_f32 v[120:121], v[90:91], v[112:113] op_sel_hi:[1,0]
	v_pk_fma_f32 v[114:115], v[100:101], v[104:105], v[114:115] op_sel_hi:[1,0,1]
	v_pk_fma_f32 v[116:117], v[100:101], v[104:105], v[116:117] op_sel:[0,1,0]
	v_pk_fma_f32 v[118:119], v[102:103], v[104:105], v[118:119] op_sel_hi:[1,0,1]
	v_pk_fma_f32 v[120:121], v[102:103], v[104:105], v[120:121] op_sel:[0,1,0]
	v_pk_fma_f32 v[72:73], v[72:73], v[92:93], v[114:115]
	v_pk_fma_f32 v[76:77], v[76:77], v[92:93], v[116:117]
	v_pk_fma_f32 v[74:75], v[74:75], v[94:95], v[118:119]
	v_pk_fma_f32 v[78:79], v[78:79], v[94:95], v[120:121]
	v_pk_mul_f32 v[122:123], v[72:73], v[96:97]
	v_pk_mul_f32 v[124:125], v[76:77], v[96:97]
	v_pk_fma_f32 v[122:123], v[74:75], v[98:99], v[122:123]
	v_pk_fma_f32 v[124:125], v[78:79], v[98:99], v[124:125]
	v_add_f32_e32 v126, v122, v123
	v_add_f32_e32 v127, v124, v125
	ds_write_b64 v187, v[126:127] offset:55296
	s_waitcnt lgkmcnt(1)
	v_pk_mul_f32 v[106:107], v[72:73], v[30:31]
	v_pk_mul_f32 v[108:109], v[76:77], v[30:31]
	v_pk_fma_f32 v[106:107], v[74:75], v[32:33], v[106:107]
	v_pk_fma_f32 v[108:109], v[78:79], v[32:33], v[108:109]
	v_add_f32_e32 v110, v106, v107
	v_add_f32_e32 v112, v108, v109
	ds_read_b128 v[84:87], v161 offset:15616
	v_add_f32_dpp v110, v110, v110 quad_perm:[1,0,3,2] row_mask:0xf bank_mask:0xf bound_ctrl:1
	v_add_f32_dpp v112, v112, v112 quad_perm:[1,0,3,2] row_mask:0xf bank_mask:0xf bound_ctrl:1
	ds_read_b128 v[88:91], v161 offset:23808
	v_add_f32_dpp v110, v110, v110 quad_perm:[2,3,0,1] row_mask:0xf bank_mask:0xf bound_ctrl:1
	v_add_f32_dpp v112, v112, v112 quad_perm:[2,3,0,1] row_mask:0xf bank_mask:0xf bound_ctrl:1
	ds_read_b128 v[100:103], v161 offset:32000
	v_add_f32_dpp v110, v110, v110 row_half_mirror row_mask:0xf bank_mask:0xf bound_ctrl:1
	v_add_f32_dpp v112, v112, v112 row_half_mirror row_mask:0xf bank_mask:0xf bound_ctrl:1
	ds_read_b64 v[104:105], v82 offset:48384
	v_add_f32_dpp v110, v110, v110 row_ror:8 row_mask:0xf bank_mask:0xf bound_ctrl:1
	v_add_f32_dpp v112, v112, v112 row_ror:8 row_mask:0xf bank_mask:0xf bound_ctrl:1
	ds_read_b128 v[92:95], v161 offset:7424
	ds_read_b128 v[96:99], v161 offset:40192
	v_pk_mul_f32 v[114:115], v[34:35], v[110:111] op_sel_hi:[1,0]
	v_pk_mul_f32 v[116:117], v[34:35], v[112:113] op_sel_hi:[1,0]
	v_pk_mul_f32 v[118:119], v[36:37], v[110:111] op_sel_hi:[1,0]
	v_pk_mul_f32 v[120:121], v[36:37], v[112:113] op_sel_hi:[1,0]
	v_pk_fma_f32 v[114:115], v[46:47], v[80:81], v[114:115] op_sel_hi:[1,0,1]
	v_pk_fma_f32 v[116:117], v[46:47], v[80:81], v[116:117] op_sel:[0,1,0]
	v_pk_fma_f32 v[118:119], v[48:49], v[80:81], v[118:119] op_sel_hi:[1,0,1]
	v_pk_fma_f32 v[120:121], v[48:49], v[80:81], v[120:121] op_sel:[0,1,0]
	v_pk_fma_f32 v[72:73], v[72:73], v[38:39], v[114:115]
	v_pk_fma_f32 v[76:77], v[76:77], v[38:39], v[116:117]
	v_pk_fma_f32 v[74:75], v[74:75], v[40:41], v[118:119]
	v_pk_fma_f32 v[78:79], v[78:79], v[40:41], v[120:121]
	v_pk_mul_f32 v[122:123], v[72:73], v[42:43]
	v_pk_mul_f32 v[124:125], v[76:77], v[42:43]
	v_pk_fma_f32 v[122:123], v[74:75], v[44:45], v[122:123]
	v_pk_fma_f32 v[124:125], v[78:79], v[44:45], v[124:125]
	v_add_f32_e32 v126, v122, v123
	v_add_f32_e32 v127, v124, v125
	ds_write_b64 v187, v[126:127] offset:57344
	s_waitcnt lgkmcnt(1)
	v_pk_mul_f32 v[106:107], v[72:73], v[84:85]
	v_pk_mul_f32 v[108:109], v[76:77], v[84:85]
	v_pk_fma_f32 v[106:107], v[74:75], v[86:87], v[106:107]
	v_pk_fma_f32 v[108:109], v[78:79], v[86:87], v[108:109]
	v_add_f32_e32 v110, v106, v107
	v_add_f32_e32 v112, v108, v109
	ds_read_b128 v[30:33], v161 offset:15872
	v_add_f32_dpp v110, v110, v110 quad_perm:[1,0,3,2] row_mask:0xf bank_mask:0xf bound_ctrl:1
	v_add_f32_dpp v112, v112, v112 quad_perm:[1,0,3,2] row_mask:0xf bank_mask:0xf bound_ctrl:1
	ds_read_b128 v[34:37], v161 offset:24064
	v_add_f32_dpp v110, v110, v110 quad_perm:[2,3,0,1] row_mask:0xf bank_mask:0xf bound_ctrl:1
	v_add_f32_dpp v112, v112, v112 quad_perm:[2,3,0,1] row_mask:0xf bank_mask:0xf bound_ctrl:1
	ds_read_b128 v[46:49], v161 offset:32256
	v_add_f32_dpp v110, v110, v110 row_half_mirror row_mask:0xf bank_mask:0xf bound_ctrl:1
	v_add_f32_dpp v112, v112, v112 row_half_mirror row_mask:0xf bank_mask:0xf bound_ctrl:1
	ds_read_b64 v[80:81], v82 offset:48640
	v_add_f32_dpp v110, v110, v110 row_ror:8 row_mask:0xf bank_mask:0xf bound_ctrl:1
	v_add_f32_dpp v112, v112, v112 row_ror:8 row_mask:0xf bank_mask:0xf bound_ctrl:1
	ds_read_b128 v[38:41], v161 offset:7680
	ds_read_b128 v[42:45], v161 offset:40448
	v_pk_mul_f32 v[114:115], v[88:89], v[110:111] op_sel_hi:[1,0]
	v_pk_mul_f32 v[116:117], v[88:89], v[112:113] op_sel_hi:[1,0]
	v_pk_mul_f32 v[118:119], v[90:91], v[110:111] op_sel_hi:[1,0]
	v_pk_mul_f32 v[120:121], v[90:91], v[112:113] op_sel_hi:[1,0]
	v_pk_fma_f32 v[114:115], v[100:101], v[104:105], v[114:115] op_sel_hi:[1,0,1]
	v_pk_fma_f32 v[116:117], v[100:101], v[104:105], v[116:117] op_sel:[0,1,0]
	v_pk_fma_f32 v[118:119], v[102:103], v[104:105], v[118:119] op_sel_hi:[1,0,1]
	v_pk_fma_f32 v[120:121], v[102:103], v[104:105], v[120:121] op_sel:[0,1,0]
	v_pk_fma_f32 v[72:73], v[72:73], v[92:93], v[114:115]
	v_pk_fma_f32 v[76:77], v[76:77], v[92:93], v[116:117]
	v_pk_fma_f32 v[74:75], v[74:75], v[94:95], v[118:119]
	v_pk_fma_f32 v[78:79], v[78:79], v[94:95], v[120:121]
	v_pk_mul_f32 v[122:123], v[72:73], v[96:97]
	v_pk_mul_f32 v[124:125], v[76:77], v[96:97]
	v_pk_fma_f32 v[122:123], v[74:75], v[98:99], v[122:123]
	v_pk_fma_f32 v[124:125], v[78:79], v[98:99], v[124:125]
	v_add_f32_e32 v126, v122, v123
	v_add_f32_e32 v127, v124, v125
	ds_write_b64 v187, v[126:127] offset:59392
	s_waitcnt lgkmcnt(1)
	v_pk_mul_f32 v[106:107], v[72:73], v[30:31]
	v_pk_mul_f32 v[108:109], v[76:77], v[30:31]
	v_pk_fma_f32 v[106:107], v[74:75], v[32:33], v[106:107]
	v_pk_fma_f32 v[108:109], v[78:79], v[32:33], v[108:109]
	v_add_f32_e32 v110, v106, v107
	v_add_f32_e32 v112, v108, v109
	ds_read_b128 v[84:87], v161 offset:16128
	v_add_f32_dpp v110, v110, v110 quad_perm:[1,0,3,2] row_mask:0xf bank_mask:0xf bound_ctrl:1
	v_add_f32_dpp v112, v112, v112 quad_perm:[1,0,3,2] row_mask:0xf bank_mask:0xf bound_ctrl:1
	ds_read_b128 v[88:91], v161 offset:24320
	v_add_f32_dpp v110, v110, v110 quad_perm:[2,3,0,1] row_mask:0xf bank_mask:0xf bound_ctrl:1
	v_add_f32_dpp v112, v112, v112 quad_perm:[2,3,0,1] row_mask:0xf bank_mask:0xf bound_ctrl:1
	ds_read_b128 v[100:103], v161 offset:32512
	v_add_f32_dpp v110, v110, v110 row_half_mirror row_mask:0xf bank_mask:0xf bound_ctrl:1
	v_add_f32_dpp v112, v112, v112 row_half_mirror row_mask:0xf bank_mask:0xf bound_ctrl:1
	ds_read_b64 v[104:105], v82 offset:48896
	v_add_f32_dpp v110, v110, v110 row_ror:8 row_mask:0xf bank_mask:0xf bound_ctrl:1
	v_add_f32_dpp v112, v112, v112 row_ror:8 row_mask:0xf bank_mask:0xf bound_ctrl:1
	ds_read_b128 v[92:95], v161 offset:7936
	ds_read_b128 v[96:99], v161 offset:40704
	v_pk_mul_f32 v[114:115], v[34:35], v[110:111] op_sel_hi:[1,0]
	v_pk_mul_f32 v[116:117], v[34:35], v[112:113] op_sel_hi:[1,0]
	v_pk_mul_f32 v[118:119], v[36:37], v[110:111] op_sel_hi:[1,0]
	v_pk_mul_f32 v[120:121], v[36:37], v[112:113] op_sel_hi:[1,0]
	v_pk_fma_f32 v[114:115], v[46:47], v[80:81], v[114:115] op_sel_hi:[1,0,1]
	v_pk_fma_f32 v[116:117], v[46:47], v[80:81], v[116:117] op_sel:[0,1,0]
	v_pk_fma_f32 v[118:119], v[48:49], v[80:81], v[118:119] op_sel_hi:[1,0,1]
	v_pk_fma_f32 v[120:121], v[48:49], v[80:81], v[120:121] op_sel:[0,1,0]
	v_pk_fma_f32 v[72:73], v[72:73], v[38:39], v[114:115]
	v_pk_fma_f32 v[76:77], v[76:77], v[38:39], v[116:117]
	v_pk_fma_f32 v[74:75], v[74:75], v[40:41], v[118:119]
	v_pk_fma_f32 v[78:79], v[78:79], v[40:41], v[120:121]
	v_pk_mul_f32 v[122:123], v[72:73], v[42:43]
	v_pk_mul_f32 v[124:125], v[76:77], v[42:43]
	v_pk_fma_f32 v[122:123], v[74:75], v[44:45], v[122:123]
	v_pk_fma_f32 v[124:125], v[78:79], v[44:45], v[124:125]
	v_add_f32_e32 v126, v122, v123
	v_add_f32_e32 v127, v124, v125
	ds_write_b64 v187, v[126:127] offset:61440
	s_waitcnt lgkmcnt(1)
	v_pk_mul_f32 v[106:107], v[72:73], v[84:85]
	v_pk_mul_f32 v[108:109], v[76:77], v[84:85]
	v_pk_fma_f32 v[106:107], v[74:75], v[86:87], v[106:107]
	v_pk_fma_f32 v[108:109], v[78:79], v[86:87], v[108:109]
	v_add_f32_e32 v110, v106, v107
	v_add_f32_e32 v112, v108, v109
	s_nop 0
	v_add_f32_dpp v110, v110, v110 quad_perm:[1,0,3,2] row_mask:0xf bank_mask:0xf bound_ctrl:1
	v_add_f32_dpp v112, v112, v112 quad_perm:[1,0,3,2] row_mask:0xf bank_mask:0xf bound_ctrl:1
	s_nop 0
	v_add_f32_dpp v110, v110, v110 quad_perm:[2,3,0,1] row_mask:0xf bank_mask:0xf bound_ctrl:1
	v_add_f32_dpp v112, v112, v112 quad_perm:[2,3,0,1] row_mask:0xf bank_mask:0xf bound_ctrl:1
	s_nop 0
	v_add_f32_dpp v110, v110, v110 row_half_mirror row_mask:0xf bank_mask:0xf bound_ctrl:1
	v_add_f32_dpp v112, v112, v112 row_half_mirror row_mask:0xf bank_mask:0xf bound_ctrl:1
	s_nop 0
	v_add_f32_dpp v110, v110, v110 row_ror:8 row_mask:0xf bank_mask:0xf bound_ctrl:1
	v_add_f32_dpp v112, v112, v112 row_ror:8 row_mask:0xf bank_mask:0xf bound_ctrl:1
	v_pk_mul_f32 v[114:115], v[88:89], v[110:111] op_sel_hi:[1,0]
	v_pk_mul_f32 v[116:117], v[88:89], v[112:113] op_sel_hi:[1,0]
	v_pk_mul_f32 v[118:119], v[90:91], v[110:111] op_sel_hi:[1,0]
	v_pk_mul_f32 v[120:121], v[90:91], v[112:113] op_sel_hi:[1,0]
	v_pk_fma_f32 v[114:115], v[100:101], v[104:105], v[114:115] op_sel_hi:[1,0,1]
	v_pk_fma_f32 v[116:117], v[100:101], v[104:105], v[116:117] op_sel:[0,1,0]
	v_pk_fma_f32 v[118:119], v[102:103], v[104:105], v[118:119] op_sel_hi:[1,0,1]
	v_pk_fma_f32 v[120:121], v[102:103], v[104:105], v[120:121] op_sel:[0,1,0]
	v_pk_fma_f32 v[72:73], v[72:73], v[92:93], v[114:115]
	v_pk_fma_f32 v[76:77], v[76:77], v[92:93], v[116:117]
	v_pk_fma_f32 v[74:75], v[74:75], v[94:95], v[118:119]
	v_pk_fma_f32 v[78:79], v[78:79], v[94:95], v[120:121]
	v_pk_mul_f32 v[122:123], v[72:73], v[96:97]
	v_pk_mul_f32 v[124:125], v[76:77], v[96:97]
	v_pk_fma_f32 v[122:123], v[74:75], v[98:99], v[122:123]
	v_pk_fma_f32 v[124:125], v[78:79], v[98:99], v[124:125]
	v_add_f32_e32 v126, v122, v123
	v_add_f32_e32 v127, v124, v125
	ds_write_b64 v187, v[126:127] offset:63488

.LBB0_3086:
	s_and_saveexec_b64 s[30:31], s[22:23]
	s_cbranch_execz .LBB0_3089
	ds_read_b128 v[30:33], v161 offset:8192
	ds_read_b128 v[34:37], v161 offset:16384
	ds_read_b128 v[46:49], v161 offset:24576
	ds_read_b64 v[80:81], v82 offset:40960
	ds_read_b128 v[38:41], v161
	ds_read_b128 v[42:45], v161 offset:32768
	s_waitcnt lgkmcnt(0)
	v_pk_mul_f32 v[106:107], v[72:73], v[30:31]
	v_pk_mul_f32 v[108:109], v[76:77], v[30:31]
	v_pk_fma_f32 v[106:107], v[74:75], v[32:33], v[106:107]
	v_pk_fma_f32 v[108:109], v[78:79], v[32:33], v[108:109]
	v_add_f32_e32 v110, v106, v107
	v_add_f32_e32 v112, v108, v109
	ds_read_b128 v[84:87], v161 offset:8448
	v_add_f32_dpp v110, v110, v110 quad_perm:[1,0,3,2] row_mask:0xf bank_mask:0xf bound_ctrl:1
	v_add_f32_dpp v112, v112, v112 quad_perm:[1,0,3,2] row_mask:0xf bank_mask:0xf bound_ctrl:1
	ds_read_b128 v[88:91], v161 offset:16640
	v_add_f32_dpp v110, v110, v110 quad_perm:[2,3,0,1] row_mask:0xf bank_mask:0xf bound_ctrl:1
	v_add_f32_dpp v112, v112, v112 quad_perm:[2,3,0,1] row_mask:0xf bank_mask:0xf bound_ctrl:1
	ds_read_b128 v[100:103], v161 offset:24832
	v_add_f32_dpp v110, v110, v110 row_half_mirror row_mask:0xf bank_mask:0xf bound_ctrl:1
	v_add_f32_dpp v112, v112, v112 row_half_mirror row_mask:0xf bank_mask:0xf bound_ctrl:1
	ds_read_b64 v[104:105], v82 offset:41216
	v_add_f32_dpp v110, v110, v110 row_ror:8 row_mask:0xf bank_mask:0xf bound_ctrl:1
	v_add_f32_dpp v112, v112, v112 row_ror:8 row_mask:0xf bank_mask:0xf bound_ctrl:1
	ds_read_b128 v[92:95], v161 offset:256
	ds_read_b128 v[96:99], v161 offset:33024
	v_pk_mul_f32 v[114:115], v[34:35], v[110:111] op_sel_hi:[1,0]
	v_pk_mul_f32 v[116:117], v[34:35], v[112:113] op_sel_hi:[1,0]
	v_pk_mul_f32 v[118:119], v[36:37], v[110:111] op_sel_hi:[1,0]
	v_pk_mul_f32 v[120:121], v[36:37], v[112:113] op_sel_hi:[1,0]
	v_pk_fma_f32 v[114:115], v[46:47], v[80:81], v[114:115] op_sel_hi:[1,0,1]
	v_pk_fma_f32 v[116:117], v[46:47], v[80:81], v[116:117] op_sel:[0,1,0]
	v_pk_fma_f32 v[118:119], v[48:49], v[80:81], v[118:119] op_sel_hi:[1,0,1]
	v_pk_fma_f32 v[120:121], v[48:49], v[80:81], v[120:121] op_sel:[0,1,0]
	v_pk_fma_f32 v[72:73], v[72:73], v[38:39], v[114:115]
	v_pk_fma_f32 v[76:77], v[76:77], v[38:39], v[116:117]
	v_pk_fma_f32 v[74:75], v[74:75], v[40:41], v[118:119]
	v_pk_fma_f32 v[78:79], v[78:79], v[40:41], v[120:121]
	v_pk_mul_f32 v[122:123], v[72:73], v[42:43]
	v_pk_mul_f32 v[124:125], v[76:77], v[42:43]
	v_pk_fma_f32 v[122:123], v[74:75], v[44:45], v[122:123]
	v_pk_fma_f32 v[124:125], v[78:79], v[44:45], v[124:125]
	v_add_f32_e32 v126, v122, v123
	v_add_f32_e32 v127, v124, v125
	ds_write_b64 v187, v[126:127]
	s_waitcnt lgkmcnt(1)
	v_pk_mul_f32 v[106:107], v[72:73], v[84:85]
	v_pk_mul_f32 v[108:109], v[76:77], v[84:85]
	v_pk_fma_f32 v[106:107], v[74:75], v[86:87], v[106:107]
	v_pk_fma_f32 v[108:109], v[78:79], v[86:87], v[108:109]
	v_add_f32_e32 v110, v106, v107
	v_add_f32_e32 v112, v108, v109
	ds_read_b128 v[30:33], v161 offset:8704
	v_add_f32_dpp v110, v110, v110 quad_perm:[1,0,3,2] row_mask:0xf bank_mask:0xf bound_ctrl:1
	v_add_f32_dpp v112, v112, v112 quad_perm:[1,0,3,2] row_mask:0xf bank_mask:0xf bound_ctrl:1
	ds_read_b128 v[34:37], v161 offset:16896
	v_add_f32_dpp v110, v110, v110 quad_perm:[2,3,0,1] row_mask:0xf bank_mask:0xf bound_ctrl:1
	v_add_f32_dpp v112, v112, v112 quad_perm:[2,3,0,1] row_mask:0xf bank_mask:0xf bound_ctrl:1
	ds_read_b128 v[46:49], v161 offset:25088
	v_add_f32_dpp v110, v110, v110 row_half_mirror row_mask:0xf bank_mask:0xf bound_ctrl:1
	v_add_f32_dpp v112, v112, v112 row_half_mirror row_mask:0xf bank_mask:0xf bound_ctrl:1
	ds_read_b64 v[80:81], v82 offset:41472
	v_add_f32_dpp v110, v110, v110 row_ror:8 row_mask:0xf bank_mask:0xf bound_ctrl:1
	v_add_f32_dpp v112, v112, v112 row_ror:8 row_mask:0xf bank_mask:0xf bound_ctrl:1
	ds_read_b128 v[38:41], v161 offset:512
	ds_read_b128 v[42:45], v161 offset:33280
	v_pk_mul_f32 v[114:115], v[88:89], v[110:111] op_sel_hi:[1,0]
	v_pk_mul_f32 v[116:117], v[88:89], v[112:113] op_sel_hi:[1,0]
	v_pk_mul_f32 v[118:119], v[90:91], v[110:111] op_sel_hi:[1,0]
	v_pk_mul_f32 v[120:121], v[90:91], v[112:113] op_sel_hi:[1,0]
	v_pk_fma_f32 v[114:115], v[100:101], v[104:105], v[114:115] op_sel_hi:[1,0,1]
	v_pk_fma_f32 v[116:117], v[100:101], v[104:105], v[116:117] op_sel:[0,1,0]
	v_pk_fma_f32 v[118:119], v[102:103], v[104:105], v[118:119] op_sel_hi:[1,0,1]
	v_pk_fma_f32 v[120:121], v[102:103], v[104:105], v[120:121] op_sel:[0,1,0]
	v_pk_fma_f32 v[72:73], v[72:73], v[92:93], v[114:115]
	v_pk_fma_f32 v[76:77], v[76:77], v[92:93], v[116:117]
	v_pk_fma_f32 v[74:75], v[74:75], v[94:95], v[118:119]
	v_pk_fma_f32 v[78:79], v[78:79], v[94:95], v[120:121]
	v_pk_mul_f32 v[122:123], v[72:73], v[96:97]
	v_pk_mul_f32 v[124:125], v[76:77], v[96:97]
	v_pk_fma_f32 v[122:123], v[74:75], v[98:99], v[122:123]
	v_pk_fma_f32 v[124:125], v[78:79], v[98:99], v[124:125]
	v_add_f32_e32 v126, v122, v123
	v_add_f32_e32 v127, v124, v125
	ds_write_b64 v187, v[126:127] offset:2048
	s_waitcnt lgkmcnt(1)
	v_pk_mul_f32 v[106:107], v[72:73], v[30:31]
	v_pk_mul_f32 v[108:109], v[76:77], v[30:31]
	v_pk_fma_f32 v[106:107], v[74:75], v[32:33], v[106:107]
	v_pk_fma_f32 v[108:109], v[78:79], v[32:33], v[108:109]
	v_add_f32_e32 v110, v106, v107
	v_add_f32_e32 v112, v108, v109
	ds_read_b128 v[84:87], v161 offset:8960
	v_add_f32_dpp v110, v110, v110 quad_perm:[1,0,3,2] row_mask:0xf bank_mask:0xf bound_ctrl:1
	v_add_f32_dpp v112, v112, v112 quad_perm:[1,0,3,2] row_mask:0xf bank_mask:0xf bound_ctrl:1
	ds_read_b128 v[88:91], v161 offset:17152
	v_add_f32_dpp v110, v110, v110 quad_perm:[2,3,0,1] row_mask:0xf bank_mask:0xf bound_ctrl:1
	v_add_f32_dpp v112, v112, v112 quad_perm:[2,3,0,1] row_mask:0xf bank_mask:0xf bound_ctrl:1
	ds_read_b128 v[100:103], v161 offset:25344
	v_add_f32_dpp v110, v110, v110 row_half_mirror row_mask:0xf bank_mask:0xf bound_ctrl:1
	v_add_f32_dpp v112, v112, v112 row_half_mirror row_mask:0xf bank_mask:0xf bound_ctrl:1
	ds_read_b64 v[104:105], v82 offset:41728
	v_add_f32_dpp v110, v110, v110 row_ror:8 row_mask:0xf bank_mask:0xf bound_ctrl:1
	v_add_f32_dpp v112, v112, v112 row_ror:8 row_mask:0xf bank_mask:0xf bound_ctrl:1
	ds_read_b128 v[92:95], v161 offset:768
	ds_read_b128 v[96:99], v161 offset:33536
	v_pk_mul_f32 v[114:115], v[34:35], v[110:111] op_sel_hi:[1,0]
	v_pk_mul_f32 v[116:117], v[34:35], v[112:113] op_sel_hi:[1,0]
	v_pk_mul_f32 v[118:119], v[36:37], v[110:111] op_sel_hi:[1,0]
	v_pk_mul_f32 v[120:121], v[36:37], v[112:113] op_sel_hi:[1,0]
	v_pk_fma_f32 v[114:115], v[46:47], v[80:81], v[114:115] op_sel_hi:[1,0,1]
	v_pk_fma_f32 v[116:117], v[46:47], v[80:81], v[116:117] op_sel:[0,1,0]
	v_pk_fma_f32 v[118:119], v[48:49], v[80:81], v[118:119] op_sel_hi:[1,0,1]
	v_pk_fma_f32 v[120:121], v[48:49], v[80:81], v[120:121] op_sel:[0,1,0]
	v_pk_fma_f32 v[72:73], v[72:73], v[38:39], v[114:115]
	v_pk_fma_f32 v[76:77], v[76:77], v[38:39], v[116:117]
	v_pk_fma_f32 v[74:75], v[74:75], v[40:41], v[118:119]
	v_pk_fma_f32 v[78:79], v[78:79], v[40:41], v[120:121]
	v_pk_mul_f32 v[122:123], v[72:73], v[42:43]
	v_pk_mul_f32 v[124:125], v[76:77], v[42:43]
	v_pk_fma_f32 v[122:123], v[74:75], v[44:45], v[122:123]
	v_pk_fma_f32 v[124:125], v[78:79], v[44:45], v[124:125]
	v_add_f32_e32 v126, v122, v123
	v_add_f32_e32 v127, v124, v125
	ds_write_b64 v187, v[126:127] offset:4096
	s_waitcnt lgkmcnt(1)
	v_pk_mul_f32 v[106:107], v[72:73], v[84:85]
	v_pk_mul_f32 v[108:109], v[76:77], v[84:85]
	v_pk_fma_f32 v[106:107], v[74:75], v[86:87], v[106:107]
	v_pk_fma_f32 v[108:109], v[78:79], v[86:87], v[108:109]
	v_add_f32_e32 v110, v106, v107
	v_add_f32_e32 v112, v108, v109
	ds_read_b128 v[30:33], v161 offset:9216
	v_add_f32_dpp v110, v110, v110 quad_perm:[1,0,3,2] row_mask:0xf bank_mask:0xf bound_ctrl:1
	v_add_f32_dpp v112, v112, v112 quad_perm:[1,0,3,2] row_mask:0xf bank_mask:0xf bound_ctrl:1
	ds_read_b128 v[34:37], v161 offset:17408
	v_add_f32_dpp v110, v110, v110 quad_perm:[2,3,0,1] row_mask:0xf bank_mask:0xf bound_ctrl:1
	v_add_f32_dpp v112, v112, v112 quad_perm:[2,3,0,1] row_mask:0xf bank_mask:0xf bound_ctrl:1
	ds_read_b128 v[46:49], v161 offset:25600
	v_add_f32_dpp v110, v110, v110 row_half_mirror row_mask:0xf bank_mask:0xf bound_ctrl:1
	v_add_f32_dpp v112, v112, v112 row_half_mirror row_mask:0xf bank_mask:0xf bound_ctrl:1
	ds_read_b64 v[80:81], v82 offset:41984
	v_add_f32_dpp v110, v110, v110 row_ror:8 row_mask:0xf bank_mask:0xf bound_ctrl:1
	v_add_f32_dpp v112, v112, v112 row_ror:8 row_mask:0xf bank_mask:0xf bound_ctrl:1
	ds_read_b128 v[38:41], v161 offset:1024
	ds_read_b128 v[42:45], v161 offset:33792
	v_pk_mul_f32 v[114:115], v[88:89], v[110:111] op_sel_hi:[1,0]
	v_pk_mul_f32 v[116:117], v[88:89], v[112:113] op_sel_hi:[1,0]
	v_pk_mul_f32 v[118:119], v[90:91], v[110:111] op_sel_hi:[1,0]
	v_pk_mul_f32 v[120:121], v[90:91], v[112:113] op_sel_hi:[1,0]
	v_pk_fma_f32 v[114:115], v[100:101], v[104:105], v[114:115] op_sel_hi:[1,0,1]
	v_pk_fma_f32 v[116:117], v[100:101], v[104:105], v[116:117] op_sel:[0,1,0]
	v_pk_fma_f32 v[118:119], v[102:103], v[104:105], v[118:119] op_sel_hi:[1,0,1]
	v_pk_fma_f32 v[120:121], v[102:103], v[104:105], v[120:121] op_sel:[0,1,0]
	v_pk_fma_f32 v[72:73], v[72:73], v[92:93], v[114:115]
	v_pk_fma_f32 v[76:77], v[76:77], v[92:93], v[116:117]
	v_pk_fma_f32 v[74:75], v[74:75], v[94:95], v[118:119]
	v_pk_fma_f32 v[78:79], v[78:79], v[94:95], v[120:121]
	v_pk_mul_f32 v[122:123], v[72:73], v[96:97]
	v_pk_mul_f32 v[124:125], v[76:77], v[96:97]
	v_pk_fma_f32 v[122:123], v[74:75], v[98:99], v[122:123]
	v_pk_fma_f32 v[124:125], v[78:79], v[98:99], v[124:125]
	v_add_f32_e32 v126, v122, v123
	v_add_f32_e32 v127, v124, v125
	ds_write_b64 v187, v[126:127] offset:6144
	s_waitcnt lgkmcnt(1)
	v_pk_mul_f32 v[106:107], v[72:73], v[30:31]
	v_pk_mul_f32 v[108:109], v[76:77], v[30:31]
	v_pk_fma_f32 v[106:107], v[74:75], v[32:33], v[106:107]
	v_pk_fma_f32 v[108:109], v[78:79], v[32:33], v[108:109]
	v_add_f32_e32 v110, v106, v107
	v_add_f32_e32 v112, v108, v109
	ds_read_b128 v[84:87], v161 offset:9472
	v_add_f32_dpp v110, v110, v110 quad_perm:[1,0,3,2] row_mask:0xf bank_mask:0xf bound_ctrl:1
	v_add_f32_dpp v112, v112, v112 quad_perm:[1,0,3,2] row_mask:0xf bank_mask:0xf bound_ctrl:1
	ds_read_b128 v[88:91], v161 offset:17664
	v_add_f32_dpp v110, v110, v110 quad_perm:[2,3,0,1] row_mask:0xf bank_mask:0xf bound_ctrl:1
	v_add_f32_dpp v112, v112, v112 quad_perm:[2,3,0,1] row_mask:0xf bank_mask:0xf bound_ctrl:1
	ds_read_b128 v[100:103], v161 offset:25856
	v_add_f32_dpp v110, v110, v110 row_half_mirror row_mask:0xf bank_mask:0xf bound_ctrl:1
	v_add_f32_dpp v112, v112, v112 row_half_mirror row_mask:0xf bank_mask:0xf bound_ctrl:1
	ds_read_b64 v[104:105], v82 offset:42240
	v_add_f32_dpp v110, v110, v110 row_ror:8 row_mask:0xf bank_mask:0xf bound_ctrl:1
	v_add_f32_dpp v112, v112, v112 row_ror:8 row_mask:0xf bank_mask:0xf bound_ctrl:1
	ds_read_b128 v[92:95], v161 offset:1280
	ds_read_b128 v[96:99], v161 offset:34048
	v_pk_mul_f32 v[114:115], v[34:35], v[110:111] op_sel_hi:[1,0]
	v_pk_mul_f32 v[116:117], v[34:35], v[112:113] op_sel_hi:[1,0]
	v_pk_mul_f32 v[118:119], v[36:37], v[110:111] op_sel_hi:[1,0]
	v_pk_mul_f32 v[120:121], v[36:37], v[112:113] op_sel_hi:[1,0]
	v_pk_fma_f32 v[114:115], v[46:47], v[80:81], v[114:115] op_sel_hi:[1,0,1]
	v_pk_fma_f32 v[116:117], v[46:47], v[80:81], v[116:117] op_sel:[0,1,0]
	v_pk_fma_f32 v[118:119], v[48:49], v[80:81], v[118:119] op_sel_hi:[1,0,1]
	v_pk_fma_f32 v[120:121], v[48:49], v[80:81], v[120:121] op_sel:[0,1,0]
	v_pk_fma_f32 v[72:73], v[72:73], v[38:39], v[114:115]
	v_pk_fma_f32 v[76:77], v[76:77], v[38:39], v[116:117]
	v_pk_fma_f32 v[74:75], v[74:75], v[40:41], v[118:119]
	v_pk_fma_f32 v[78:79], v[78:79], v[40:41], v[120:121]
	v_pk_mul_f32 v[122:123], v[72:73], v[42:43]
	v_pk_mul_f32 v[124:125], v[76:77], v[42:43]
	v_pk_fma_f32 v[122:123], v[74:75], v[44:45], v[122:123]
	v_pk_fma_f32 v[124:125], v[78:79], v[44:45], v[124:125]
	v_add_f32_e32 v126, v122, v123
	v_add_f32_e32 v127, v124, v125
	ds_write_b64 v187, v[126:127] offset:8192
	s_waitcnt lgkmcnt(1)
	v_pk_mul_f32 v[106:107], v[72:73], v[84:85]
	v_pk_mul_f32 v[108:109], v[76:77], v[84:85]
	v_pk_fma_f32 v[106:107], v[74:75], v[86:87], v[106:107]
	v_pk_fma_f32 v[108:109], v[78:79], v[86:87], v[108:109]
	v_add_f32_e32 v110, v106, v107
	v_add_f32_e32 v112, v108, v109
	ds_read_b128 v[30:33], v161 offset:9728
	v_add_f32_dpp v110, v110, v110 quad_perm:[1,0,3,2] row_mask:0xf bank_mask:0xf bound_ctrl:1
	v_add_f32_dpp v112, v112, v112 quad_perm:[1,0,3,2] row_mask:0xf bank_mask:0xf bound_ctrl:1
	ds_read_b128 v[34:37], v161 offset:17920
	v_add_f32_dpp v110, v110, v110 quad_perm:[2,3,0,1] row_mask:0xf bank_mask:0xf bound_ctrl:1
	v_add_f32_dpp v112, v112, v112 quad_perm:[2,3,0,1] row_mask:0xf bank_mask:0xf bound_ctrl:1
	ds_read_b128 v[46:49], v161 offset:26112
	v_add_f32_dpp v110, v110, v110 row_half_mirror row_mask:0xf bank_mask:0xf bound_ctrl:1
	v_add_f32_dpp v112, v112, v112 row_half_mirror row_mask:0xf bank_mask:0xf bound_ctrl:1
	ds_read_b64 v[80:81], v82 offset:42496
	v_add_f32_dpp v110, v110, v110 row_ror:8 row_mask:0xf bank_mask:0xf bound_ctrl:1
	v_add_f32_dpp v112, v112, v112 row_ror:8 row_mask:0xf bank_mask:0xf bound_ctrl:1
	ds_read_b128 v[38:41], v161 offset:1536
	ds_read_b128 v[42:45], v161 offset:34304
	v_pk_mul_f32 v[114:115], v[88:89], v[110:111] op_sel_hi:[1,0]
	v_pk_mul_f32 v[116:117], v[88:89], v[112:113] op_sel_hi:[1,0]
	v_pk_mul_f32 v[118:119], v[90:91], v[110:111] op_sel_hi:[1,0]
	v_pk_mul_f32 v[120:121], v[90:91], v[112:113] op_sel_hi:[1,0]
	v_pk_fma_f32 v[114:115], v[100:101], v[104:105], v[114:115] op_sel_hi:[1,0,1]
	v_pk_fma_f32 v[116:117], v[100:101], v[104:105], v[116:117] op_sel:[0,1,0]
	v_pk_fma_f32 v[118:119], v[102:103], v[104:105], v[118:119] op_sel_hi:[1,0,1]
	v_pk_fma_f32 v[120:121], v[102:103], v[104:105], v[120:121] op_sel:[0,1,0]
	v_pk_fma_f32 v[72:73], v[72:73], v[92:93], v[114:115]
	v_pk_fma_f32 v[76:77], v[76:77], v[92:93], v[116:117]
	v_pk_fma_f32 v[74:75], v[74:75], v[94:95], v[118:119]
	v_pk_fma_f32 v[78:79], v[78:79], v[94:95], v[120:121]
	v_pk_mul_f32 v[122:123], v[72:73], v[96:97]
	v_pk_mul_f32 v[124:125], v[76:77], v[96:97]
	v_pk_fma_f32 v[122:123], v[74:75], v[98:99], v[122:123]
	v_pk_fma_f32 v[124:125], v[78:79], v[98:99], v[124:125]
	v_add_f32_e32 v126, v122, v123
	v_add_f32_e32 v127, v124, v125
	ds_write_b64 v187, v[126:127] offset:10240
	s_waitcnt lgkmcnt(1)
	v_pk_mul_f32 v[106:107], v[72:73], v[30:31]
	v_pk_mul_f32 v[108:109], v[76:77], v[30:31]
	v_pk_fma_f32 v[106:107], v[74:75], v[32:33], v[106:107]
	v_pk_fma_f32 v[108:109], v[78:79], v[32:33], v[108:109]
	v_add_f32_e32 v110, v106, v107
	v_add_f32_e32 v112, v108, v109
	ds_read_b128 v[84:87], v161 offset:9984
	v_add_f32_dpp v110, v110, v110 quad_perm:[1,0,3,2] row_mask:0xf bank_mask:0xf bound_ctrl:1
	v_add_f32_dpp v112, v112, v112 quad_perm:[1,0,3,2] row_mask:0xf bank_mask:0xf bound_ctrl:1
	ds_read_b128 v[88:91], v161 offset:18176
	v_add_f32_dpp v110, v110, v110 quad_perm:[2,3,0,1] row_mask:0xf bank_mask:0xf bound_ctrl:1
	v_add_f32_dpp v112, v112, v112 quad_perm:[2,3,0,1] row_mask:0xf bank_mask:0xf bound_ctrl:1
	ds_read_b128 v[100:103], v161 offset:26368
	v_add_f32_dpp v110, v110, v110 row_half_mirror row_mask:0xf bank_mask:0xf bound_ctrl:1
	v_add_f32_dpp v112, v112, v112 row_half_mirror row_mask:0xf bank_mask:0xf bound_ctrl:1
	ds_read_b64 v[104:105], v82 offset:42752
	v_add_f32_dpp v110, v110, v110 row_ror:8 row_mask:0xf bank_mask:0xf bound_ctrl:1
	v_add_f32_dpp v112, v112, v112 row_ror:8 row_mask:0xf bank_mask:0xf bound_ctrl:1
	ds_read_b128 v[92:95], v161 offset:1792
	ds_read_b128 v[96:99], v161 offset:34560
	v_pk_mul_f32 v[114:115], v[34:35], v[110:111] op_sel_hi:[1,0]
	v_pk_mul_f32 v[116:117], v[34:35], v[112:113] op_sel_hi:[1,0]
	v_pk_mul_f32 v[118:119], v[36:37], v[110:111] op_sel_hi:[1,0]
	v_pk_mul_f32 v[120:121], v[36:37], v[112:113] op_sel_hi:[1,0]
	v_pk_fma_f32 v[114:115], v[46:47], v[80:81], v[114:115] op_sel_hi:[1,0,1]
	v_pk_fma_f32 v[116:117], v[46:47], v[80:81], v[116:117] op_sel:[0,1,0]
	v_pk_fma_f32 v[118:119], v[48:49], v[80:81], v[118:119] op_sel_hi:[1,0,1]
	v_pk_fma_f32 v[120:121], v[48:49], v[80:81], v[120:121] op_sel:[0,1,0]
	v_pk_fma_f32 v[72:73], v[72:73], v[38:39], v[114:115]
	v_pk_fma_f32 v[76:77], v[76:77], v[38:39], v[116:117]
	v_pk_fma_f32 v[74:75], v[74:75], v[40:41], v[118:119]
	v_pk_fma_f32 v[78:79], v[78:79], v[40:41], v[120:121]
	v_pk_mul_f32 v[122:123], v[72:73], v[42:43]
	v_pk_mul_f32 v[124:125], v[76:77], v[42:43]
	v_pk_fma_f32 v[122:123], v[74:75], v[44:45], v[122:123]
	v_pk_fma_f32 v[124:125], v[78:79], v[44:45], v[124:125]
	v_add_f32_e32 v126, v122, v123
	v_add_f32_e32 v127, v124, v125
	ds_write_b64 v187, v[126:127] offset:12288
	s_waitcnt lgkmcnt(1)
	v_pk_mul_f32 v[106:107], v[72:73], v[84:85]
	v_pk_mul_f32 v[108:109], v[76:77], v[84:85]
	v_pk_fma_f32 v[106:107], v[74:75], v[86:87], v[106:107]
	v_pk_fma_f32 v[108:109], v[78:79], v[86:87], v[108:109]
	v_add_f32_e32 v110, v106, v107
	v_add_f32_e32 v112, v108, v109
	ds_read_b128 v[30:33], v161 offset:10240
	v_add_f32_dpp v110, v110, v110 quad_perm:[1,0,3,2] row_mask:0xf bank_mask:0xf bound_ctrl:1
	v_add_f32_dpp v112, v112, v112 quad_perm:[1,0,3,2] row_mask:0xf bank_mask:0xf bound_ctrl:1
	ds_read_b128 v[34:37], v161 offset:18432
	v_add_f32_dpp v110, v110, v110 quad_perm:[2,3,0,1] row_mask:0xf bank_mask:0xf bound_ctrl:1
	v_add_f32_dpp v112, v112, v112 quad_perm:[2,3,0,1] row_mask:0xf bank_mask:0xf bound_ctrl:1
	ds_read_b128 v[46:49], v161 offset:26624
	v_add_f32_dpp v110, v110, v110 row_half_mirror row_mask:0xf bank_mask:0xf bound_ctrl:1
	v_add_f32_dpp v112, v112, v112 row_half_mirror row_mask:0xf bank_mask:0xf bound_ctrl:1
	ds_read_b64 v[80:81], v82 offset:43008
	v_add_f32_dpp v110, v110, v110 row_ror:8 row_mask:0xf bank_mask:0xf bound_ctrl:1
	v_add_f32_dpp v112, v112, v112 row_ror:8 row_mask:0xf bank_mask:0xf bound_ctrl:1
	ds_read_b128 v[38:41], v161 offset:2048
	ds_read_b128 v[42:45], v161 offset:34816
	v_pk_mul_f32 v[114:115], v[88:89], v[110:111] op_sel_hi:[1,0]
	v_pk_mul_f32 v[116:117], v[88:89], v[112:113] op_sel_hi:[1,0]
	v_pk_mul_f32 v[118:119], v[90:91], v[110:111] op_sel_hi:[1,0]
	v_pk_mul_f32 v[120:121], v[90:91], v[112:113] op_sel_hi:[1,0]
	v_pk_fma_f32 v[114:115], v[100:101], v[104:105], v[114:115] op_sel_hi:[1,0,1]
	v_pk_fma_f32 v[116:117], v[100:101], v[104:105], v[116:117] op_sel:[0,1,0]
	v_pk_fma_f32 v[118:119], v[102:103], v[104:105], v[118:119] op_sel_hi:[1,0,1]
	v_pk_fma_f32 v[120:121], v[102:103], v[104:105], v[120:121] op_sel:[0,1,0]
	v_pk_fma_f32 v[72:73], v[72:73], v[92:93], v[114:115]
	v_pk_fma_f32 v[76:77], v[76:77], v[92:93], v[116:117]
	v_pk_fma_f32 v[74:75], v[74:75], v[94:95], v[118:119]
	v_pk_fma_f32 v[78:79], v[78:79], v[94:95], v[120:121]
	v_pk_mul_f32 v[122:123], v[72:73], v[96:97]
	v_pk_mul_f32 v[124:125], v[76:77], v[96:97]
	v_pk_fma_f32 v[122:123], v[74:75], v[98:99], v[122:123]
	v_pk_fma_f32 v[124:125], v[78:79], v[98:99], v[124:125]
	v_add_f32_e32 v126, v122, v123
	v_add_f32_e32 v127, v124, v125
	ds_write_b64 v187, v[126:127] offset:14336
	s_waitcnt lgkmcnt(1)
	v_pk_mul_f32 v[106:107], v[72:73], v[30:31]
	v_pk_mul_f32 v[108:109], v[76:77], v[30:31]
	v_pk_fma_f32 v[106:107], v[74:75], v[32:33], v[106:107]
	v_pk_fma_f32 v[108:109], v[78:79], v[32:33], v[108:109]
	v_add_f32_e32 v110, v106, v107
	v_add_f32_e32 v112, v108, v109
	ds_read_b128 v[84:87], v161 offset:10496
	v_add_f32_dpp v110, v110, v110 quad_perm:[1,0,3,2] row_mask:0xf bank_mask:0xf bound_ctrl:1
	v_add_f32_dpp v112, v112, v112 quad_perm:[1,0,3,2] row_mask:0xf bank_mask:0xf bound_ctrl:1
	ds_read_b128 v[88:91], v161 offset:18688
	v_add_f32_dpp v110, v110, v110 quad_perm:[2,3,0,1] row_mask:0xf bank_mask:0xf bound_ctrl:1
	v_add_f32_dpp v112, v112, v112 quad_perm:[2,3,0,1] row_mask:0xf bank_mask:0xf bound_ctrl:1
	ds_read_b128 v[100:103], v161 offset:26880
	v_add_f32_dpp v110, v110, v110 row_half_mirror row_mask:0xf bank_mask:0xf bound_ctrl:1
	v_add_f32_dpp v112, v112, v112 row_half_mirror row_mask:0xf bank_mask:0xf bound_ctrl:1
	ds_read_b64 v[104:105], v82 offset:43264
	v_add_f32_dpp v110, v110, v110 row_ror:8 row_mask:0xf bank_mask:0xf bound_ctrl:1
	v_add_f32_dpp v112, v112, v112 row_ror:8 row_mask:0xf bank_mask:0xf bound_ctrl:1
	ds_read_b128 v[92:95], v161 offset:2304
	ds_read_b128 v[96:99], v161 offset:35072
	v_pk_mul_f32 v[114:115], v[34:35], v[110:111] op_sel_hi:[1,0]
	v_pk_mul_f32 v[116:117], v[34:35], v[112:113] op_sel_hi:[1,0]
	v_pk_mul_f32 v[118:119], v[36:37], v[110:111] op_sel_hi:[1,0]
	v_pk_mul_f32 v[120:121], v[36:37], v[112:113] op_sel_hi:[1,0]
	v_pk_fma_f32 v[114:115], v[46:47], v[80:81], v[114:115] op_sel_hi:[1,0,1]
	v_pk_fma_f32 v[116:117], v[46:47], v[80:81], v[116:117] op_sel:[0,1,0]
	v_pk_fma_f32 v[118:119], v[48:49], v[80:81], v[118:119] op_sel_hi:[1,0,1]
	v_pk_fma_f32 v[120:121], v[48:49], v[80:81], v[120:121] op_sel:[0,1,0]
	v_pk_fma_f32 v[72:73], v[72:73], v[38:39], v[114:115]
	v_pk_fma_f32 v[76:77], v[76:77], v[38:39], v[116:117]
	v_pk_fma_f32 v[74:75], v[74:75], v[40:41], v[118:119]
	v_pk_fma_f32 v[78:79], v[78:79], v[40:41], v[120:121]
	v_pk_mul_f32 v[122:123], v[72:73], v[42:43]
	v_pk_mul_f32 v[124:125], v[76:77], v[42:43]
	v_pk_fma_f32 v[122:123], v[74:75], v[44:45], v[122:123]
	v_pk_fma_f32 v[124:125], v[78:79], v[44:45], v[124:125]
	v_add_f32_e32 v126, v122, v123
	v_add_f32_e32 v127, v124, v125
	ds_write_b64 v187, v[126:127] offset:16384
	s_waitcnt lgkmcnt(1)
	v_pk_mul_f32 v[106:107], v[72:73], v[84:85]
	v_pk_mul_f32 v[108:109], v[76:77], v[84:85]
	v_pk_fma_f32 v[106:107], v[74:75], v[86:87], v[106:107]
	v_pk_fma_f32 v[108:109], v[78:79], v[86:87], v[108:109]
	v_add_f32_e32 v110, v106, v107
	v_add_f32_e32 v112, v108, v109
	ds_read_b128 v[30:33], v161 offset:10752
	v_add_f32_dpp v110, v110, v110 quad_perm:[1,0,3,2] row_mask:0xf bank_mask:0xf bound_ctrl:1
	v_add_f32_dpp v112, v112, v112 quad_perm:[1,0,3,2] row_mask:0xf bank_mask:0xf bound_ctrl:1
	ds_read_b128 v[34:37], v161 offset:18944
	v_add_f32_dpp v110, v110, v110 quad_perm:[2,3,0,1] row_mask:0xf bank_mask:0xf bound_ctrl:1
	v_add_f32_dpp v112, v112, v112 quad_perm:[2,3,0,1] row_mask:0xf bank_mask:0xf bound_ctrl:1
	ds_read_b128 v[46:49], v161 offset:27136
	v_add_f32_dpp v110, v110, v110 row_half_mirror row_mask:0xf bank_mask:0xf bound_ctrl:1
	v_add_f32_dpp v112, v112, v112 row_half_mirror row_mask:0xf bank_mask:0xf bound_ctrl:1
	ds_read_b64 v[80:81], v82 offset:43520
	v_add_f32_dpp v110, v110, v110 row_ror:8 row_mask:0xf bank_mask:0xf bound_ctrl:1
	v_add_f32_dpp v112, v112, v112 row_ror:8 row_mask:0xf bank_mask:0xf bound_ctrl:1
	ds_read_b128 v[38:41], v161 offset:2560
	ds_read_b128 v[42:45], v161 offset:35328
	v_pk_mul_f32 v[114:115], v[88:89], v[110:111] op_sel_hi:[1,0]
	v_pk_mul_f32 v[116:117], v[88:89], v[112:113] op_sel_hi:[1,0]
	v_pk_mul_f32 v[118:119], v[90:91], v[110:111] op_sel_hi:[1,0]
	v_pk_mul_f32 v[120:121], v[90:91], v[112:113] op_sel_hi:[1,0]
	v_pk_fma_f32 v[114:115], v[100:101], v[104:105], v[114:115] op_sel_hi:[1,0,1]
	v_pk_fma_f32 v[116:117], v[100:101], v[104:105], v[116:117] op_sel:[0,1,0]
	v_pk_fma_f32 v[118:119], v[102:103], v[104:105], v[118:119] op_sel_hi:[1,0,1]
	v_pk_fma_f32 v[120:121], v[102:103], v[104:105], v[120:121] op_sel:[0,1,0]
	v_pk_fma_f32 v[72:73], v[72:73], v[92:93], v[114:115]
	v_pk_fma_f32 v[76:77], v[76:77], v[92:93], v[116:117]
	v_pk_fma_f32 v[74:75], v[74:75], v[94:95], v[118:119]
	v_pk_fma_f32 v[78:79], v[78:79], v[94:95], v[120:121]
	v_pk_mul_f32 v[122:123], v[72:73], v[96:97]
	v_pk_mul_f32 v[124:125], v[76:77], v[96:97]
	v_pk_fma_f32 v[122:123], v[74:75], v[98:99], v[122:123]
	v_pk_fma_f32 v[124:125], v[78:79], v[98:99], v[124:125]
	v_add_f32_e32 v126, v122, v123
	v_add_f32_e32 v127, v124, v125
	ds_write_b64 v187, v[126:127] offset:18432
	s_waitcnt lgkmcnt(1)
	v_pk_mul_f32 v[106:107], v[72:73], v[30:31]
	v_pk_mul_f32 v[108:109], v[76:77], v[30:31]
	v_pk_fma_f32 v[106:107], v[74:75], v[32:33], v[106:107]
	v_pk_fma_f32 v[108:109], v[78:79], v[32:33], v[108:109]
	v_add_f32_e32 v110, v106, v107
	v_add_f32_e32 v112, v108, v109
	ds_read_b128 v[84:87], v161 offset:11008
	v_add_f32_dpp v110, v110, v110 quad_perm:[1,0,3,2] row_mask:0xf bank_mask:0xf bound_ctrl:1
	v_add_f32_dpp v112, v112, v112 quad_perm:[1,0,3,2] row_mask:0xf bank_mask:0xf bound_ctrl:1
	ds_read_b128 v[88:91], v161 offset:19200
	v_add_f32_dpp v110, v110, v110 quad_perm:[2,3,0,1] row_mask:0xf bank_mask:0xf bound_ctrl:1
	v_add_f32_dpp v112, v112, v112 quad_perm:[2,3,0,1] row_mask:0xf bank_mask:0xf bound_ctrl:1
	ds_read_b128 v[100:103], v161 offset:27392
	v_add_f32_dpp v110, v110, v110 row_half_mirror row_mask:0xf bank_mask:0xf bound_ctrl:1
	v_add_f32_dpp v112, v112, v112 row_half_mirror row_mask:0xf bank_mask:0xf bound_ctrl:1
	ds_read_b64 v[104:105], v82 offset:43776
	v_add_f32_dpp v110, v110, v110 row_ror:8 row_mask:0xf bank_mask:0xf bound_ctrl:1
	v_add_f32_dpp v112, v112, v112 row_ror:8 row_mask:0xf bank_mask:0xf bound_ctrl:1
	ds_read_b128 v[92:95], v161 offset:2816
	ds_read_b128 v[96:99], v161 offset:35584
	v_pk_mul_f32 v[114:115], v[34:35], v[110:111] op_sel_hi:[1,0]
	v_pk_mul_f32 v[116:117], v[34:35], v[112:113] op_sel_hi:[1,0]
	v_pk_mul_f32 v[118:119], v[36:37], v[110:111] op_sel_hi:[1,0]
	v_pk_mul_f32 v[120:121], v[36:37], v[112:113] op_sel_hi:[1,0]
	v_pk_fma_f32 v[114:115], v[46:47], v[80:81], v[114:115] op_sel_hi:[1,0,1]
	v_pk_fma_f32 v[116:117], v[46:47], v[80:81], v[116:117] op_sel:[0,1,0]
	v_pk_fma_f32 v[118:119], v[48:49], v[80:81], v[118:119] op_sel_hi:[1,0,1]
	v_pk_fma_f32 v[120:121], v[48:49], v[80:81], v[120:121] op_sel:[0,1,0]
	v_pk_fma_f32 v[72:73], v[72:73], v[38:39], v[114:115]
	v_pk_fma_f32 v[76:77], v[76:77], v[38:39], v[116:117]
	v_pk_fma_f32 v[74:75], v[74:75], v[40:41], v[118:119]
	v_pk_fma_f32 v[78:79], v[78:79], v[40:41], v[120:121]
	v_pk_mul_f32 v[122:123], v[72:73], v[42:43]
	v_pk_mul_f32 v[124:125], v[76:77], v[42:43]
	v_pk_fma_f32 v[122:123], v[74:75], v[44:45], v[122:123]
	v_pk_fma_f32 v[124:125], v[78:79], v[44:45], v[124:125]
	v_add_f32_e32 v126, v122, v123
	v_add_f32_e32 v127, v124, v125
	ds_write_b64 v187, v[126:127] offset:20480
	s_waitcnt lgkmcnt(1)
	v_pk_mul_f32 v[106:107], v[72:73], v[84:85]
	v_pk_mul_f32 v[108:109], v[76:77], v[84:85]
	v_pk_fma_f32 v[106:107], v[74:75], v[86:87], v[106:107]
	v_pk_fma_f32 v[108:109], v[78:79], v[86:87], v[108:109]
	v_add_f32_e32 v110, v106, v107
	v_add_f32_e32 v112, v108, v109
	ds_read_b128 v[30:33], v161 offset:11264
	v_add_f32_dpp v110, v110, v110 quad_perm:[1,0,3,2] row_mask:0xf bank_mask:0xf bound_ctrl:1
	v_add_f32_dpp v112, v112, v112 quad_perm:[1,0,3,2] row_mask:0xf bank_mask:0xf bound_ctrl:1
	ds_read_b128 v[34:37], v161 offset:19456
	v_add_f32_dpp v110, v110, v110 quad_perm:[2,3,0,1] row_mask:0xf bank_mask:0xf bound_ctrl:1
	v_add_f32_dpp v112, v112, v112 quad_perm:[2,3,0,1] row_mask:0xf bank_mask:0xf bound_ctrl:1
	ds_read_b128 v[46:49], v161 offset:27648
	v_add_f32_dpp v110, v110, v110 row_half_mirror row_mask:0xf bank_mask:0xf bound_ctrl:1
	v_add_f32_dpp v112, v112, v112 row_half_mirror row_mask:0xf bank_mask:0xf bound_ctrl:1
	ds_read_b64 v[80:81], v82 offset:44032
	v_add_f32_dpp v110, v110, v110 row_ror:8 row_mask:0xf bank_mask:0xf bound_ctrl:1
	v_add_f32_dpp v112, v112, v112 row_ror:8 row_mask:0xf bank_mask:0xf bound_ctrl:1
	ds_read_b128 v[38:41], v161 offset:3072
	ds_read_b128 v[42:45], v161 offset:35840
	v_pk_mul_f32 v[114:115], v[88:89], v[110:111] op_sel_hi:[1,0]
	v_pk_mul_f32 v[116:117], v[88:89], v[112:113] op_sel_hi:[1,0]
	v_pk_mul_f32 v[118:119], v[90:91], v[110:111] op_sel_hi:[1,0]
	v_pk_mul_f32 v[120:121], v[90:91], v[112:113] op_sel_hi:[1,0]
	v_pk_fma_f32 v[114:115], v[100:101], v[104:105], v[114:115] op_sel_hi:[1,0,1]
	v_pk_fma_f32 v[116:117], v[100:101], v[104:105], v[116:117] op_sel:[0,1,0]
	v_pk_fma_f32 v[118:119], v[102:103], v[104:105], v[118:119] op_sel_hi:[1,0,1]
	v_pk_fma_f32 v[120:121], v[102:103], v[104:105], v[120:121] op_sel:[0,1,0]
	v_pk_fma_f32 v[72:73], v[72:73], v[92:93], v[114:115]
	v_pk_fma_f32 v[76:77], v[76:77], v[92:93], v[116:117]
	v_pk_fma_f32 v[74:75], v[74:75], v[94:95], v[118:119]
	v_pk_fma_f32 v[78:79], v[78:79], v[94:95], v[120:121]
	v_pk_mul_f32 v[122:123], v[72:73], v[96:97]
	v_pk_mul_f32 v[124:125], v[76:77], v[96:97]
	v_pk_fma_f32 v[122:123], v[74:75], v[98:99], v[122:123]
	v_pk_fma_f32 v[124:125], v[78:79], v[98:99], v[124:125]
	v_add_f32_e32 v126, v122, v123
	v_add_f32_e32 v127, v124, v125
	ds_write_b64 v187, v[126:127] offset:22528
	s_waitcnt lgkmcnt(1)
	v_pk_mul_f32 v[106:107], v[72:73], v[30:31]
	v_pk_mul_f32 v[108:109], v[76:77], v[30:31]
	v_pk_fma_f32 v[106:107], v[74:75], v[32:33], v[106:107]
	v_pk_fma_f32 v[108:109], v[78:79], v[32:33], v[108:109]
	v_add_f32_e32 v110, v106, v107
	v_add_f32_e32 v112, v108, v109
	ds_read_b128 v[84:87], v161 offset:11520
	v_add_f32_dpp v110, v110, v110 quad_perm:[1,0,3,2] row_mask:0xf bank_mask:0xf bound_ctrl:1
	v_add_f32_dpp v112, v112, v112 quad_perm:[1,0,3,2] row_mask:0xf bank_mask:0xf bound_ctrl:1
	ds_read_b128 v[88:91], v161 offset:19712
	v_add_f32_dpp v110, v110, v110 quad_perm:[2,3,0,1] row_mask:0xf bank_mask:0xf bound_ctrl:1
	v_add_f32_dpp v112, v112, v112 quad_perm:[2,3,0,1] row_mask:0xf bank_mask:0xf bound_ctrl:1
	ds_read_b128 v[100:103], v161 offset:27904
	v_add_f32_dpp v110, v110, v110 row_half_mirror row_mask:0xf bank_mask:0xf bound_ctrl:1
	v_add_f32_dpp v112, v112, v112 row_half_mirror row_mask:0xf bank_mask:0xf bound_ctrl:1
	ds_read_b64 v[104:105], v82 offset:44288
	v_add_f32_dpp v110, v110, v110 row_ror:8 row_mask:0xf bank_mask:0xf bound_ctrl:1
	v_add_f32_dpp v112, v112, v112 row_ror:8 row_mask:0xf bank_mask:0xf bound_ctrl:1
	ds_read_b128 v[92:95], v161 offset:3328
	ds_read_b128 v[96:99], v161 offset:36096
	v_pk_mul_f32 v[114:115], v[34:35], v[110:111] op_sel_hi:[1,0]
	v_pk_mul_f32 v[116:117], v[34:35], v[112:113] op_sel_hi:[1,0]
	v_pk_mul_f32 v[118:119], v[36:37], v[110:111] op_sel_hi:[1,0]
	v_pk_mul_f32 v[120:121], v[36:37], v[112:113] op_sel_hi:[1,0]
	v_pk_fma_f32 v[114:115], v[46:47], v[80:81], v[114:115] op_sel_hi:[1,0,1]
	v_pk_fma_f32 v[116:117], v[46:47], v[80:81], v[116:117] op_sel:[0,1,0]
	v_pk_fma_f32 v[118:119], v[48:49], v[80:81], v[118:119] op_sel_hi:[1,0,1]
	v_pk_fma_f32 v[120:121], v[48:49], v[80:81], v[120:121] op_sel:[0,1,0]
	v_pk_fma_f32 v[72:73], v[72:73], v[38:39], v[114:115]
	v_pk_fma_f32 v[76:77], v[76:77], v[38:39], v[116:117]
	v_pk_fma_f32 v[74:75], v[74:75], v[40:41], v[118:119]
	v_pk_fma_f32 v[78:79], v[78:79], v[40:41], v[120:121]
	v_pk_mul_f32 v[122:123], v[72:73], v[42:43]
	v_pk_mul_f32 v[124:125], v[76:77], v[42:43]
	v_pk_fma_f32 v[122:123], v[74:75], v[44:45], v[122:123]
	v_pk_fma_f32 v[124:125], v[78:79], v[44:45], v[124:125]
	v_add_f32_e32 v126, v122, v123
	v_add_f32_e32 v127, v124, v125
	ds_write_b64 v187, v[126:127] offset:24576
	s_waitcnt lgkmcnt(1)
	v_pk_mul_f32 v[106:107], v[72:73], v[84:85]
	v_pk_mul_f32 v[108:109], v[76:77], v[84:85]
	v_pk_fma_f32 v[106:107], v[74:75], v[86:87], v[106:107]
	v_pk_fma_f32 v[108:109], v[78:79], v[86:87], v[108:109]
	v_add_f32_e32 v110, v106, v107
	v_add_f32_e32 v112, v108, v109
	ds_read_b128 v[30:33], v161 offset:11776
	v_add_f32_dpp v110, v110, v110 quad_perm:[1,0,3,2] row_mask:0xf bank_mask:0xf bound_ctrl:1
	v_add_f32_dpp v112, v112, v112 quad_perm:[1,0,3,2] row_mask:0xf bank_mask:0xf bound_ctrl:1
	ds_read_b128 v[34:37], v161 offset:19968
	v_add_f32_dpp v110, v110, v110 quad_perm:[2,3,0,1] row_mask:0xf bank_mask:0xf bound_ctrl:1
	v_add_f32_dpp v112, v112, v112 quad_perm:[2,3,0,1] row_mask:0xf bank_mask:0xf bound_ctrl:1
	ds_read_b128 v[46:49], v161 offset:28160
	v_add_f32_dpp v110, v110, v110 row_half_mirror row_mask:0xf bank_mask:0xf bound_ctrl:1
	v_add_f32_dpp v112, v112, v112 row_half_mirror row_mask:0xf bank_mask:0xf bound_ctrl:1
	ds_read_b64 v[80:81], v82 offset:44544
	v_add_f32_dpp v110, v110, v110 row_ror:8 row_mask:0xf bank_mask:0xf bound_ctrl:1
	v_add_f32_dpp v112, v112, v112 row_ror:8 row_mask:0xf bank_mask:0xf bound_ctrl:1
	ds_read_b128 v[38:41], v161 offset:3584
	ds_read_b128 v[42:45], v161 offset:36352
	v_pk_mul_f32 v[114:115], v[88:89], v[110:111] op_sel_hi:[1,0]
	v_pk_mul_f32 v[116:117], v[88:89], v[112:113] op_sel_hi:[1,0]
	v_pk_mul_f32 v[118:119], v[90:91], v[110:111] op_sel_hi:[1,0]
	v_pk_mul_f32 v[120:121], v[90:91], v[112:113] op_sel_hi:[1,0]
	v_pk_fma_f32 v[114:115], v[100:101], v[104:105], v[114:115] op_sel_hi:[1,0,1]
	v_pk_fma_f32 v[116:117], v[100:101], v[104:105], v[116:117] op_sel:[0,1,0]
	v_pk_fma_f32 v[118:119], v[102:103], v[104:105], v[118:119] op_sel_hi:[1,0,1]
	v_pk_fma_f32 v[120:121], v[102:103], v[104:105], v[120:121] op_sel:[0,1,0]
	v_pk_fma_f32 v[72:73], v[72:73], v[92:93], v[114:115]
	v_pk_fma_f32 v[76:77], v[76:77], v[92:93], v[116:117]
	v_pk_fma_f32 v[74:75], v[74:75], v[94:95], v[118:119]
	v_pk_fma_f32 v[78:79], v[78:79], v[94:95], v[120:121]
	v_pk_mul_f32 v[122:123], v[72:73], v[96:97]
	v_pk_mul_f32 v[124:125], v[76:77], v[96:97]
	v_pk_fma_f32 v[122:123], v[74:75], v[98:99], v[122:123]
	v_pk_fma_f32 v[124:125], v[78:79], v[98:99], v[124:125]
	v_add_f32_e32 v126, v122, v123
	v_add_f32_e32 v127, v124, v125
	ds_write_b64 v187, v[126:127] offset:26624
	s_waitcnt lgkmcnt(1)
	v_pk_mul_f32 v[106:107], v[72:73], v[30:31]
	v_pk_mul_f32 v[108:109], v[76:77], v[30:31]
	v_pk_fma_f32 v[106:107], v[74:75], v[32:33], v[106:107]
	v_pk_fma_f32 v[108:109], v[78:79], v[32:33], v[108:109]
	v_add_f32_e32 v110, v106, v107
	v_add_f32_e32 v112, v108, v109
	ds_read_b128 v[84:87], v161 offset:12032
	v_add_f32_dpp v110, v110, v110 quad_perm:[1,0,3,2] row_mask:0xf bank_mask:0xf bound_ctrl:1
	v_add_f32_dpp v112, v112, v112 quad_perm:[1,0,3,2] row_mask:0xf bank_mask:0xf bound_ctrl:1
	ds_read_b128 v[88:91], v161 offset:20224
	v_add_f32_dpp v110, v110, v110 quad_perm:[2,3,0,1] row_mask:0xf bank_mask:0xf bound_ctrl:1
	v_add_f32_dpp v112, v112, v112 quad_perm:[2,3,0,1] row_mask:0xf bank_mask:0xf bound_ctrl:1
	ds_read_b128 v[100:103], v161 offset:28416
	v_add_f32_dpp v110, v110, v110 row_half_mirror row_mask:0xf bank_mask:0xf bound_ctrl:1
	v_add_f32_dpp v112, v112, v112 row_half_mirror row_mask:0xf bank_mask:0xf bound_ctrl:1
	ds_read_b64 v[104:105], v82 offset:44800
	v_add_f32_dpp v110, v110, v110 row_ror:8 row_mask:0xf bank_mask:0xf bound_ctrl:1
	v_add_f32_dpp v112, v112, v112 row_ror:8 row_mask:0xf bank_mask:0xf bound_ctrl:1
	ds_read_b128 v[92:95], v161 offset:3840
	ds_read_b128 v[96:99], v161 offset:36608
	v_pk_mul_f32 v[114:115], v[34:35], v[110:111] op_sel_hi:[1,0]
	v_pk_mul_f32 v[116:117], v[34:35], v[112:113] op_sel_hi:[1,0]
	v_pk_mul_f32 v[118:119], v[36:37], v[110:111] op_sel_hi:[1,0]
	v_pk_mul_f32 v[120:121], v[36:37], v[112:113] op_sel_hi:[1,0]
	v_pk_fma_f32 v[114:115], v[46:47], v[80:81], v[114:115] op_sel_hi:[1,0,1]
	v_pk_fma_f32 v[116:117], v[46:47], v[80:81], v[116:117] op_sel:[0,1,0]
	v_pk_fma_f32 v[118:119], v[48:49], v[80:81], v[118:119] op_sel_hi:[1,0,1]
	v_pk_fma_f32 v[120:121], v[48:49], v[80:81], v[120:121] op_sel:[0,1,0]
	v_pk_fma_f32 v[72:73], v[72:73], v[38:39], v[114:115]
	v_pk_fma_f32 v[76:77], v[76:77], v[38:39], v[116:117]
	v_pk_fma_f32 v[74:75], v[74:75], v[40:41], v[118:119]
	v_pk_fma_f32 v[78:79], v[78:79], v[40:41], v[120:121]
	v_pk_mul_f32 v[122:123], v[72:73], v[42:43]
	v_pk_mul_f32 v[124:125], v[76:77], v[42:43]
	v_pk_fma_f32 v[122:123], v[74:75], v[44:45], v[122:123]
	v_pk_fma_f32 v[124:125], v[78:79], v[44:45], v[124:125]
	v_add_f32_e32 v126, v122, v123
	v_add_f32_e32 v127, v124, v125
	ds_write_b64 v187, v[126:127] offset:28672
	s_waitcnt lgkmcnt(1)
	v_pk_mul_f32 v[106:107], v[72:73], v[84:85]
	v_pk_mul_f32 v[108:109], v[76:77], v[84:85]
	v_pk_fma_f32 v[106:107], v[74:75], v[86:87], v[106:107]
	v_pk_fma_f32 v[108:109], v[78:79], v[86:87], v[108:109]
	v_add_f32_e32 v110, v106, v107
	v_add_f32_e32 v112, v108, v109
	ds_read_b128 v[30:33], v161 offset:12288
	v_add_f32_dpp v110, v110, v110 quad_perm:[1,0,3,2] row_mask:0xf bank_mask:0xf bound_ctrl:1
	v_add_f32_dpp v112, v112, v112 quad_perm:[1,0,3,2] row_mask:0xf bank_mask:0xf bound_ctrl:1
	ds_read_b128 v[34:37], v161 offset:20480
	v_add_f32_dpp v110, v110, v110 quad_perm:[2,3,0,1] row_mask:0xf bank_mask:0xf bound_ctrl:1
	v_add_f32_dpp v112, v112, v112 quad_perm:[2,3,0,1] row_mask:0xf bank_mask:0xf bound_ctrl:1
	ds_read_b128 v[46:49], v161 offset:28672
	v_add_f32_dpp v110, v110, v110 row_half_mirror row_mask:0xf bank_mask:0xf bound_ctrl:1
	v_add_f32_dpp v112, v112, v112 row_half_mirror row_mask:0xf bank_mask:0xf bound_ctrl:1
	ds_read_b64 v[80:81], v82 offset:45056
	v_add_f32_dpp v110, v110, v110 row_ror:8 row_mask:0xf bank_mask:0xf bound_ctrl:1
	v_add_f32_dpp v112, v112, v112 row_ror:8 row_mask:0xf bank_mask:0xf bound_ctrl:1
	ds_read_b128 v[38:41], v161 offset:4096
	ds_read_b128 v[42:45], v161 offset:36864
	v_pk_mul_f32 v[114:115], v[88:89], v[110:111] op_sel_hi:[1,0]
	v_pk_mul_f32 v[116:117], v[88:89], v[112:113] op_sel_hi:[1,0]
	v_pk_mul_f32 v[118:119], v[90:91], v[110:111] op_sel_hi:[1,0]
	v_pk_mul_f32 v[120:121], v[90:91], v[112:113] op_sel_hi:[1,0]
	v_pk_fma_f32 v[114:115], v[100:101], v[104:105], v[114:115] op_sel_hi:[1,0,1]
	v_pk_fma_f32 v[116:117], v[100:101], v[104:105], v[116:117] op_sel:[0,1,0]
	v_pk_fma_f32 v[118:119], v[102:103], v[104:105], v[118:119] op_sel_hi:[1,0,1]
	v_pk_fma_f32 v[120:121], v[102:103], v[104:105], v[120:121] op_sel:[0,1,0]
	v_pk_fma_f32 v[72:73], v[72:73], v[92:93], v[114:115]
	v_pk_fma_f32 v[76:77], v[76:77], v[92:93], v[116:117]
	v_pk_fma_f32 v[74:75], v[74:75], v[94:95], v[118:119]
	v_pk_fma_f32 v[78:79], v[78:79], v[94:95], v[120:121]
	v_pk_mul_f32 v[122:123], v[72:73], v[96:97]
	v_pk_mul_f32 v[124:125], v[76:77], v[96:97]
	v_pk_fma_f32 v[122:123], v[74:75], v[98:99], v[122:123]
	v_pk_fma_f32 v[124:125], v[78:79], v[98:99], v[124:125]
	v_add_f32_e32 v126, v122, v123
	v_add_f32_e32 v127, v124, v125
	ds_write_b64 v187, v[126:127] offset:30720
	s_waitcnt lgkmcnt(1)
	v_pk_mul_f32 v[106:107], v[72:73], v[30:31]
	v_pk_mul_f32 v[108:109], v[76:77], v[30:31]
	v_pk_fma_f32 v[106:107], v[74:75], v[32:33], v[106:107]
	v_pk_fma_f32 v[108:109], v[78:79], v[32:33], v[108:109]
	v_add_f32_e32 v110, v106, v107
	v_add_f32_e32 v112, v108, v109
	ds_read_b128 v[84:87], v161 offset:12544
	v_add_f32_dpp v110, v110, v110 quad_perm:[1,0,3,2] row_mask:0xf bank_mask:0xf bound_ctrl:1
	v_add_f32_dpp v112, v112, v112 quad_perm:[1,0,3,2] row_mask:0xf bank_mask:0xf bound_ctrl:1
	ds_read_b128 v[88:91], v161 offset:20736
	v_add_f32_dpp v110, v110, v110 quad_perm:[2,3,0,1] row_mask:0xf bank_mask:0xf bound_ctrl:1
	v_add_f32_dpp v112, v112, v112 quad_perm:[2,3,0,1] row_mask:0xf bank_mask:0xf bound_ctrl:1
	ds_read_b128 v[100:103], v161 offset:28928
	v_add_f32_dpp v110, v110, v110 row_half_mirror row_mask:0xf bank_mask:0xf bound_ctrl:1
	v_add_f32_dpp v112, v112, v112 row_half_mirror row_mask:0xf bank_mask:0xf bound_ctrl:1
	ds_read_b64 v[104:105], v82 offset:45312
	v_add_f32_dpp v110, v110, v110 row_ror:8 row_mask:0xf bank_mask:0xf bound_ctrl:1
	v_add_f32_dpp v112, v112, v112 row_ror:8 row_mask:0xf bank_mask:0xf bound_ctrl:1
	ds_read_b128 v[92:95], v161 offset:4352
	ds_read_b128 v[96:99], v161 offset:37120
	v_pk_mul_f32 v[114:115], v[34:35], v[110:111] op_sel_hi:[1,0]
	v_pk_mul_f32 v[116:117], v[34:35], v[112:113] op_sel_hi:[1,0]
	v_pk_mul_f32 v[118:119], v[36:37], v[110:111] op_sel_hi:[1,0]
	v_pk_mul_f32 v[120:121], v[36:37], v[112:113] op_sel_hi:[1,0]
	v_pk_fma_f32 v[114:115], v[46:47], v[80:81], v[114:115] op_sel_hi:[1,0,1]
	v_pk_fma_f32 v[116:117], v[46:47], v[80:81], v[116:117] op_sel:[0,1,0]
	v_pk_fma_f32 v[118:119], v[48:49], v[80:81], v[118:119] op_sel_hi:[1,0,1]
	v_pk_fma_f32 v[120:121], v[48:49], v[80:81], v[120:121] op_sel:[0,1,0]
	v_pk_fma_f32 v[72:73], v[72:73], v[38:39], v[114:115]
	v_pk_fma_f32 v[76:77], v[76:77], v[38:39], v[116:117]
	v_pk_fma_f32 v[74:75], v[74:75], v[40:41], v[118:119]
	v_pk_fma_f32 v[78:79], v[78:79], v[40:41], v[120:121]
	v_pk_mul_f32 v[122:123], v[72:73], v[42:43]
	v_pk_mul_f32 v[124:125], v[76:77], v[42:43]
	v_pk_fma_f32 v[122:123], v[74:75], v[44:45], v[122:123]
	v_pk_fma_f32 v[124:125], v[78:79], v[44:45], v[124:125]
	v_add_f32_e32 v126, v122, v123
	v_add_f32_e32 v127, v124, v125
	ds_write_b64 v187, v[126:127] offset:32768
	s_waitcnt lgkmcnt(1)
	v_pk_mul_f32 v[106:107], v[72:73], v[84:85]
	v_pk_mul_f32 v[108:109], v[76:77], v[84:85]
	v_pk_fma_f32 v[106:107], v[74:75], v[86:87], v[106:107]
	v_pk_fma_f32 v[108:109], v[78:79], v[86:87], v[108:109]
	v_add_f32_e32 v110, v106, v107
	v_add_f32_e32 v112, v108, v109
	ds_read_b128 v[30:33], v161 offset:12800
	v_add_f32_dpp v110, v110, v110 quad_perm:[1,0,3,2] row_mask:0xf bank_mask:0xf bound_ctrl:1
	v_add_f32_dpp v112, v112, v112 quad_perm:[1,0,3,2] row_mask:0xf bank_mask:0xf bound_ctrl:1
	ds_read_b128 v[34:37], v161 offset:20992
	v_add_f32_dpp v110, v110, v110 quad_perm:[2,3,0,1] row_mask:0xf bank_mask:0xf bound_ctrl:1
	v_add_f32_dpp v112, v112, v112 quad_perm:[2,3,0,1] row_mask:0xf bank_mask:0xf bound_ctrl:1
	ds_read_b128 v[46:49], v161 offset:29184
	v_add_f32_dpp v110, v110, v110 row_half_mirror row_mask:0xf bank_mask:0xf bound_ctrl:1
	v_add_f32_dpp v112, v112, v112 row_half_mirror row_mask:0xf bank_mask:0xf bound_ctrl:1
	ds_read_b64 v[80:81], v82 offset:45568
	v_add_f32_dpp v110, v110, v110 row_ror:8 row_mask:0xf bank_mask:0xf bound_ctrl:1
	v_add_f32_dpp v112, v112, v112 row_ror:8 row_mask:0xf bank_mask:0xf bound_ctrl:1
	ds_read_b128 v[38:41], v161 offset:4608
	ds_read_b128 v[42:45], v161 offset:37376
	v_pk_mul_f32 v[114:115], v[88:89], v[110:111] op_sel_hi:[1,0]
	v_pk_mul_f32 v[116:117], v[88:89], v[112:113] op_sel_hi:[1,0]
	v_pk_mul_f32 v[118:119], v[90:91], v[110:111] op_sel_hi:[1,0]
	v_pk_mul_f32 v[120:121], v[90:91], v[112:113] op_sel_hi:[1,0]
	v_pk_fma_f32 v[114:115], v[100:101], v[104:105], v[114:115] op_sel_hi:[1,0,1]
	v_pk_fma_f32 v[116:117], v[100:101], v[104:105], v[116:117] op_sel:[0,1,0]
	v_pk_fma_f32 v[118:119], v[102:103], v[104:105], v[118:119] op_sel_hi:[1,0,1]
	v_pk_fma_f32 v[120:121], v[102:103], v[104:105], v[120:121] op_sel:[0,1,0]
	v_pk_fma_f32 v[72:73], v[72:73], v[92:93], v[114:115]
	v_pk_fma_f32 v[76:77], v[76:77], v[92:93], v[116:117]
	v_pk_fma_f32 v[74:75], v[74:75], v[94:95], v[118:119]
	v_pk_fma_f32 v[78:79], v[78:79], v[94:95], v[120:121]
	v_pk_mul_f32 v[122:123], v[72:73], v[96:97]
	v_pk_mul_f32 v[124:125], v[76:77], v[96:97]
	v_pk_fma_f32 v[122:123], v[74:75], v[98:99], v[122:123]
	v_pk_fma_f32 v[124:125], v[78:79], v[98:99], v[124:125]
	v_add_f32_e32 v126, v122, v123
	v_add_f32_e32 v127, v124, v125
	ds_write_b64 v187, v[126:127] offset:34816
	s_waitcnt lgkmcnt(1)
	v_pk_mul_f32 v[106:107], v[72:73], v[30:31]
	v_pk_mul_f32 v[108:109], v[76:77], v[30:31]
	v_pk_fma_f32 v[106:107], v[74:75], v[32:33], v[106:107]
	v_pk_fma_f32 v[108:109], v[78:79], v[32:33], v[108:109]
	v_add_f32_e32 v110, v106, v107
	v_add_f32_e32 v112, v108, v109
	ds_read_b128 v[84:87], v161 offset:13056
	v_add_f32_dpp v110, v110, v110 quad_perm:[1,0,3,2] row_mask:0xf bank_mask:0xf bound_ctrl:1
	v_add_f32_dpp v112, v112, v112 quad_perm:[1,0,3,2] row_mask:0xf bank_mask:0xf bound_ctrl:1
	ds_read_b128 v[88:91], v161 offset:21248
	v_add_f32_dpp v110, v110, v110 quad_perm:[2,3,0,1] row_mask:0xf bank_mask:0xf bound_ctrl:1
	v_add_f32_dpp v112, v112, v112 quad_perm:[2,3,0,1] row_mask:0xf bank_mask:0xf bound_ctrl:1
	ds_read_b128 v[100:103], v161 offset:29440
	v_add_f32_dpp v110, v110, v110 row_half_mirror row_mask:0xf bank_mask:0xf bound_ctrl:1
	v_add_f32_dpp v112, v112, v112 row_half_mirror row_mask:0xf bank_mask:0xf bound_ctrl:1
	ds_read_b64 v[104:105], v82 offset:45824
	v_add_f32_dpp v110, v110, v110 row_ror:8 row_mask:0xf bank_mask:0xf bound_ctrl:1
	v_add_f32_dpp v112, v112, v112 row_ror:8 row_mask:0xf bank_mask:0xf bound_ctrl:1
	ds_read_b128 v[92:95], v161 offset:4864
	ds_read_b128 v[96:99], v161 offset:37632
	v_pk_mul_f32 v[114:115], v[34:35], v[110:111] op_sel_hi:[1,0]
	v_pk_mul_f32 v[116:117], v[34:35], v[112:113] op_sel_hi:[1,0]
	v_pk_mul_f32 v[118:119], v[36:37], v[110:111] op_sel_hi:[1,0]
	v_pk_mul_f32 v[120:121], v[36:37], v[112:113] op_sel_hi:[1,0]
	v_pk_fma_f32 v[114:115], v[46:47], v[80:81], v[114:115] op_sel_hi:[1,0,1]
	v_pk_fma_f32 v[116:117], v[46:47], v[80:81], v[116:117] op_sel:[0,1,0]
	v_pk_fma_f32 v[118:119], v[48:49], v[80:81], v[118:119] op_sel_hi:[1,0,1]
	v_pk_fma_f32 v[120:121], v[48:49], v[80:81], v[120:121] op_sel:[0,1,0]
	v_pk_fma_f32 v[72:73], v[72:73], v[38:39], v[114:115]
	v_pk_fma_f32 v[76:77], v[76:77], v[38:39], v[116:117]
	v_pk_fma_f32 v[74:75], v[74:75], v[40:41], v[118:119]
	v_pk_fma_f32 v[78:79], v[78:79], v[40:41], v[120:121]
	v_pk_mul_f32 v[122:123], v[72:73], v[42:43]
	v_pk_mul_f32 v[124:125], v[76:77], v[42:43]
	v_pk_fma_f32 v[122:123], v[74:75], v[44:45], v[122:123]
	v_pk_fma_f32 v[124:125], v[78:79], v[44:45], v[124:125]
	v_add_f32_e32 v126, v122, v123
	v_add_f32_e32 v127, v124, v125
	ds_write_b64 v187, v[126:127] offset:36864
	s_waitcnt lgkmcnt(1)
	v_pk_mul_f32 v[106:107], v[72:73], v[84:85]
	v_pk_mul_f32 v[108:109], v[76:77], v[84:85]
	v_pk_fma_f32 v[106:107], v[74:75], v[86:87], v[106:107]
	v_pk_fma_f32 v[108:109], v[78:79], v[86:87], v[108:109]
	v_add_f32_e32 v110, v106, v107
	v_add_f32_e32 v112, v108, v109
	ds_read_b128 v[30:33], v161 offset:13312
	v_add_f32_dpp v110, v110, v110 quad_perm:[1,0,3,2] row_mask:0xf bank_mask:0xf bound_ctrl:1
	v_add_f32_dpp v112, v112, v112 quad_perm:[1,0,3,2] row_mask:0xf bank_mask:0xf bound_ctrl:1
	ds_read_b128 v[34:37], v161 offset:21504
	v_add_f32_dpp v110, v110, v110 quad_perm:[2,3,0,1] row_mask:0xf bank_mask:0xf bound_ctrl:1
	v_add_f32_dpp v112, v112, v112 quad_perm:[2,3,0,1] row_mask:0xf bank_mask:0xf bound_ctrl:1
	ds_read_b128 v[46:49], v161 offset:29696
	v_add_f32_dpp v110, v110, v110 row_half_mirror row_mask:0xf bank_mask:0xf bound_ctrl:1
	v_add_f32_dpp v112, v112, v112 row_half_mirror row_mask:0xf bank_mask:0xf bound_ctrl:1
	ds_read_b64 v[80:81], v82 offset:46080
	v_add_f32_dpp v110, v110, v110 row_ror:8 row_mask:0xf bank_mask:0xf bound_ctrl:1
	v_add_f32_dpp v112, v112, v112 row_ror:8 row_mask:0xf bank_mask:0xf bound_ctrl:1
	ds_read_b128 v[38:41], v161 offset:5120
	ds_read_b128 v[42:45], v161 offset:37888
	v_pk_mul_f32 v[114:115], v[88:89], v[110:111] op_sel_hi:[1,0]
	v_pk_mul_f32 v[116:117], v[88:89], v[112:113] op_sel_hi:[1,0]
	v_pk_mul_f32 v[118:119], v[90:91], v[110:111] op_sel_hi:[1,0]
	v_pk_mul_f32 v[120:121], v[90:91], v[112:113] op_sel_hi:[1,0]
	v_pk_fma_f32 v[114:115], v[100:101], v[104:105], v[114:115] op_sel_hi:[1,0,1]
	v_pk_fma_f32 v[116:117], v[100:101], v[104:105], v[116:117] op_sel:[0,1,0]
	v_pk_fma_f32 v[118:119], v[102:103], v[104:105], v[118:119] op_sel_hi:[1,0,1]
	v_pk_fma_f32 v[120:121], v[102:103], v[104:105], v[120:121] op_sel:[0,1,0]
	v_pk_fma_f32 v[72:73], v[72:73], v[92:93], v[114:115]
	v_pk_fma_f32 v[76:77], v[76:77], v[92:93], v[116:117]
	v_pk_fma_f32 v[74:75], v[74:75], v[94:95], v[118:119]
	v_pk_fma_f32 v[78:79], v[78:79], v[94:95], v[120:121]
	v_pk_mul_f32 v[122:123], v[72:73], v[96:97]
	v_pk_mul_f32 v[124:125], v[76:77], v[96:97]
	v_pk_fma_f32 v[122:123], v[74:75], v[98:99], v[122:123]
	v_pk_fma_f32 v[124:125], v[78:79], v[98:99], v[124:125]
	v_add_f32_e32 v126, v122, v123
	v_add_f32_e32 v127, v124, v125
	ds_write_b64 v187, v[126:127] offset:38912
	s_waitcnt lgkmcnt(1)
	v_pk_mul_f32 v[106:107], v[72:73], v[30:31]
	v_pk_mul_f32 v[108:109], v[76:77], v[30:31]
	v_pk_fma_f32 v[106:107], v[74:75], v[32:33], v[106:107]
	v_pk_fma_f32 v[108:109], v[78:79], v[32:33], v[108:109]
	v_add_f32_e32 v110, v106, v107
	v_add_f32_e32 v112, v108, v109
	ds_read_b128 v[84:87], v161 offset:13568
	v_add_f32_dpp v110, v110, v110 quad_perm:[1,0,3,2] row_mask:0xf bank_mask:0xf bound_ctrl:1
	v_add_f32_dpp v112, v112, v112 quad_perm:[1,0,3,2] row_mask:0xf bank_mask:0xf bound_ctrl:1
	ds_read_b128 v[88:91], v161 offset:21760
	v_add_f32_dpp v110, v110, v110 quad_perm:[2,3,0,1] row_mask:0xf bank_mask:0xf bound_ctrl:1
	v_add_f32_dpp v112, v112, v112 quad_perm:[2,3,0,1] row_mask:0xf bank_mask:0xf bound_ctrl:1
	ds_read_b128 v[100:103], v161 offset:29952
	v_add_f32_dpp v110, v110, v110 row_half_mirror row_mask:0xf bank_mask:0xf bound_ctrl:1
	v_add_f32_dpp v112, v112, v112 row_half_mirror row_mask:0xf bank_mask:0xf bound_ctrl:1
	ds_read_b64 v[104:105], v82 offset:46336
	v_add_f32_dpp v110, v110, v110 row_ror:8 row_mask:0xf bank_mask:0xf bound_ctrl:1
	v_add_f32_dpp v112, v112, v112 row_ror:8 row_mask:0xf bank_mask:0xf bound_ctrl:1
	ds_read_b128 v[92:95], v161 offset:5376
	ds_read_b128 v[96:99], v161 offset:38144
	v_pk_mul_f32 v[114:115], v[34:35], v[110:111] op_sel_hi:[1,0]
	v_pk_mul_f32 v[116:117], v[34:35], v[112:113] op_sel_hi:[1,0]
	v_pk_mul_f32 v[118:119], v[36:37], v[110:111] op_sel_hi:[1,0]
	v_pk_mul_f32 v[120:121], v[36:37], v[112:113] op_sel_hi:[1,0]
	v_pk_fma_f32 v[114:115], v[46:47], v[80:81], v[114:115] op_sel_hi:[1,0,1]
	v_pk_fma_f32 v[116:117], v[46:47], v[80:81], v[116:117] op_sel:[0,1,0]
	v_pk_fma_f32 v[118:119], v[48:49], v[80:81], v[118:119] op_sel_hi:[1,0,1]
	v_pk_fma_f32 v[120:121], v[48:49], v[80:81], v[120:121] op_sel:[0,1,0]
	v_pk_fma_f32 v[72:73], v[72:73], v[38:39], v[114:115]
	v_pk_fma_f32 v[76:77], v[76:77], v[38:39], v[116:117]
	v_pk_fma_f32 v[74:75], v[74:75], v[40:41], v[118:119]
	v_pk_fma_f32 v[78:79], v[78:79], v[40:41], v[120:121]
	v_pk_mul_f32 v[122:123], v[72:73], v[42:43]
	v_pk_mul_f32 v[124:125], v[76:77], v[42:43]
	v_pk_fma_f32 v[122:123], v[74:75], v[44:45], v[122:123]
	v_pk_fma_f32 v[124:125], v[78:79], v[44:45], v[124:125]
	v_add_f32_e32 v126, v122, v123
	v_add_f32_e32 v127, v124, v125
	ds_write_b64 v187, v[126:127] offset:40960
	s_waitcnt lgkmcnt(1)
	v_pk_mul_f32 v[106:107], v[72:73], v[84:85]
	v_pk_mul_f32 v[108:109], v[76:77], v[84:85]
	v_pk_fma_f32 v[106:107], v[74:75], v[86:87], v[106:107]
	v_pk_fma_f32 v[108:109], v[78:79], v[86:87], v[108:109]
	v_add_f32_e32 v110, v106, v107
	v_add_f32_e32 v112, v108, v109
	ds_read_b128 v[30:33], v161 offset:13824
	v_add_f32_dpp v110, v110, v110 quad_perm:[1,0,3,2] row_mask:0xf bank_mask:0xf bound_ctrl:1
	v_add_f32_dpp v112, v112, v112 quad_perm:[1,0,3,2] row_mask:0xf bank_mask:0xf bound_ctrl:1
	ds_read_b128 v[34:37], v161 offset:22016
	v_add_f32_dpp v110, v110, v110 quad_perm:[2,3,0,1] row_mask:0xf bank_mask:0xf bound_ctrl:1
	v_add_f32_dpp v112, v112, v112 quad_perm:[2,3,0,1] row_mask:0xf bank_mask:0xf bound_ctrl:1
	ds_read_b128 v[46:49], v161 offset:30208
	v_add_f32_dpp v110, v110, v110 row_half_mirror row_mask:0xf bank_mask:0xf bound_ctrl:1
	v_add_f32_dpp v112, v112, v112 row_half_mirror row_mask:0xf bank_mask:0xf bound_ctrl:1
	ds_read_b64 v[80:81], v82 offset:46592
	v_add_f32_dpp v110, v110, v110 row_ror:8 row_mask:0xf bank_mask:0xf bound_ctrl:1
	v_add_f32_dpp v112, v112, v112 row_ror:8 row_mask:0xf bank_mask:0xf bound_ctrl:1
	ds_read_b128 v[38:41], v161 offset:5632
	ds_read_b128 v[42:45], v161 offset:38400
	v_pk_mul_f32 v[114:115], v[88:89], v[110:111] op_sel_hi:[1,0]
	v_pk_mul_f32 v[116:117], v[88:89], v[112:113] op_sel_hi:[1,0]
	v_pk_mul_f32 v[118:119], v[90:91], v[110:111] op_sel_hi:[1,0]
	v_pk_mul_f32 v[120:121], v[90:91], v[112:113] op_sel_hi:[1,0]
	v_pk_fma_f32 v[114:115], v[100:101], v[104:105], v[114:115] op_sel_hi:[1,0,1]
	v_pk_fma_f32 v[116:117], v[100:101], v[104:105], v[116:117] op_sel:[0,1,0]
	v_pk_fma_f32 v[118:119], v[102:103], v[104:105], v[118:119] op_sel_hi:[1,0,1]
	v_pk_fma_f32 v[120:121], v[102:103], v[104:105], v[120:121] op_sel:[0,1,0]
	v_pk_fma_f32 v[72:73], v[72:73], v[92:93], v[114:115]
	v_pk_fma_f32 v[76:77], v[76:77], v[92:93], v[116:117]
	v_pk_fma_f32 v[74:75], v[74:75], v[94:95], v[118:119]
	v_pk_fma_f32 v[78:79], v[78:79], v[94:95], v[120:121]
	v_pk_mul_f32 v[122:123], v[72:73], v[96:97]
	v_pk_mul_f32 v[124:125], v[76:77], v[96:97]
	v_pk_fma_f32 v[122:123], v[74:75], v[98:99], v[122:123]
	v_pk_fma_f32 v[124:125], v[78:79], v[98:99], v[124:125]
	v_add_f32_e32 v126, v122, v123
	v_add_f32_e32 v127, v124, v125
	ds_write_b64 v187, v[126:127] offset:43008
	s_waitcnt lgkmcnt(1)
	v_pk_mul_f32 v[106:107], v[72:73], v[30:31]
	v_pk_mul_f32 v[108:109], v[76:77], v[30:31]
	v_pk_fma_f32 v[106:107], v[74:75], v[32:33], v[106:107]
	v_pk_fma_f32 v[108:109], v[78:79], v[32:33], v[108:109]
	v_add_f32_e32 v110, v106, v107
	v_add_f32_e32 v112, v108, v109
	ds_read_b128 v[84:87], v161 offset:14080
	v_add_f32_dpp v110, v110, v110 quad_perm:[1,0,3,2] row_mask:0xf bank_mask:0xf bound_ctrl:1
	v_add_f32_dpp v112, v112, v112 quad_perm:[1,0,3,2] row_mask:0xf bank_mask:0xf bound_ctrl:1
	ds_read_b128 v[88:91], v161 offset:22272
	v_add_f32_dpp v110, v110, v110 quad_perm:[2,3,0,1] row_mask:0xf bank_mask:0xf bound_ctrl:1
	v_add_f32_dpp v112, v112, v112 quad_perm:[2,3,0,1] row_mask:0xf bank_mask:0xf bound_ctrl:1
	ds_read_b128 v[100:103], v161 offset:30464
	v_add_f32_dpp v110, v110, v110 row_half_mirror row_mask:0xf bank_mask:0xf bound_ctrl:1
	v_add_f32_dpp v112, v112, v112 row_half_mirror row_mask:0xf bank_mask:0xf bound_ctrl:1
	ds_read_b64 v[104:105], v82 offset:46848
	v_add_f32_dpp v110, v110, v110 row_ror:8 row_mask:0xf bank_mask:0xf bound_ctrl:1
	v_add_f32_dpp v112, v112, v112 row_ror:8 row_mask:0xf bank_mask:0xf bound_ctrl:1
	ds_read_b128 v[92:95], v161 offset:5888
	ds_read_b128 v[96:99], v161 offset:38656
	v_pk_mul_f32 v[114:115], v[34:35], v[110:111] op_sel_hi:[1,0]
	v_pk_mul_f32 v[116:117], v[34:35], v[112:113] op_sel_hi:[1,0]
	v_pk_mul_f32 v[118:119], v[36:37], v[110:111] op_sel_hi:[1,0]
	v_pk_mul_f32 v[120:121], v[36:37], v[112:113] op_sel_hi:[1,0]
	v_pk_fma_f32 v[114:115], v[46:47], v[80:81], v[114:115] op_sel_hi:[1,0,1]
	v_pk_fma_f32 v[116:117], v[46:47], v[80:81], v[116:117] op_sel:[0,1,0]
	v_pk_fma_f32 v[118:119], v[48:49], v[80:81], v[118:119] op_sel_hi:[1,0,1]
	v_pk_fma_f32 v[120:121], v[48:49], v[80:81], v[120:121] op_sel:[0,1,0]
	v_pk_fma_f32 v[72:73], v[72:73], v[38:39], v[114:115]
	v_pk_fma_f32 v[76:77], v[76:77], v[38:39], v[116:117]
	v_pk_fma_f32 v[74:75], v[74:75], v[40:41], v[118:119]
	v_pk_fma_f32 v[78:79], v[78:79], v[40:41], v[120:121]
	v_pk_mul_f32 v[122:123], v[72:73], v[42:43]
	v_pk_mul_f32 v[124:125], v[76:77], v[42:43]
	v_pk_fma_f32 v[122:123], v[74:75], v[44:45], v[122:123]
	v_pk_fma_f32 v[124:125], v[78:79], v[44:45], v[124:125]
	v_add_f32_e32 v126, v122, v123
	v_add_f32_e32 v127, v124, v125
	ds_write_b64 v187, v[126:127] offset:45056
	s_waitcnt lgkmcnt(1)
	v_pk_mul_f32 v[106:107], v[72:73], v[84:85]
	v_pk_mul_f32 v[108:109], v[76:77], v[84:85]
	v_pk_fma_f32 v[106:107], v[74:75], v[86:87], v[106:107]
	v_pk_fma_f32 v[108:109], v[78:79], v[86:87], v[108:109]
	v_add_f32_e32 v110, v106, v107
	v_add_f32_e32 v112, v108, v109
	ds_read_b128 v[30:33], v161 offset:14336
	v_add_f32_dpp v110, v110, v110 quad_perm:[1,0,3,2] row_mask:0xf bank_mask:0xf bound_ctrl:1
	v_add_f32_dpp v112, v112, v112 quad_perm:[1,0,3,2] row_mask:0xf bank_mask:0xf bound_ctrl:1
	ds_read_b128 v[34:37], v161 offset:22528
	v_add_f32_dpp v110, v110, v110 quad_perm:[2,3,0,1] row_mask:0xf bank_mask:0xf bound_ctrl:1
	v_add_f32_dpp v112, v112, v112 quad_perm:[2,3,0,1] row_mask:0xf bank_mask:0xf bound_ctrl:1
	ds_read_b128 v[46:49], v161 offset:30720
	v_add_f32_dpp v110, v110, v110 row_half_mirror row_mask:0xf bank_mask:0xf bound_ctrl:1
	v_add_f32_dpp v112, v112, v112 row_half_mirror row_mask:0xf bank_mask:0xf bound_ctrl:1
	ds_read_b64 v[80:81], v82 offset:47104
	v_add_f32_dpp v110, v110, v110 row_ror:8 row_mask:0xf bank_mask:0xf bound_ctrl:1
	v_add_f32_dpp v112, v112, v112 row_ror:8 row_mask:0xf bank_mask:0xf bound_ctrl:1
	ds_read_b128 v[38:41], v161 offset:6144
	ds_read_b128 v[42:45], v161 offset:38912
	v_pk_mul_f32 v[114:115], v[88:89], v[110:111] op_sel_hi:[1,0]
	v_pk_mul_f32 v[116:117], v[88:89], v[112:113] op_sel_hi:[1,0]
	v_pk_mul_f32 v[118:119], v[90:91], v[110:111] op_sel_hi:[1,0]
	v_pk_mul_f32 v[120:121], v[90:91], v[112:113] op_sel_hi:[1,0]
	v_pk_fma_f32 v[114:115], v[100:101], v[104:105], v[114:115] op_sel_hi:[1,0,1]
	v_pk_fma_f32 v[116:117], v[100:101], v[104:105], v[116:117] op_sel:[0,1,0]
	v_pk_fma_f32 v[118:119], v[102:103], v[104:105], v[118:119] op_sel_hi:[1,0,1]
	v_pk_fma_f32 v[120:121], v[102:103], v[104:105], v[120:121] op_sel:[0,1,0]
	v_pk_fma_f32 v[72:73], v[72:73], v[92:93], v[114:115]
	v_pk_fma_f32 v[76:77], v[76:77], v[92:93], v[116:117]
	v_pk_fma_f32 v[74:75], v[74:75], v[94:95], v[118:119]
	v_pk_fma_f32 v[78:79], v[78:79], v[94:95], v[120:121]
	v_pk_mul_f32 v[122:123], v[72:73], v[96:97]
	v_pk_mul_f32 v[124:125], v[76:77], v[96:97]
	v_pk_fma_f32 v[122:123], v[74:75], v[98:99], v[122:123]
	v_pk_fma_f32 v[124:125], v[78:79], v[98:99], v[124:125]
	v_add_f32_e32 v126, v122, v123
	v_add_f32_e32 v127, v124, v125
	ds_write_b64 v187, v[126:127] offset:47104
	s_waitcnt lgkmcnt(1)
	v_pk_mul_f32 v[106:107], v[72:73], v[30:31]
	v_pk_mul_f32 v[108:109], v[76:77], v[30:31]
	v_pk_fma_f32 v[106:107], v[74:75], v[32:33], v[106:107]
	v_pk_fma_f32 v[108:109], v[78:79], v[32:33], v[108:109]
	v_add_f32_e32 v110, v106, v107
	v_add_f32_e32 v112, v108, v109
	ds_read_b128 v[84:87], v161 offset:14592
	v_add_f32_dpp v110, v110, v110 quad_perm:[1,0,3,2] row_mask:0xf bank_mask:0xf bound_ctrl:1
	v_add_f32_dpp v112, v112, v112 quad_perm:[1,0,3,2] row_mask:0xf bank_mask:0xf bound_ctrl:1
	ds_read_b128 v[88:91], v161 offset:22784
	v_add_f32_dpp v110, v110, v110 quad_perm:[2,3,0,1] row_mask:0xf bank_mask:0xf bound_ctrl:1
	v_add_f32_dpp v112, v112, v112 quad_perm:[2,3,0,1] row_mask:0xf bank_mask:0xf bound_ctrl:1
	ds_read_b128 v[100:103], v161 offset:30976
	v_add_f32_dpp v110, v110, v110 row_half_mirror row_mask:0xf bank_mask:0xf bound_ctrl:1
	v_add_f32_dpp v112, v112, v112 row_half_mirror row_mask:0xf bank_mask:0xf bound_ctrl:1
	ds_read_b64 v[104:105], v82 offset:47360
	v_add_f32_dpp v110, v110, v110 row_ror:8 row_mask:0xf bank_mask:0xf bound_ctrl:1
	v_add_f32_dpp v112, v112, v112 row_ror:8 row_mask:0xf bank_mask:0xf bound_ctrl:1
	ds_read_b128 v[92:95], v161 offset:6400
	ds_read_b128 v[96:99], v161 offset:39168
	v_pk_mul_f32 v[114:115], v[34:35], v[110:111] op_sel_hi:[1,0]
	v_pk_mul_f32 v[116:117], v[34:35], v[112:113] op_sel_hi:[1,0]
	v_pk_mul_f32 v[118:119], v[36:37], v[110:111] op_sel_hi:[1,0]
	v_pk_mul_f32 v[120:121], v[36:37], v[112:113] op_sel_hi:[1,0]
	v_pk_fma_f32 v[114:115], v[46:47], v[80:81], v[114:115] op_sel_hi:[1,0,1]
	v_pk_fma_f32 v[116:117], v[46:47], v[80:81], v[116:117] op_sel:[0,1,0]
	v_pk_fma_f32 v[118:119], v[48:49], v[80:81], v[118:119] op_sel_hi:[1,0,1]
	v_pk_fma_f32 v[120:121], v[48:49], v[80:81], v[120:121] op_sel:[0,1,0]
	v_pk_fma_f32 v[72:73], v[72:73], v[38:39], v[114:115]
	v_pk_fma_f32 v[76:77], v[76:77], v[38:39], v[116:117]
	v_pk_fma_f32 v[74:75], v[74:75], v[40:41], v[118:119]
	v_pk_fma_f32 v[78:79], v[78:79], v[40:41], v[120:121]
	v_pk_mul_f32 v[122:123], v[72:73], v[42:43]
	v_pk_mul_f32 v[124:125], v[76:77], v[42:43]
	v_pk_fma_f32 v[122:123], v[74:75], v[44:45], v[122:123]
	v_pk_fma_f32 v[124:125], v[78:79], v[44:45], v[124:125]
	v_add_f32_e32 v126, v122, v123
	v_add_f32_e32 v127, v124, v125
	ds_write_b64 v187, v[126:127] offset:49152
	s_waitcnt lgkmcnt(1)
	v_pk_mul_f32 v[106:107], v[72:73], v[84:85]
	v_pk_mul_f32 v[108:109], v[76:77], v[84:85]
	v_pk_fma_f32 v[106:107], v[74:75], v[86:87], v[106:107]
	v_pk_fma_f32 v[108:109], v[78:79], v[86:87], v[108:109]
	v_add_f32_e32 v110, v106, v107
	v_add_f32_e32 v112, v108, v109
	ds_read_b128 v[30:33], v161 offset:14848
	v_add_f32_dpp v110, v110, v110 quad_perm:[1,0,3,2] row_mask:0xf bank_mask:0xf bound_ctrl:1
	v_add_f32_dpp v112, v112, v112 quad_perm:[1,0,3,2] row_mask:0xf bank_mask:0xf bound_ctrl:1
	ds_read_b128 v[34:37], v161 offset:23040
	v_add_f32_dpp v110, v110, v110 quad_perm:[2,3,0,1] row_mask:0xf bank_mask:0xf bound_ctrl:1
	v_add_f32_dpp v112, v112, v112 quad_perm:[2,3,0,1] row_mask:0xf bank_mask:0xf bound_ctrl:1
	ds_read_b128 v[46:49], v161 offset:31232
	v_add_f32_dpp v110, v110, v110 row_half_mirror row_mask:0xf bank_mask:0xf bound_ctrl:1
	v_add_f32_dpp v112, v112, v112 row_half_mirror row_mask:0xf bank_mask:0xf bound_ctrl:1
	ds_read_b64 v[80:81], v82 offset:47616
	v_add_f32_dpp v110, v110, v110 row_ror:8 row_mask:0xf bank_mask:0xf bound_ctrl:1
	v_add_f32_dpp v112, v112, v112 row_ror:8 row_mask:0xf bank_mask:0xf bound_ctrl:1
	ds_read_b128 v[38:41], v161 offset:6656
	ds_read_b128 v[42:45], v161 offset:39424
	v_pk_mul_f32 v[114:115], v[88:89], v[110:111] op_sel_hi:[1,0]
	v_pk_mul_f32 v[116:117], v[88:89], v[112:113] op_sel_hi:[1,0]
	v_pk_mul_f32 v[118:119], v[90:91], v[110:111] op_sel_hi:[1,0]
	v_pk_mul_f32 v[120:121], v[90:91], v[112:113] op_sel_hi:[1,0]
	v_pk_fma_f32 v[114:115], v[100:101], v[104:105], v[114:115] op_sel_hi:[1,0,1]
	v_pk_fma_f32 v[116:117], v[100:101], v[104:105], v[116:117] op_sel:[0,1,0]
	v_pk_fma_f32 v[118:119], v[102:103], v[104:105], v[118:119] op_sel_hi:[1,0,1]
	v_pk_fma_f32 v[120:121], v[102:103], v[104:105], v[120:121] op_sel:[0,1,0]
	v_pk_fma_f32 v[72:73], v[72:73], v[92:93], v[114:115]
	v_pk_fma_f32 v[76:77], v[76:77], v[92:93], v[116:117]
	v_pk_fma_f32 v[74:75], v[74:75], v[94:95], v[118:119]
	v_pk_fma_f32 v[78:79], v[78:79], v[94:95], v[120:121]
	v_pk_mul_f32 v[122:123], v[72:73], v[96:97]
	v_pk_mul_f32 v[124:125], v[76:77], v[96:97]
	v_pk_fma_f32 v[122:123], v[74:75], v[98:99], v[122:123]
	v_pk_fma_f32 v[124:125], v[78:79], v[98:99], v[124:125]
	v_add_f32_e32 v126, v122, v123
	v_add_f32_e32 v127, v124, v125
	ds_write_b64 v187, v[126:127] offset:51200
	s_waitcnt lgkmcnt(1)
	v_pk_mul_f32 v[106:107], v[72:73], v[30:31]
	v_pk_mul_f32 v[108:109], v[76:77], v[30:31]
	v_pk_fma_f32 v[106:107], v[74:75], v[32:33], v[106:107]
	v_pk_fma_f32 v[108:109], v[78:79], v[32:33], v[108:109]
	v_add_f32_e32 v110, v106, v107
	v_add_f32_e32 v112, v108, v109
	ds_read_b128 v[84:87], v161 offset:15104
	v_add_f32_dpp v110, v110, v110 quad_perm:[1,0,3,2] row_mask:0xf bank_mask:0xf bound_ctrl:1
	v_add_f32_dpp v112, v112, v112 quad_perm:[1,0,3,2] row_mask:0xf bank_mask:0xf bound_ctrl:1
	ds_read_b128 v[88:91], v161 offset:23296
	v_add_f32_dpp v110, v110, v110 quad_perm:[2,3,0,1] row_mask:0xf bank_mask:0xf bound_ctrl:1
	v_add_f32_dpp v112, v112, v112 quad_perm:[2,3,0,1] row_mask:0xf bank_mask:0xf bound_ctrl:1
	ds_read_b128 v[100:103], v161 offset:31488
	v_add_f32_dpp v110, v110, v110 row_half_mirror row_mask:0xf bank_mask:0xf bound_ctrl:1
	v_add_f32_dpp v112, v112, v112 row_half_mirror row_mask:0xf bank_mask:0xf bound_ctrl:1
	ds_read_b64 v[104:105], v82 offset:47872
	v_add_f32_dpp v110, v110, v110 row_ror:8 row_mask:0xf bank_mask:0xf bound_ctrl:1
	v_add_f32_dpp v112, v112, v112 row_ror:8 row_mask:0xf bank_mask:0xf bound_ctrl:1
	ds_read_b128 v[92:95], v161 offset:6912
	ds_read_b128 v[96:99], v161 offset:39680
	v_pk_mul_f32 v[114:115], v[34:35], v[110:111] op_sel_hi:[1,0]
	v_pk_mul_f32 v[116:117], v[34:35], v[112:113] op_sel_hi:[1,0]
	v_pk_mul_f32 v[118:119], v[36:37], v[110:111] op_sel_hi:[1,0]
	v_pk_mul_f32 v[120:121], v[36:37], v[112:113] op_sel_hi:[1,0]
	v_pk_fma_f32 v[114:115], v[46:47], v[80:81], v[114:115] op_sel_hi:[1,0,1]
	v_pk_fma_f32 v[116:117], v[46:47], v[80:81], v[116:117] op_sel:[0,1,0]
	v_pk_fma_f32 v[118:119], v[48:49], v[80:81], v[118:119] op_sel_hi:[1,0,1]
	v_pk_fma_f32 v[120:121], v[48:49], v[80:81], v[120:121] op_sel:[0,1,0]
	v_pk_fma_f32 v[72:73], v[72:73], v[38:39], v[114:115]
	v_pk_fma_f32 v[76:77], v[76:77], v[38:39], v[116:117]
	v_pk_fma_f32 v[74:75], v[74:75], v[40:41], v[118:119]
	v_pk_fma_f32 v[78:79], v[78:79], v[40:41], v[120:121]
	v_pk_mul_f32 v[122:123], v[72:73], v[42:43]
	v_pk_mul_f32 v[124:125], v[76:77], v[42:43]
	v_pk_fma_f32 v[122:123], v[74:75], v[44:45], v[122:123]
	v_pk_fma_f32 v[124:125], v[78:79], v[44:45], v[124:125]
	v_add_f32_e32 v126, v122, v123
	v_add_f32_e32 v127, v124, v125
	ds_write_b64 v187, v[126:127] offset:53248
	s_waitcnt lgkmcnt(1)
	v_pk_mul_f32 v[106:107], v[72:73], v[84:85]
	v_pk_mul_f32 v[108:109], v[76:77], v[84:85]
	v_pk_fma_f32 v[106:107], v[74:75], v[86:87], v[106:107]
	v_pk_fma_f32 v[108:109], v[78:79], v[86:87], v[108:109]
	v_add_f32_e32 v110, v106, v107
	v_add_f32_e32 v112, v108, v109
	ds_read_b128 v[30:33], v161 offset:15360
	v_add_f32_dpp v110, v110, v110 quad_perm:[1,0,3,2] row_mask:0xf bank_mask:0xf bound_ctrl:1
	v_add_f32_dpp v112, v112, v112 quad_perm:[1,0,3,2] row_mask:0xf bank_mask:0xf bound_ctrl:1
	ds_read_b128 v[34:37], v161 offset:23552
	v_add_f32_dpp v110, v110, v110 quad_perm:[2,3,0,1] row_mask:0xf bank_mask:0xf bound_ctrl:1
	v_add_f32_dpp v112, v112, v112 quad_perm:[2,3,0,1] row_mask:0xf bank_mask:0xf bound_ctrl:1
	ds_read_b128 v[46:49], v161 offset:31744
	v_add_f32_dpp v110, v110, v110 row_half_mirror row_mask:0xf bank_mask:0xf bound_ctrl:1
	v_add_f32_dpp v112, v112, v112 row_half_mirror row_mask:0xf bank_mask:0xf bound_ctrl:1
	ds_read_b64 v[80:81], v82 offset:48128
	v_add_f32_dpp v110, v110, v110 row_ror:8 row_mask:0xf bank_mask:0xf bound_ctrl:1
	v_add_f32_dpp v112, v112, v112 row_ror:8 row_mask:0xf bank_mask:0xf bound_ctrl:1
	ds_read_b128 v[38:41], v161 offset:7168
	ds_read_b128 v[42:45], v161 offset:39936
	v_pk_mul_f32 v[114:115], v[88:89], v[110:111] op_sel_hi:[1,0]
	v_pk_mul_f32 v[116:117], v[88:89], v[112:113] op_sel_hi:[1,0]
	v_pk_mul_f32 v[118:119], v[90:91], v[110:111] op_sel_hi:[1,0]
	v_pk_mul_f32 v[120:121], v[90:91], v[112:113] op_sel_hi:[1,0]
	v_pk_fma_f32 v[114:115], v[100:101], v[104:105], v[114:115] op_sel_hi:[1,0,1]
	v_pk_fma_f32 v[116:117], v[100:101], v[104:105], v[116:117] op_sel:[0,1,0]
	v_pk_fma_f32 v[118:119], v[102:103], v[104:105], v[118:119] op_sel_hi:[1,0,1]
	v_pk_fma_f32 v[120:121], v[102:103], v[104:105], v[120:121] op_sel:[0,1,0]
	v_pk_fma_f32 v[72:73], v[72:73], v[92:93], v[114:115]
	v_pk_fma_f32 v[76:77], v[76:77], v[92:93], v[116:117]
	v_pk_fma_f32 v[74:75], v[74:75], v[94:95], v[118:119]
	v_pk_fma_f32 v[78:79], v[78:79], v[94:95], v[120:121]
	v_pk_mul_f32 v[122:123], v[72:73], v[96:97]
	v_pk_mul_f32 v[124:125], v[76:77], v[96:97]
	v_pk_fma_f32 v[122:123], v[74:75], v[98:99], v[122:123]
	v_pk_fma_f32 v[124:125], v[78:79], v[98:99], v[124:125]
	v_add_f32_e32 v126, v122, v123
	v_add_f32_e32 v127, v124, v125
	ds_write_b64 v187, v[126:127] offset:55296
	s_waitcnt lgkmcnt(1)
	v_pk_mul_f32 v[106:107], v[72:73], v[30:31]
	v_pk_mul_f32 v[108:109], v[76:77], v[30:31]
	v_pk_fma_f32 v[106:107], v[74:75], v[32:33], v[106:107]
	v_pk_fma_f32 v[108:109], v[78:79], v[32:33], v[108:109]
	v_add_f32_e32 v110, v106, v107
	v_add_f32_e32 v112, v108, v109
	ds_read_b128 v[84:87], v161 offset:15616
	v_add_f32_dpp v110, v110, v110 quad_perm:[1,0,3,2] row_mask:0xf bank_mask:0xf bound_ctrl:1
	v_add_f32_dpp v112, v112, v112 quad_perm:[1,0,3,2] row_mask:0xf bank_mask:0xf bound_ctrl:1
	ds_read_b128 v[88:91], v161 offset:23808
	v_add_f32_dpp v110, v110, v110 quad_perm:[2,3,0,1] row_mask:0xf bank_mask:0xf bound_ctrl:1
	v_add_f32_dpp v112, v112, v112 quad_perm:[2,3,0,1] row_mask:0xf bank_mask:0xf bound_ctrl:1
	ds_read_b128 v[100:103], v161 offset:32000
	v_add_f32_dpp v110, v110, v110 row_half_mirror row_mask:0xf bank_mask:0xf bound_ctrl:1
	v_add_f32_dpp v112, v112, v112 row_half_mirror row_mask:0xf bank_mask:0xf bound_ctrl:1
	ds_read_b64 v[104:105], v82 offset:48384
	v_add_f32_dpp v110, v110, v110 row_ror:8 row_mask:0xf bank_mask:0xf bound_ctrl:1
	v_add_f32_dpp v112, v112, v112 row_ror:8 row_mask:0xf bank_mask:0xf bound_ctrl:1
	ds_read_b128 v[92:95], v161 offset:7424
	ds_read_b128 v[96:99], v161 offset:40192
	v_pk_mul_f32 v[114:115], v[34:35], v[110:111] op_sel_hi:[1,0]
	v_pk_mul_f32 v[116:117], v[34:35], v[112:113] op_sel_hi:[1,0]
	v_pk_mul_f32 v[118:119], v[36:37], v[110:111] op_sel_hi:[1,0]
	v_pk_mul_f32 v[120:121], v[36:37], v[112:113] op_sel_hi:[1,0]
	v_pk_fma_f32 v[114:115], v[46:47], v[80:81], v[114:115] op_sel_hi:[1,0,1]
	v_pk_fma_f32 v[116:117], v[46:47], v[80:81], v[116:117] op_sel:[0,1,0]
	v_pk_fma_f32 v[118:119], v[48:49], v[80:81], v[118:119] op_sel_hi:[1,0,1]
	v_pk_fma_f32 v[120:121], v[48:49], v[80:81], v[120:121] op_sel:[0,1,0]
	v_pk_fma_f32 v[72:73], v[72:73], v[38:39], v[114:115]
	v_pk_fma_f32 v[76:77], v[76:77], v[38:39], v[116:117]
	v_pk_fma_f32 v[74:75], v[74:75], v[40:41], v[118:119]
	v_pk_fma_f32 v[78:79], v[78:79], v[40:41], v[120:121]
	v_pk_mul_f32 v[122:123], v[72:73], v[42:43]
	v_pk_mul_f32 v[124:125], v[76:77], v[42:43]
	v_pk_fma_f32 v[122:123], v[74:75], v[44:45], v[122:123]
	v_pk_fma_f32 v[124:125], v[78:79], v[44:45], v[124:125]
	v_add_f32_e32 v126, v122, v123
	v_add_f32_e32 v127, v124, v125
	ds_write_b64 v187, v[126:127] offset:57344
	s_waitcnt lgkmcnt(1)
	v_pk_mul_f32 v[106:107], v[72:73], v[84:85]
	v_pk_mul_f32 v[108:109], v[76:77], v[84:85]
	v_pk_fma_f32 v[106:107], v[74:75], v[86:87], v[106:107]
	v_pk_fma_f32 v[108:109], v[78:79], v[86:87], v[108:109]
	v_add_f32_e32 v110, v106, v107
	v_add_f32_e32 v112, v108, v109
	ds_read_b128 v[30:33], v161 offset:15872
	v_add_f32_dpp v110, v110, v110 quad_perm:[1,0,3,2] row_mask:0xf bank_mask:0xf bound_ctrl:1
	v_add_f32_dpp v112, v112, v112 quad_perm:[1,0,3,2] row_mask:0xf bank_mask:0xf bound_ctrl:1
	ds_read_b128 v[34:37], v161 offset:24064
	v_add_f32_dpp v110, v110, v110 quad_perm:[2,3,0,1] row_mask:0xf bank_mask:0xf bound_ctrl:1
	v_add_f32_dpp v112, v112, v112 quad_perm:[2,3,0,1] row_mask:0xf bank_mask:0xf bound_ctrl:1
	ds_read_b128 v[46:49], v161 offset:32256
	v_add_f32_dpp v110, v110, v110 row_half_mirror row_mask:0xf bank_mask:0xf bound_ctrl:1
	v_add_f32_dpp v112, v112, v112 row_half_mirror row_mask:0xf bank_mask:0xf bound_ctrl:1
	ds_read_b64 v[80:81], v82 offset:48640
	v_add_f32_dpp v110, v110, v110 row_ror:8 row_mask:0xf bank_mask:0xf bound_ctrl:1
	v_add_f32_dpp v112, v112, v112 row_ror:8 row_mask:0xf bank_mask:0xf bound_ctrl:1
	ds_read_b128 v[38:41], v161 offset:7680
	ds_read_b128 v[42:45], v161 offset:40448
	v_pk_mul_f32 v[114:115], v[88:89], v[110:111] op_sel_hi:[1,0]
	v_pk_mul_f32 v[116:117], v[88:89], v[112:113] op_sel_hi:[1,0]
	v_pk_mul_f32 v[118:119], v[90:91], v[110:111] op_sel_hi:[1,0]
	v_pk_mul_f32 v[120:121], v[90:91], v[112:113] op_sel_hi:[1,0]
	v_pk_fma_f32 v[114:115], v[100:101], v[104:105], v[114:115] op_sel_hi:[1,0,1]
	v_pk_fma_f32 v[116:117], v[100:101], v[104:105], v[116:117] op_sel:[0,1,0]
	v_pk_fma_f32 v[118:119], v[102:103], v[104:105], v[118:119] op_sel_hi:[1,0,1]
	v_pk_fma_f32 v[120:121], v[102:103], v[104:105], v[120:121] op_sel:[0,1,0]
	v_pk_fma_f32 v[72:73], v[72:73], v[92:93], v[114:115]
	v_pk_fma_f32 v[76:77], v[76:77], v[92:93], v[116:117]
	v_pk_fma_f32 v[74:75], v[74:75], v[94:95], v[118:119]
	v_pk_fma_f32 v[78:79], v[78:79], v[94:95], v[120:121]
	v_pk_mul_f32 v[122:123], v[72:73], v[96:97]
	v_pk_mul_f32 v[124:125], v[76:77], v[96:97]
	v_pk_fma_f32 v[122:123], v[74:75], v[98:99], v[122:123]
	v_pk_fma_f32 v[124:125], v[78:79], v[98:99], v[124:125]
	v_add_f32_e32 v126, v122, v123
	v_add_f32_e32 v127, v124, v125
	ds_write_b64 v187, v[126:127] offset:59392
	s_waitcnt lgkmcnt(1)
	v_pk_mul_f32 v[106:107], v[72:73], v[30:31]
	v_pk_mul_f32 v[108:109], v[76:77], v[30:31]
	v_pk_fma_f32 v[106:107], v[74:75], v[32:33], v[106:107]
	v_pk_fma_f32 v[108:109], v[78:79], v[32:33], v[108:109]
	v_add_f32_e32 v110, v106, v107
	v_add_f32_e32 v112, v108, v109
	ds_read_b128 v[84:87], v161 offset:16128
	v_add_f32_dpp v110, v110, v110 quad_perm:[1,0,3,2] row_mask:0xf bank_mask:0xf bound_ctrl:1
	v_add_f32_dpp v112, v112, v112 quad_perm:[1,0,3,2] row_mask:0xf bank_mask:0xf bound_ctrl:1
	ds_read_b128 v[88:91], v161 offset:24320
	v_add_f32_dpp v110, v110, v110 quad_perm:[2,3,0,1] row_mask:0xf bank_mask:0xf bound_ctrl:1
	v_add_f32_dpp v112, v112, v112 quad_perm:[2,3,0,1] row_mask:0xf bank_mask:0xf bound_ctrl:1
	ds_read_b128 v[100:103], v161 offset:32512
	v_add_f32_dpp v110, v110, v110 row_half_mirror row_mask:0xf bank_mask:0xf bound_ctrl:1
	v_add_f32_dpp v112, v112, v112 row_half_mirror row_mask:0xf bank_mask:0xf bound_ctrl:1
	ds_read_b64 v[104:105], v82 offset:48896
	v_add_f32_dpp v110, v110, v110 row_ror:8 row_mask:0xf bank_mask:0xf bound_ctrl:1
	v_add_f32_dpp v112, v112, v112 row_ror:8 row_mask:0xf bank_mask:0xf bound_ctrl:1
	ds_read_b128 v[92:95], v161 offset:7936
	ds_read_b128 v[96:99], v161 offset:40704
	v_pk_mul_f32 v[114:115], v[34:35], v[110:111] op_sel_hi:[1,0]
	v_pk_mul_f32 v[116:117], v[34:35], v[112:113] op_sel_hi:[1,0]
	v_pk_mul_f32 v[118:119], v[36:37], v[110:111] op_sel_hi:[1,0]
	v_pk_mul_f32 v[120:121], v[36:37], v[112:113] op_sel_hi:[1,0]
	v_pk_fma_f32 v[114:115], v[46:47], v[80:81], v[114:115] op_sel_hi:[1,0,1]
	v_pk_fma_f32 v[116:117], v[46:47], v[80:81], v[116:117] op_sel:[0,1,0]
	v_pk_fma_f32 v[118:119], v[48:49], v[80:81], v[118:119] op_sel_hi:[1,0,1]
	v_pk_fma_f32 v[120:121], v[48:49], v[80:81], v[120:121] op_sel:[0,1,0]
	v_pk_fma_f32 v[72:73], v[72:73], v[38:39], v[114:115]
	v_pk_fma_f32 v[76:77], v[76:77], v[38:39], v[116:117]
	v_pk_fma_f32 v[74:75], v[74:75], v[40:41], v[118:119]
	v_pk_fma_f32 v[78:79], v[78:79], v[40:41], v[120:121]
	v_pk_mul_f32 v[122:123], v[72:73], v[42:43]
	v_pk_mul_f32 v[124:125], v[76:77], v[42:43]
	v_pk_fma_f32 v[122:123], v[74:75], v[44:45], v[122:123]
	v_pk_fma_f32 v[124:125], v[78:79], v[44:45], v[124:125]
	v_add_f32_e32 v126, v122, v123
	v_add_f32_e32 v127, v124, v125
	ds_write_b64 v187, v[126:127] offset:61440
	s_waitcnt lgkmcnt(1)
	v_pk_mul_f32 v[106:107], v[72:73], v[84:85]
	v_pk_mul_f32 v[108:109], v[76:77], v[84:85]
	v_pk_fma_f32 v[106:107], v[74:75], v[86:87], v[106:107]
	v_pk_fma_f32 v[108:109], v[78:79], v[86:87], v[108:109]
	v_add_f32_e32 v110, v106, v107
	v_add_f32_e32 v112, v108, v109
	s_nop 0
	v_add_f32_dpp v110, v110, v110 quad_perm:[1,0,3,2] row_mask:0xf bank_mask:0xf bound_ctrl:1
	v_add_f32_dpp v112, v112, v112 quad_perm:[1,0,3,2] row_mask:0xf bank_mask:0xf bound_ctrl:1
	s_nop 0
	v_add_f32_dpp v110, v110, v110 quad_perm:[2,3,0,1] row_mask:0xf bank_mask:0xf bound_ctrl:1
	v_add_f32_dpp v112, v112, v112 quad_perm:[2,3,0,1] row_mask:0xf bank_mask:0xf bound_ctrl:1
	s_nop 0
	v_add_f32_dpp v110, v110, v110 row_half_mirror row_mask:0xf bank_mask:0xf bound_ctrl:1
	v_add_f32_dpp v112, v112, v112 row_half_mirror row_mask:0xf bank_mask:0xf bound_ctrl:1
	s_nop 0
	v_add_f32_dpp v110, v110, v110 row_ror:8 row_mask:0xf bank_mask:0xf bound_ctrl:1
	v_add_f32_dpp v112, v112, v112 row_ror:8 row_mask:0xf bank_mask:0xf bound_ctrl:1
	v_pk_mul_f32 v[114:115], v[88:89], v[110:111] op_sel_hi:[1,0]
	v_pk_mul_f32 v[116:117], v[88:89], v[112:113] op_sel_hi:[1,0]
	v_pk_mul_f32 v[118:119], v[90:91], v[110:111] op_sel_hi:[1,0]
	v_pk_mul_f32 v[120:121], v[90:91], v[112:113] op_sel_hi:[1,0]
	v_pk_fma_f32 v[114:115], v[100:101], v[104:105], v[114:115] op_sel_hi:[1,0,1]
	v_pk_fma_f32 v[116:117], v[100:101], v[104:105], v[116:117] op_sel:[0,1,0]
	v_pk_fma_f32 v[118:119], v[102:103], v[104:105], v[118:119] op_sel_hi:[1,0,1]
	v_pk_fma_f32 v[120:121], v[102:103], v[104:105], v[120:121] op_sel:[0,1,0]
	v_pk_fma_f32 v[72:73], v[72:73], v[92:93], v[114:115]
	v_pk_fma_f32 v[76:77], v[76:77], v[92:93], v[116:117]
	v_pk_fma_f32 v[74:75], v[74:75], v[94:95], v[118:119]
	v_pk_fma_f32 v[78:79], v[78:79], v[94:95], v[120:121]
	v_pk_mul_f32 v[122:123], v[72:73], v[96:97]
	v_pk_mul_f32 v[124:125], v[76:77], v[96:97]
	v_pk_fma_f32 v[122:123], v[74:75], v[98:99], v[122:123]
	v_pk_fma_f32 v[124:125], v[78:79], v[98:99], v[124:125]
	v_add_f32_e32 v126, v122, v123
	v_add_f32_e32 v127, v124, v125
	ds_write_b64 v187, v[126:127] offset:63488
